# out-proj epilogues: non-temporal hint on the f32 residual loads and output stores
# speedup vs baseline: 1.0001x; 1.0001x over previous
.LBB0_1279:
	ds_read_b128 v[128:131], v238
	ds_read_b128 v[136:139], v253
	ds_read_b128 v[132:135], v238 offset:4096
	ds_read_b128 v[140:143], v253 offset:4096
	ds_read_b128 v[144:147], v253 offset:8192
	ds_read_b128 v[148:151], v253 offset:12288
	s_waitcnt lgkmcnt(6)
	v_mfma_f32_32x32x16_bf16 v[112:127], v[188:191], v[196:199], v[112:127]
	v_mfma_f32_32x32x16_bf16 v[48:63], v[192:195], v[196:199], v[48:63]
	v_mfma_f32_32x32x16_bf16 v[96:111], v[188:191], v[200:203], v[96:111]
	v_mfma_f32_32x32x16_bf16 v[32:47], v[192:195], v[200:203], v[32:47]
	v_mfma_f32_32x32x16_bf16 v[80:95], v[188:191], v[204:207], v[80:95]
	v_mfma_f32_32x32x16_bf16 v[16:31], v[192:195], v[204:207], v[16:31]
	v_mfma_f32_32x32x16_bf16 v[64:79], v[188:191], v[226:229], v[64:79]
	v_mfma_f32_32x32x16_bf16 v[0:15], v[192:195], v[226:229], v[0:15]
	ds_read_b128 v[188:191], v239
	ds_read_b128 v[196:199], v254
	ds_read_b128 v[192:195], v239 offset:4096
	ds_read_b128 v[200:203], v254 offset:4096
	ds_read_b128 v[204:207], v254 offset:8192
	ds_read_b128 v[226:229], v254 offset:12288
	s_waitcnt lgkmcnt(6)
	v_mfma_f32_32x32x16_bf16 v[112:127], v[128:131], v[136:139], v[112:127]
	v_mfma_f32_32x32x16_bf16 v[48:63], v[132:135], v[136:139], v[48:63]
	v_mfma_f32_32x32x16_bf16 v[96:111], v[128:131], v[140:143], v[96:111]
	v_mfma_f32_32x32x16_bf16 v[32:47], v[132:135], v[140:143], v[32:47]
	v_mfma_f32_32x32x16_bf16 v[80:95], v[128:131], v[144:147], v[80:95]
	v_mfma_f32_32x32x16_bf16 v[16:31], v[132:135], v[144:147], v[16:31]
	v_mfma_f32_32x32x16_bf16 v[64:79], v[128:131], v[148:151], v[64:79]
	v_mfma_f32_32x32x16_bf16 v[0:15], v[132:135], v[148:151], v[0:15]
	ds_read_b128 v[128:131], v240
	ds_read_b128 v[136:139], v255
	ds_read_b128 v[132:135], v240 offset:4096
	ds_read_b128 v[140:143], v255 offset:4096
	ds_read_b128 v[144:147], v255 offset:8192
	ds_read_b128 v[148:151], v255 offset:12288
	s_waitcnt lgkmcnt(6)
	v_mfma_f32_32x32x16_bf16 v[112:127], v[188:191], v[196:199], v[112:127]
	v_mfma_f32_32x32x16_bf16 v[48:63], v[192:195], v[196:199], v[48:63]
	v_mfma_f32_32x32x16_bf16 v[96:111], v[188:191], v[200:203], v[96:111]
	v_mfma_f32_32x32x16_bf16 v[32:47], v[192:195], v[200:203], v[32:47]
	v_mfma_f32_32x32x16_bf16 v[80:95], v[188:191], v[204:207], v[80:95]
	v_mfma_f32_32x32x16_bf16 v[16:31], v[192:195], v[204:207], v[16:31]
	v_mfma_f32_32x32x16_bf16 v[64:79], v[188:191], v[226:229], v[64:79]
	v_mfma_f32_32x32x16_bf16 v[0:15], v[192:195], v[226:229], v[0:15]
	s_waitcnt vmcnt(0) lgkmcnt(0)
	s_barrier
	v_mfma_f32_32x32x16_bf16 v[112:127], v[128:131], v[136:139], v[112:127]
	v_mfma_f32_32x32x16_bf16 v[48:63], v[132:135], v[136:139], v[48:63]
	v_mfma_f32_32x32x16_bf16 v[96:111], v[128:131], v[140:143], v[96:111]
	v_mfma_f32_32x32x16_bf16 v[32:47], v[132:135], v[140:143], v[32:47]
	v_mfma_f32_32x32x16_bf16 v[80:95], v[128:131], v[144:147], v[80:95]
	v_mfma_f32_32x32x16_bf16 v[16:31], v[132:135], v[144:147], v[16:31]
	v_mfma_f32_32x32x16_bf16 v[64:79], v[128:131], v[148:151], v[64:79]
	v_mfma_f32_32x32x16_bf16 v[0:15], v[132:135], v[148:151], v[0:15]
	s_lshl_b32 s2, s5, 8
	s_sub_i32 s2, s2, s6
	v_mov_b32_e32 v168, v214
	s_add_i32 s55, s4, s30
	s_or_b32 s26, s2, s31
	s_ashr_i32 s27, s26, 31
	s_load_dwordx2 s[24:25], s[0:1], 0x140
	v_ashrrev_i32_e32 v180, 3, v168
	v_and_b32_e32 v183, -4, v180
	v_add_u32_e32 v225, s55, v183
	v_add_u32_e32 v190, 8, v225
	v_min_i32_e32 v190, 0x7fff, v190
	v_ashrrev_i32_e32 v190, 12, v190
	v_min_i32_e32 v184, 0x7fff, v225
	v_and_b32_e32 v182, 31, v168
	v_ashrrev_i32_e32 v184, 12, v184
	v_or_b32_e32 v180, s26, v182
	v_mul_hi_i32_i24_e32 v185, 0x3000, v184
	v_mul_i32_i24_e32 v184, 0x3000, v184
	v_ashrrev_i32_e32 v181, 31, v180
	s_waitcnt lgkmcnt(0)
	v_lshl_add_u64 v[184:185], s[24:25], 0, v[184:185]
	v_add_u32_e32 v188, 9, v225
	v_mul_hi_i32_i24_e32 v187, 0x3000, v190
	v_mul_i32_i24_e32 v186, 0x3000, v190
	v_min_i32_e32 v188, 0x7fff, v188
	v_add_u32_e32 v190, 10, v225
	v_ashrrev_i32_e32 v188, 12, v188
	v_min_i32_e32 v190, 0x7fff, v190
	v_mul_hi_i32_i24_e32 v189, 0x3000, v188
	v_mul_i32_i24_e32 v188, 0x3000, v188
	v_ashrrev_i32_e32 v190, 12, v190
	v_lshl_add_u64 v[188:189], s[24:25], 0, v[188:189]
	v_mul_hi_i32_i24_e32 v191, 0x3000, v190
	v_mul_i32_i24_e32 v190, 0x3000, v190
	v_lshl_add_u64 v[184:185], v[184:185], 0, s[18:19]
	v_lshlrev_b64 v[180:181], 2, v[180:181]
	v_lshl_add_u64 v[186:187], s[24:25], 0, v[186:187]
	v_lshl_add_u64 v[188:189], v[188:189], 0, s[18:19]
	v_lshl_add_u64 v[190:191], s[24:25], 0, v[190:191]
	v_lshl_add_u64 v[208:209], v[184:185], 0, v[180:181]
	v_lshl_add_u64 v[186:187], v[186:187], 0, s[18:19]
	v_lshl_add_u64 v[190:191], v[190:191], 0, s[18:19]
	v_lshl_add_u64 v[230:231], v[186:187], 0, v[180:181]
	v_lshl_add_u64 v[196:197], v[188:189], 0, v[180:181]
	v_lshl_add_u64 v[198:199], v[190:191], 0, v[180:181]
	global_load_dword v232, v[208:209], off
	global_load_dword v233, v[208:209], off offset:128
	global_load_dword v238, v[230:231], off
	global_load_dword v239, v[230:231], off offset:128
	global_load_dword v240, v[196:197], off
	global_load_dword v241, v[196:197], off offset:128
	global_load_dword v242, v[198:199], off
	global_load_dword v243, v[198:199], off offset:128
	v_add_u32_e32 v196, 17, v225
	v_min_i32_e32 v196, 0x7fff, v196
	v_add_u32_e32 v198, 18, v225
	v_ashrrev_i32_e32 v196, 12, v196
	v_min_i32_e32 v198, 0x7fff, v198
	v_mul_hi_i32_i24_e32 v197, 0x3000, v196
	v_mul_i32_i24_e32 v196, 0x3000, v196
	v_ashrrev_i32_e32 v198, 12, v198
	v_lshl_add_u64 v[196:197], s[24:25], 0, v[196:197]
	v_mul_hi_i32_i24_e32 v199, 0x3000, v198
	v_mul_i32_i24_e32 v198, 0x3000, v198
	v_add_u32_e32 v192, 11, v225
	v_add_u32_e32 v194, 16, v225
	v_min_i32_e32 v192, 0x7fff, v192
	v_min_i32_e32 v194, 0x7fff, v194
	v_ashrrev_i32_e32 v192, 12, v192
	v_ashrrev_i32_e32 v194, 12, v194
	v_mul_hi_i32_i24_e32 v193, 0x3000, v192
	v_mul_i32_i24_e32 v192, 0x3000, v192
	v_mul_hi_i32_i24_e32 v195, 0x3000, v194
	v_mul_i32_i24_e32 v194, 0x3000, v194
	v_lshl_add_u64 v[192:193], s[24:25], 0, v[192:193]
	v_lshl_add_u64 v[194:195], s[24:25], 0, v[194:195]
	v_lshl_add_u64 v[192:193], v[192:193], 0, s[18:19]
	v_lshl_add_u64 v[194:195], v[194:195], 0, s[18:19]
	v_lshl_add_u64 v[196:197], v[196:197], 0, s[18:19]
	v_lshl_add_u64 v[198:199], s[24:25], 0, v[198:199]
	v_lshl_add_u64 v[208:209], v[192:193], 0, v[180:181]
	v_lshl_add_u64 v[198:199], v[198:199], 0, s[18:19]
	v_lshl_add_u64 v[226:227], v[198:199], 0, v[180:181]
	s_waitcnt vmcnt(7)
	v_mul_f32_e32 v112, v112, v232
	v_lshl_add_u64 v[204:205], v[194:195], 0, v[180:181]
	v_lshl_add_u64 v[206:207], v[196:197], 0, v[180:181]
	s_waitcnt vmcnt(6)
	s_nop 2
	v_mul_f32_e32 v96, v96, v233
	v_mul_f32_e32 v97, v97, v233
	global_load_dword v234, v[208:209], off
	global_load_dword v235, v[208:209], off offset:128
	global_load_dword v236, v[204:205], off
	global_load_dword v237, v[204:205], off offset:128
	global_load_dword v244, v[206:207], off
	global_load_dword v245, v[206:207], off offset:128
	global_load_dword v246, v[226:227], off
	global_load_dword v247, v[226:227], off offset:128
	v_add_u32_e32 v204, 25, v225
	v_add_u32_e32 v206, 26, v225
	v_min_i32_e32 v204, 0x7fff, v204
	v_min_i32_e32 v206, 0x7fff, v206
	v_ashrrev_i32_e32 v204, 12, v204
	v_ashrrev_i32_e32 v206, 12, v206
	v_add_u32_e32 v200, 19, v225
	v_min_i32_e32 v200, 0x7fff, v200
	v_add_u32_e32 v202, 24, v225
	v_ashrrev_i32_e32 v200, 12, v200
	v_min_i32_e32 v202, 0x7fff, v202
	v_mul_hi_i32_i24_e32 v201, 0x3000, v200
	v_mul_i32_i24_e32 v200, 0x3000, v200
	v_ashrrev_i32_e32 v202, 12, v202
	v_mul_hi_i32_i24_e32 v205, 0x3000, v204
	v_mul_i32_i24_e32 v204, 0x3000, v204
	v_mul_hi_i32_i24_e32 v207, 0x3000, v206
	v_mul_i32_i24_e32 v206, 0x3000, v206
	v_lshl_add_u64 v[200:201], s[24:25], 0, v[200:201]
	v_mul_hi_i32_i24_e32 v203, 0x3000, v202
	v_mul_i32_i24_e32 v202, 0x3000, v202
	v_lshl_add_u64 v[204:205], s[24:25], 0, v[204:205]
	v_lshl_add_u64 v[206:207], s[24:25], 0, v[206:207]
	v_lshl_add_u64 v[200:201], v[200:201], 0, s[18:19]
	v_lshl_add_u64 v[202:203], s[24:25], 0, v[202:203]
	v_lshl_add_u64 v[204:205], v[204:205], 0, s[18:19]
	v_lshl_add_u64 v[206:207], v[206:207], 0, s[18:19]
	v_lshl_add_u64 v[208:209], v[200:201], 0, v[180:181]
	v_lshl_add_u64 v[202:203], v[202:203], 0, s[18:19]
	v_lshl_add_u64 v[228:229], v[204:205], 0, v[180:181]
	v_lshl_add_u64 v[230:231], v[206:207], 0, v[180:181]
	v_lshl_add_u64 v[226:227], v[202:203], 0, v[180:181]
	global_load_dword v248, v[208:209], off
	global_load_dword v249, v[208:209], off offset:128
	global_load_dword v250, v[226:227], off
	global_load_dword v251, v[226:227], off offset:128
	global_load_dword v252, v[228:229], off
	s_nop 0
	global_load_dword v228, v[228:229], off offset:128
	s_nop 0
	global_load_dword v229, v[230:231], off
	s_nop 0
	global_load_dword v230, v[230:231], off offset:128
	v_add_u32_e32 v208, 27, v225
	v_min_i32_e32 v208, 0x7fff, v208
	v_ashrrev_i32_e32 v208, 12, v208
	v_mul_hi_i32_i24_e32 v209, 0x3000, v208
	v_mul_i32_i24_e32 v208, 0x3000, v208
	v_lshl_add_u64 v[208:209], s[24:25], 0, v[208:209]
	v_lshl_add_u64 v[208:209], v[208:209], 0, s[18:19]
	v_lshl_add_u64 v[226:227], v[208:209], 0, v[180:181]
	global_load_dword v225, v[226:227], off
	s_nop 0
	global_load_dword v226, v[226:227], off offset:128
	v_mad_u64_u32 v[160:161], s[2:3], v183, s36, v[182:183]
	v_lshl_add_u32 v162, v160, 2, s34
	ds_write2_b32 v162, v112, v96 offset1:32
	v_mul_f32_e32 v96, v113, v232
	ds_write2_b32 v162, v96, v97 offset0:68 offset1:100
	v_mul_f32_e32 v96, v114, v232
	v_mul_f32_e32 v97, v98, v233
	ds_write2_b32 v162, v96, v97 offset0:136 offset1:168
	v_mul_f32_e32 v96, v115, v232
	v_mul_f32_e32 v97, v99, v233
	ds_write2_b32 v162, v96, v97 offset0:204 offset1:236
	s_waitcnt vmcnt(23)
	v_mul_f32_e32 v96, v116, v238
	s_waitcnt vmcnt(22)
	v_mul_f32_e32 v97, v100, v239
	v_add_u32_e32 v115, 0x800, v162
	ds_write2_b32 v115, v96, v97 offset0:32 offset1:64
	s_waitcnt vmcnt(21)
	v_mul_f32_e32 v96, v117, v240
	s_waitcnt vmcnt(20)
	v_mul_f32_e32 v97, v101, v241
	ds_write2_b32 v115, v96, v97 offset0:100 offset1:132
	s_waitcnt vmcnt(19)
	v_mul_f32_e32 v96, v118, v242
	s_waitcnt vmcnt(18)
	v_mul_f32_e32 v97, v102, v243
	ds_write2_b32 v115, v96, v97 offset0:168 offset1:200
	v_add_u32_e32 v116, 0xa00, v162
	v_add_u32_e32 v117, 0x1000, v162
	v_add_u32_e32 v118, 0x1400, v162
	v_ashrrev_i32_e32 v163, 4, v168
	v_and_b32_e32 v160, 15, v168
	v_mul_lo_u32 v161, v163, s37
	s_waitcnt vmcnt(17)
	v_mul_f32_e32 v96, v119, v234
	s_waitcnt vmcnt(16)
	v_mul_f32_e32 v97, v103, v235
	ds_write2_b32 v116, v96, v97 offset0:108 offset1:140
	s_waitcnt vmcnt(15)
	v_mul_f32_e32 v96, v120, v236
	s_waitcnt vmcnt(14)
	v_mul_f32_e32 v97, v104, v237
	ds_write2_b32 v117, v96, v97 offset0:64 offset1:96
	s_waitcnt vmcnt(13)
	v_mul_f32_e32 v96, v121, v244
	s_waitcnt vmcnt(12)
	v_mul_f32_e32 v97, v105, v245
	ds_write2_b32 v117, v96, v97 offset0:132 offset1:164
	s_waitcnt vmcnt(11)
	v_mul_f32_e32 v96, v122, v246
	s_waitcnt vmcnt(10)
	v_mul_f32_e32 v97, v106, v247
	ds_write2_b32 v117, v96, v97 offset0:200 offset1:232
	v_add_u32_e32 v119, 0x1800, v162
	v_add_u32_e32 v120, 0x1a00, v162
	v_lshl_add_u32 v164, v160, 4, s34
	v_lshlrev_b32_e32 v168, 2, v160
	v_add_u32_e32 v160, s55, v163
	v_add_u32_e32 v121, 0x1c00, v162
	v_cmp_gt_i32_e32 vcc, s38, v160
	v_add_u32_e32 v114, v164, v161
	v_ashrrev_i32_e32 v161, 31, v160
	s_waitcnt vmcnt(9)
	v_mul_f32_e32 v96, v123, v248
	s_waitcnt vmcnt(8)
	v_mul_f32_e32 v97, v107, v249
	ds_write2_b32 v118, v96, v97 offset0:12 offset1:44
	s_waitcnt vmcnt(7)
	v_mul_f32_e32 v96, v124, v250
	s_waitcnt vmcnt(6)
	v_mul_f32_e32 v97, v108, v251
	ds_write2_b32 v119, v96, v97 offset0:96 offset1:128
	s_waitcnt vmcnt(5)
	v_mul_f32_e32 v96, v125, v252
	s_waitcnt vmcnt(4)
	v_mul_f32_e32 v97, v109, v228
	ds_write2_b32 v119, v96, v97 offset0:164 offset1:196
	s_waitcnt vmcnt(3)
	v_mul_f32_e32 v96, v126, v229
	s_waitcnt vmcnt(2)
	v_mul_f32_e32 v97, v110, v230
	ds_write2_b32 v120, v96, v97 offset0:104 offset1:136
	s_waitcnt vmcnt(1)
	v_mul_f32_e32 v96, v127, v225
	s_waitcnt vmcnt(0)
	v_mul_f32_e32 v97, v111, v226
	ds_write2_b32 v121, v96, v97 offset0:44 offset1:76
	v_or_b32_e32 v96, s26, v168
	v_mov_b32_e32 v97, s27
	v_add_u32_e32 v128, 0, v160
	v_ashrrev_i32_e32 v129, 31, v128
	v_lshlrev_b64 v[128:129], 10, v[128:129]
	v_lshl_add_u64 v[128:129], v[128:129], 0, v[96:97]
	v_lshlrev_b64 v[128:129], 2, v[128:129]
	v_lshl_add_u64 v[128:129], s[16:17], 0, v[128:129]
	global_load_dwordx4 v[128:131], v[128:129], off nt
	v_add_u32_e32 v132, 4, v160
	v_ashrrev_i32_e32 v133, 31, v132
	v_lshlrev_b64 v[132:133], 10, v[132:133]
	v_lshl_add_u64 v[132:133], v[132:133], 0, v[96:97]
	v_lshlrev_b64 v[132:133], 2, v[132:133]
	v_lshl_add_u64 v[132:133], s[16:17], 0, v[132:133]
	global_load_dwordx4 v[132:135], v[132:133], off nt
	v_add_u32_e32 v136, 8, v160
	v_ashrrev_i32_e32 v137, 31, v136
	v_lshlrev_b64 v[136:137], 10, v[136:137]
	v_lshl_add_u64 v[136:137], v[136:137], 0, v[96:97]
	v_lshlrev_b64 v[136:137], 2, v[136:137]
	v_lshl_add_u64 v[136:137], s[16:17], 0, v[136:137]
	global_load_dwordx4 v[136:139], v[136:137], off nt
	v_add_u32_e32 v140, 12, v160
	v_ashrrev_i32_e32 v141, 31, v140
	v_lshlrev_b64 v[140:141], 10, v[140:141]
	v_lshl_add_u64 v[140:141], v[140:141], 0, v[96:97]
	v_lshlrev_b64 v[140:141], 2, v[140:141]
	v_lshl_add_u64 v[140:141], s[16:17], 0, v[140:141]
	global_load_dwordx4 v[140:143], v[140:141], off nt
	v_add_u32_e32 v144, 16, v160
	v_ashrrev_i32_e32 v145, 31, v144
	v_lshlrev_b64 v[144:145], 10, v[144:145]
	v_lshl_add_u64 v[144:145], v[144:145], 0, v[96:97]
	v_lshlrev_b64 v[144:145], 2, v[144:145]
	v_lshl_add_u64 v[144:145], s[16:17], 0, v[144:145]
	global_load_dwordx4 v[144:147], v[144:145], off nt
	v_add_u32_e32 v148, 20, v160
	v_ashrrev_i32_e32 v149, 31, v148
	v_lshlrev_b64 v[148:149], 10, v[148:149]
	v_lshl_add_u64 v[148:149], v[148:149], 0, v[96:97]
	v_lshlrev_b64 v[148:149], 2, v[148:149]
	v_lshl_add_u64 v[148:149], s[16:17], 0, v[148:149]
	global_load_dwordx4 v[148:151], v[148:149], off nt
	v_add_u32_e32 v152, 24, v160
	v_ashrrev_i32_e32 v153, 31, v152
	v_lshlrev_b64 v[152:153], 10, v[152:153]
	v_lshl_add_u64 v[152:153], v[152:153], 0, v[96:97]
	v_lshlrev_b64 v[152:153], 2, v[152:153]
	v_lshl_add_u64 v[152:153], s[16:17], 0, v[152:153]
	global_load_dwordx4 v[152:155], v[152:153], off nt
	v_add_u32_e32 v156, 28, v160
	v_ashrrev_i32_e32 v157, 31, v156
	v_lshlrev_b64 v[156:157], 10, v[156:157]
	v_lshl_add_u64 v[156:157], v[156:157], 0, v[96:97]
	v_lshlrev_b64 v[156:157], 2, v[156:157]
	v_lshl_add_u64 v[156:157], s[16:17], 0, v[156:157]
	global_load_dwordx4 v[156:159], v[156:157], off nt
	s_and_saveexec_b64 s[2:3], vcc
	s_cbranch_execz .LBB0_1281
	v_lshlrev_b64 v[98:99], 10, v[160:161]
	v_lshl_add_u64 v[98:99], v[98:99], 0, v[96:97]
	v_lshlrev_b64 v[106:107], 2, v[98:99]
	v_lshl_add_u64 v[98:99], s[16:17], 0, v[106:107]
	ds_read_b128 v[102:105], v114
	s_load_dwordx2 s[4:5], s[0:1], 0xb8
	s_waitcnt vmcnt(7) lgkmcnt(0)
	v_pk_add_f32 v[100:101], v[104:105], v[130:131]
	v_pk_add_f32 v[98:99], v[102:103], v[128:129]
	v_lshl_add_u64 v[102:103], s[4:5], 0, v[106:107]
	global_store_dwordx4 v[102:103], v[98:101], off nt
.LBB0_1281:
	s_or_b64 exec, exec, s[2:3]
	s_nop 0
	v_add_u32_e32 v100, 4, v160
	v_cmp_gt_i32_e64 s[2:3], s39, v160
	v_ashrrev_i32_e32 v101, 31, v100
	s_and_saveexec_b64 s[4:5], s[2:3]
	s_cbranch_execz .LBB0_1283
	v_lshlrev_b64 v[98:99], 10, v[100:101]
	v_lshl_add_u64 v[98:99], v[98:99], 0, v[96:97]
	v_lshlrev_b64 v[98:99], 2, v[98:99]
	v_lshl_add_u64 v[102:103], s[16:17], 0, v[98:99]
	ds_read_b128 v[106:109], v114 offset:1088
	s_load_dwordx2 s[6:7], s[0:1], 0xb8
	s_waitcnt lgkmcnt(0)
	v_lshl_add_u64 v[98:99], s[6:7], 0, v[98:99]
	s_waitcnt vmcnt(7)
	v_pk_add_f32 v[104:105], v[108:109], v[134:135]
	v_pk_add_f32 v[102:103], v[106:107], v[132:133]
	global_store_dwordx4 v[98:99], v[102:105], off nt
.LBB0_1283:
	s_or_b64 exec, exec, s[4:5]
	s_nop 0
	v_add_u32_e32 v102, 8, v160
	v_cmp_gt_i32_e64 s[4:5], s48, v160
	v_ashrrev_i32_e32 v103, 31, v102
	s_and_saveexec_b64 s[6:7], s[4:5]
	s_cbranch_execz .LBB0_1285
	v_lshlrev_b64 v[98:99], 10, v[102:103]
	v_lshl_add_u64 v[98:99], v[98:99], 0, v[96:97]
	v_lshlrev_b64 v[98:99], 2, v[98:99]
	v_lshl_add_u64 v[104:105], s[16:17], 0, v[98:99]
	ds_read_b128 v[108:111], v114 offset:2176
	s_load_dwordx2 s[8:9], s[0:1], 0xb8
	s_waitcnt lgkmcnt(0)
	v_lshl_add_u64 v[98:99], s[8:9], 0, v[98:99]
	s_waitcnt vmcnt(7)
	v_pk_add_f32 v[106:107], v[110:111], v[138:139]
	v_pk_add_f32 v[104:105], v[108:109], v[136:137]
	global_store_dwordx4 v[98:99], v[104:107], off nt
.LBB0_1285:
	s_or_b64 exec, exec, s[6:7]
	s_nop 0
	v_add_u32_e32 v104, 12, v160
	v_cmp_gt_i32_e64 s[6:7], s49, v160
	v_ashrrev_i32_e32 v105, 31, v104
	s_and_saveexec_b64 s[8:9], s[6:7]
	s_cbranch_execz .LBB0_1287
	v_lshlrev_b64 v[98:99], 10, v[104:105]
	v_lshl_add_u64 v[98:99], v[98:99], 0, v[96:97]
	v_lshlrev_b64 v[98:99], 2, v[98:99]
	v_lshl_add_u64 v[106:107], s[16:17], 0, v[98:99]
	ds_read_b128 v[110:113], v114 offset:3264
	s_load_dwordx2 s[10:11], s[0:1], 0xb8
	s_waitcnt lgkmcnt(0)
	v_lshl_add_u64 v[98:99], s[10:11], 0, v[98:99]
	s_waitcnt vmcnt(7)
	v_pk_add_f32 v[108:109], v[112:113], v[142:143]
	v_pk_add_f32 v[106:107], v[110:111], v[140:141]
	global_store_dwordx4 v[98:99], v[106:109], off nt
.LBB0_1287:
	s_or_b64 exec, exec, s[8:9]
	s_nop 0
	v_add_u32_e32 v106, 16, v160
	v_cmp_gt_i32_e64 s[8:9], s50, v160
	v_ashrrev_i32_e32 v107, 31, v106
	s_and_saveexec_b64 s[10:11], s[8:9]
	s_cbranch_execz .LBB0_1289
	v_lshlrev_b64 v[98:99], 10, v[106:107]
	v_lshl_add_u64 v[98:99], v[98:99], 0, v[96:97]
	v_lshlrev_b64 v[98:99], 2, v[98:99]
	v_lshl_add_u64 v[108:109], s[16:17], 0, v[98:99]
	ds_read_b128 v[122:125], v114 offset:4352
	s_load_dwordx2 s[12:13], s[0:1], 0xb8
	s_waitcnt lgkmcnt(0)
	v_lshl_add_u64 v[98:99], s[12:13], 0, v[98:99]
	s_waitcnt vmcnt(7)
	v_pk_add_f32 v[110:111], v[124:125], v[146:147]
	v_pk_add_f32 v[108:109], v[122:123], v[144:145]
	global_store_dwordx4 v[98:99], v[108:111], off nt
.LBB0_1289:
	s_or_b64 exec, exec, s[10:11]
	s_nop 0
	v_add_u32_e32 v108, 20, v160
	v_cmp_gt_i32_e64 s[10:11], s51, v160
	v_ashrrev_i32_e32 v109, 31, v108
	s_and_saveexec_b64 s[12:13], s[10:11]
	s_cbranch_execz .LBB0_1291
	v_lshlrev_b64 v[98:99], 10, v[108:109]
	v_lshl_add_u64 v[98:99], v[98:99], 0, v[96:97]
	v_lshlrev_b64 v[98:99], 2, v[98:99]
	v_lshl_add_u64 v[110:111], s[16:17], 0, v[98:99]
	ds_read_b128 v[122:125], v114 offset:5440
	s_load_dwordx2 s[14:15], s[0:1], 0xb8
	s_waitcnt lgkmcnt(0)
	v_lshl_add_u64 v[98:99], s[14:15], 0, v[98:99]
	s_waitcnt vmcnt(7)
	v_pk_add_f32 v[112:113], v[124:125], v[150:151]
	v_pk_add_f32 v[110:111], v[122:123], v[148:149]
	global_store_dwordx4 v[98:99], v[110:113], off nt
.LBB0_1291:
	s_or_b64 exec, exec, s[12:13]
	s_nop 0
	v_add_u32_e32 v110, 24, v160
	v_cmp_gt_i32_e64 s[12:13], s52, v160
	v_ashrrev_i32_e32 v111, 31, v110
	s_and_saveexec_b64 s[14:15], s[12:13]
	s_cbranch_execz .LBB0_1293
	v_lshlrev_b64 v[98:99], 10, v[110:111]
	v_lshl_add_u64 v[98:99], v[98:99], 0, v[96:97]
	v_lshlrev_b64 v[98:99], 2, v[98:99]
	v_lshl_add_u64 v[112:113], s[16:17], 0, v[98:99]
	ds_read_b128 v[164:167], v114 offset:6528
	s_load_dwordx2 s[28:29], s[0:1], 0xb8
	s_waitcnt lgkmcnt(0)
	v_lshl_add_u64 v[98:99], s[28:29], 0, v[98:99]
	s_waitcnt vmcnt(7)
	v_pk_add_f32 v[124:125], v[166:167], v[154:155]
	v_pk_add_f32 v[122:123], v[164:165], v[152:153]
	global_store_dwordx4 v[98:99], v[122:125], off nt
.LBB0_1293:
	s_or_b64 exec, exec, s[14:15]
	v_add_u32_e32 v112, 28, v160
	v_cmp_gt_i32_e64 s[14:15], s53, v160
	v_ashrrev_i32_e32 v113, 31, v112
	s_and_saveexec_b64 s[28:29], s[14:15]
	s_cbranch_execz .LBB0_1295
	v_lshlrev_b64 v[98:99], 10, v[112:113]
	v_lshl_add_u64 v[98:99], v[98:99], 0, v[96:97]
	v_lshlrev_b64 v[98:99], 2, v[98:99]
	v_lshl_add_u64 v[122:123], s[16:17], 0, v[98:99]
	ds_read_b128 v[164:167], v114 offset:7616
	s_load_dwordx2 s[56:57], s[0:1], 0xb8
	s_waitcnt lgkmcnt(0)
	v_lshl_add_u64 v[98:99], s[56:57], 0, v[98:99]
	s_waitcnt vmcnt(7)
	v_pk_add_f32 v[124:125], v[166:167], v[158:159]
	v_pk_add_f32 v[122:123], v[164:165], v[156:157]
	global_store_dwordx4 v[98:99], v[122:125], off nt
.LBB0_1295:
	s_or_b64 exec, exec, s[28:29]
	v_add3_u32 v98, v182, s26, 64
	v_ashrrev_i32_e32 v99, 31, v98
	v_lshlrev_b64 v[98:99], 2, v[98:99]
	v_lshl_add_u64 v[122:123], v[184:185], 0, v[98:99]
	v_lshl_add_u64 v[124:125], v[186:187], 0, v[98:99]
	v_lshl_add_u64 v[126:127], v[188:189], 0, v[98:99]
	v_lshl_add_u64 v[164:165], v[190:191], 0, v[98:99]
	global_load_dword v166, v[122:123], off
	global_load_dword v167, v[122:123], off offset:128
	global_load_dword v182, v[124:125], off
	global_load_dword v184, v[124:125], off offset:128
	global_load_dword v185, v[126:127], off
	global_load_dword v186, v[126:127], off offset:128
	global_load_dword v187, v[164:165], off
	global_load_dword v188, v[164:165], off offset:128
	v_lshl_add_u64 v[122:123], v[192:193], 0, v[98:99]
	v_lshl_add_u64 v[124:125], v[194:195], 0, v[98:99]
	v_lshl_add_u64 v[126:127], v[196:197], 0, v[98:99]
	v_lshl_add_u64 v[164:165], v[198:199], 0, v[98:99]
	global_load_dword v189, v[122:123], off
	global_load_dword v190, v[122:123], off offset:128
	global_load_dword v191, v[124:125], off
	global_load_dword v192, v[124:125], off offset:128
	global_load_dword v193, v[126:127], off
	global_load_dword v194, v[126:127], off offset:128
	global_load_dword v195, v[164:165], off
	global_load_dword v196, v[164:165], off offset:128
	v_lshl_add_u64 v[122:123], v[200:201], 0, v[98:99]
	v_lshl_add_u64 v[124:125], v[202:203], 0, v[98:99]
	v_lshl_add_u64 v[126:127], v[204:205], 0, v[98:99]
	v_lshl_add_u64 v[164:165], v[206:207], 0, v[98:99]
	global_load_dword v197, v[122:123], off
	global_load_dword v198, v[122:123], off offset:128
	global_load_dword v199, v[124:125], off
	s_nop 0
	global_load_dword v124, v[124:125], off offset:128
	s_nop 0
	global_load_dword v125, v[126:127], off
	s_nop 0
	global_load_dword v126, v[126:127], off offset:128
	s_nop 0
	global_load_dword v127, v[164:165], off
	s_nop 0
	global_load_dword v164, v[164:165], off offset:128
	v_lshl_add_u64 v[122:123], v[208:209], 0, v[98:99]
	global_load_dword v165, v[122:123], off
	s_nop 0
	global_load_dword v122, v[122:123], off offset:128
	s_waitcnt vmcnt(25)
	v_mul_f32_e32 v80, v80, v166
	s_waitcnt vmcnt(24)
	v_mul_f32_e32 v64, v64, v167
	v_mul_f32_e32 v65, v65, v167
	v_mul_f32_e32 v81, v81, v166
	v_mul_f32_e32 v82, v82, v166
	v_mul_f32_e32 v66, v66, v167
	v_mul_f32_e32 v83, v83, v166
	v_mul_f32_e32 v67, v67, v167
	s_waitcnt vmcnt(23)
	v_mul_f32_e32 v84, v84, v182
	s_waitcnt vmcnt(22)
	v_mul_f32_e32 v68, v68, v184
	s_waitcnt vmcnt(21)
	v_mul_f32_e32 v85, v85, v185
	s_waitcnt vmcnt(20)
	v_mul_f32_e32 v69, v69, v186
	s_waitcnt vmcnt(19)
	v_mul_f32_e32 v86, v86, v187
	s_waitcnt vmcnt(18)
	v_mul_f32_e32 v70, v70, v188
	s_waitcnt vmcnt(17)
	v_mul_f32_e32 v87, v87, v189
	s_waitcnt vmcnt(16)
	v_mul_f32_e32 v71, v71, v190
	s_waitcnt vmcnt(15)
	v_mul_f32_e32 v88, v88, v191
	s_waitcnt vmcnt(14)
	v_mul_f32_e32 v72, v72, v192
	s_waitcnt vmcnt(13)
	v_mul_f32_e32 v89, v89, v193
	s_waitcnt vmcnt(12)
	v_mul_f32_e32 v73, v73, v194
	s_waitcnt vmcnt(11)
	v_mul_f32_e32 v90, v90, v195
	s_waitcnt vmcnt(10)
	v_mul_f32_e32 v74, v74, v196
	s_waitcnt vmcnt(9)
	v_mul_f32_e32 v91, v91, v197
	s_waitcnt vmcnt(8)
	v_mul_f32_e32 v75, v75, v198
	s_waitcnt vmcnt(7)
	v_mul_f32_e32 v92, v92, v199
	s_waitcnt vmcnt(6)
	v_mul_f32_e32 v76, v76, v124
	s_waitcnt vmcnt(5)
	v_mul_f32_e32 v93, v93, v125
	s_waitcnt vmcnt(4)
	v_mul_f32_e32 v77, v77, v126
	s_waitcnt vmcnt(3)
	v_mul_f32_e32 v94, v94, v127
	s_waitcnt vmcnt(2)
	v_mul_f32_e32 v78, v78, v164
	ds_write2_b32 v162, v80, v64 offset1:32
	ds_write2_b32 v162, v81, v65 offset0:68 offset1:100
	ds_write2_b32 v162, v82, v66 offset0:136 offset1:168
	ds_write2_b32 v162, v83, v67 offset0:204 offset1:236
	ds_write2_b32 v115, v84, v68 offset0:32 offset1:64
	ds_write2_b32 v115, v85, v69 offset0:100 offset1:132
	ds_write2_b32 v115, v86, v70 offset0:168 offset1:200
	ds_write2_b32 v116, v87, v71 offset0:108 offset1:140
	ds_write2_b32 v117, v88, v72 offset0:64 offset1:96
	ds_write2_b32 v117, v89, v73 offset0:132 offset1:164
	ds_write2_b32 v117, v90, v74 offset0:200 offset1:232
	ds_write2_b32 v118, v91, v75 offset0:12 offset1:44
	ds_write2_b32 v119, v92, v76 offset0:96 offset1:128
	ds_write2_b32 v119, v93, v77 offset0:164 offset1:196
	ds_write2_b32 v120, v94, v78 offset0:104 offset1:136
	s_waitcnt vmcnt(1)
	v_mul_f32_e32 v64, v95, v165
	s_waitcnt vmcnt(0)
	v_mul_f32_e32 v65, v79, v122
	ds_write2_b32 v121, v64, v65 offset0:44 offset1:76
	v_lshl_add_u64 v[64:65], v[168:169], 0, s[26:27]
	v_add_u32_e32 v128, 0, v160
	v_ashrrev_i32_e32 v129, 31, v128
	v_lshlrev_b64 v[128:129], 10, v[128:129]
	v_lshl_add_u64 v[128:129], v[128:129], 0, v[64:65]
	v_lshlrev_b64 v[128:129], 2, v[128:129]
	v_lshl_add_u64 v[128:129], s[16:17], 0, v[128:129]
	global_load_dwordx4 v[128:131], v[128:129], off offset:256 nt
	v_add_u32_e32 v132, 4, v160
	v_ashrrev_i32_e32 v133, 31, v132
	v_lshlrev_b64 v[132:133], 10, v[132:133]
	v_lshl_add_u64 v[132:133], v[132:133], 0, v[64:65]
	v_lshlrev_b64 v[132:133], 2, v[132:133]
	v_lshl_add_u64 v[132:133], s[16:17], 0, v[132:133]
	global_load_dwordx4 v[132:135], v[132:133], off offset:256 nt
	v_add_u32_e32 v136, 8, v160
	v_ashrrev_i32_e32 v137, 31, v136
	v_lshlrev_b64 v[136:137], 10, v[136:137]
	v_lshl_add_u64 v[136:137], v[136:137], 0, v[64:65]
	v_lshlrev_b64 v[136:137], 2, v[136:137]
	v_lshl_add_u64 v[136:137], s[16:17], 0, v[136:137]
	global_load_dwordx4 v[136:139], v[136:137], off offset:256 nt
	v_add_u32_e32 v140, 12, v160
	v_ashrrev_i32_e32 v141, 31, v140
	v_lshlrev_b64 v[140:141], 10, v[140:141]
	v_lshl_add_u64 v[140:141], v[140:141], 0, v[64:65]
	v_lshlrev_b64 v[140:141], 2, v[140:141]
	v_lshl_add_u64 v[140:141], s[16:17], 0, v[140:141]
	global_load_dwordx4 v[140:143], v[140:141], off offset:256 nt
	v_add_u32_e32 v144, 16, v160
	v_ashrrev_i32_e32 v145, 31, v144
	v_lshlrev_b64 v[144:145], 10, v[144:145]
	v_lshl_add_u64 v[144:145], v[144:145], 0, v[64:65]
	v_lshlrev_b64 v[144:145], 2, v[144:145]
	v_lshl_add_u64 v[144:145], s[16:17], 0, v[144:145]
	global_load_dwordx4 v[144:147], v[144:145], off offset:256 nt
	v_add_u32_e32 v148, 20, v160
	v_ashrrev_i32_e32 v149, 31, v148
	v_lshlrev_b64 v[148:149], 10, v[148:149]
	v_lshl_add_u64 v[148:149], v[148:149], 0, v[64:65]
	v_lshlrev_b64 v[148:149], 2, v[148:149]
	v_lshl_add_u64 v[148:149], s[16:17], 0, v[148:149]
	global_load_dwordx4 v[148:151], v[148:149], off offset:256 nt
	v_add_u32_e32 v152, 24, v160
	v_ashrrev_i32_e32 v153, 31, v152
	v_lshlrev_b64 v[152:153], 10, v[152:153]
	v_lshl_add_u64 v[152:153], v[152:153], 0, v[64:65]
	v_lshlrev_b64 v[152:153], 2, v[152:153]
	v_lshl_add_u64 v[152:153], s[16:17], 0, v[152:153]
	global_load_dwordx4 v[152:155], v[152:153], off offset:256 nt
	v_add_u32_e32 v156, 28, v160
	v_ashrrev_i32_e32 v157, 31, v156
	v_lshlrev_b64 v[156:157], 10, v[156:157]
	v_lshl_add_u64 v[156:157], v[156:157], 0, v[64:65]
	v_lshlrev_b64 v[156:157], 2, v[156:157]
	v_lshl_add_u64 v[156:157], s[16:17], 0, v[156:157]
	global_load_dwordx4 v[156:159], v[156:157], off offset:256 nt
	s_and_saveexec_b64 s[26:27], vcc
	s_cbranch_execz .LBB0_1303
	v_lshlrev_b64 v[66:67], 10, v[160:161]
	v_lshl_add_u64 v[66:67], v[66:67], 0, v[64:65]
	v_lshlrev_b64 v[74:75], 2, v[66:67]
	v_lshl_add_u64 v[66:67], s[16:17], 0, v[74:75]
	ds_read_b128 v[70:73], v114
	s_load_dwordx2 s[28:29], s[0:1], 0xb8
	s_waitcnt vmcnt(7) lgkmcnt(0)
	v_pk_add_f32 v[68:69], v[72:73], v[130:131]
	v_pk_add_f32 v[66:67], v[70:71], v[128:129]
	v_lshl_add_u64 v[70:71], s[28:29], 0, v[74:75]
	global_store_dwordx4 v[70:71], v[66:69], off offset:256 nt
	s_or_b64 exec, exec, s[26:27]
	s_and_saveexec_b64 s[26:27], s[2:3]
	s_cbranch_execnz .LBB0_1304

.LBB0_1298:
	v_lshlrev_b64 v[66:67], 10, v[102:103]
	v_lshl_add_u64 v[66:67], v[66:67], 0, v[64:65]
	v_lshlrev_b64 v[74:75], 2, v[66:67]
	v_lshl_add_u64 v[66:67], s[16:17], 0, v[74:75]
	ds_read_b128 v[70:73], v114 offset:2176
	s_load_dwordx2 s[4:5], s[0:1], 0xb8
	s_waitcnt vmcnt(7) lgkmcnt(0)
	v_pk_add_f32 v[68:69], v[72:73], v[138:139]
	v_pk_add_f32 v[66:67], v[70:71], v[136:137]
	v_lshl_add_u64 v[70:71], s[4:5], 0, v[74:75]
	global_store_dwordx4 v[70:71], v[66:69], off offset:256 nt
	s_or_b64 exec, exec, s[2:3]
	s_and_saveexec_b64 s[2:3], s[6:7]
	s_cbranch_execnz .LBB0_1306

.LBB0_1300:
	v_lshlrev_b64 v[66:67], 10, v[106:107]
	v_lshl_add_u64 v[66:67], v[66:67], 0, v[64:65]
	v_lshlrev_b64 v[74:75], 2, v[66:67]
	v_lshl_add_u64 v[66:67], s[16:17], 0, v[74:75]
	ds_read_b128 v[70:73], v114 offset:4352
	s_load_dwordx2 s[4:5], s[0:1], 0xb8
	s_waitcnt vmcnt(7) lgkmcnt(0)
	v_pk_add_f32 v[68:69], v[72:73], v[146:147]
	v_pk_add_f32 v[66:67], v[70:71], v[144:145]
	v_lshl_add_u64 v[70:71], s[4:5], 0, v[74:75]
	global_store_dwordx4 v[70:71], v[66:69], off offset:256 nt
	s_or_b64 exec, exec, s[2:3]
	s_and_saveexec_b64 s[2:3], s[10:11]
	s_cbranch_execnz .LBB0_1308

.LBB0_1302:
	v_lshlrev_b64 v[66:67], 10, v[110:111]
	v_lshl_add_u64 v[66:67], v[66:67], 0, v[64:65]
	v_lshlrev_b64 v[74:75], 2, v[66:67]
	v_lshl_add_u64 v[66:67], s[16:17], 0, v[74:75]
	ds_read_b128 v[70:73], v114 offset:6528
	s_load_dwordx2 s[4:5], s[0:1], 0xb8
	s_waitcnt vmcnt(7) lgkmcnt(0)
	v_pk_add_f32 v[68:69], v[72:73], v[154:155]
	v_pk_add_f32 v[66:67], v[70:71], v[152:153]
	v_lshl_add_u64 v[70:71], s[4:5], 0, v[74:75]
	global_store_dwordx4 v[70:71], v[66:69], off offset:256 nt
	s_or_b64 exec, exec, s[2:3]
	s_and_saveexec_b64 s[2:3], s[14:15]
	s_cbranch_execnz .LBB0_1310
	s_branch .LBB0_1311

.LBB0_1304:
	v_lshlrev_b64 v[66:67], 10, v[100:101]
	v_lshl_add_u64 v[66:67], v[66:67], 0, v[64:65]
	v_lshlrev_b64 v[74:75], 2, v[66:67]
	v_lshl_add_u64 v[66:67], s[16:17], 0, v[74:75]
	ds_read_b128 v[70:73], v114 offset:1088
	s_load_dwordx2 s[2:3], s[0:1], 0xb8
	s_waitcnt vmcnt(7) lgkmcnt(0)
	v_pk_add_f32 v[68:69], v[72:73], v[134:135]
	v_pk_add_f32 v[66:67], v[70:71], v[132:133]
	v_lshl_add_u64 v[70:71], s[2:3], 0, v[74:75]
	global_store_dwordx4 v[70:71], v[66:69], off offset:256 nt
	s_or_b64 exec, exec, s[26:27]
	s_and_saveexec_b64 s[2:3], s[4:5]
	s_cbranch_execnz .LBB0_1298

.LBB0_1306:
	v_lshlrev_b64 v[66:67], 10, v[104:105]
	v_lshl_add_u64 v[66:67], v[66:67], 0, v[64:65]
	v_lshlrev_b64 v[74:75], 2, v[66:67]
	v_lshl_add_u64 v[66:67], s[16:17], 0, v[74:75]
	ds_read_b128 v[70:73], v114 offset:3264
	s_load_dwordx2 s[4:5], s[0:1], 0xb8
	s_waitcnt vmcnt(7) lgkmcnt(0)
	v_pk_add_f32 v[68:69], v[72:73], v[142:143]
	v_pk_add_f32 v[66:67], v[70:71], v[140:141]
	v_lshl_add_u64 v[70:71], s[4:5], 0, v[74:75]
	global_store_dwordx4 v[70:71], v[66:69], off offset:256 nt
	s_or_b64 exec, exec, s[2:3]
	s_and_saveexec_b64 s[2:3], s[8:9]
	s_cbranch_execnz .LBB0_1300

.LBB0_1308:
	v_lshlrev_b64 v[66:67], 10, v[108:109]
	v_lshl_add_u64 v[66:67], v[66:67], 0, v[64:65]
	v_lshlrev_b64 v[74:75], 2, v[66:67]
	v_lshl_add_u64 v[66:67], s[16:17], 0, v[74:75]
	ds_read_b128 v[70:73], v114 offset:5440
	s_load_dwordx2 s[4:5], s[0:1], 0xb8
	s_waitcnt vmcnt(7) lgkmcnt(0)
	v_pk_add_f32 v[68:69], v[72:73], v[150:151]
	v_pk_add_f32 v[66:67], v[70:71], v[148:149]
	v_lshl_add_u64 v[70:71], s[4:5], 0, v[74:75]
	global_store_dwordx4 v[70:71], v[66:69], off offset:256 nt
	s_or_b64 exec, exec, s[2:3]
	s_and_saveexec_b64 s[2:3], s[12:13]
	s_cbranch_execnz .LBB0_1302

.LBB0_1310:
	v_lshlrev_b64 v[66:67], 10, v[112:113]
	v_lshl_add_u64 v[66:67], v[66:67], 0, v[64:65]
	v_lshlrev_b64 v[74:75], 2, v[66:67]
	v_lshl_add_u64 v[66:67], s[16:17], 0, v[74:75]
	ds_read_b128 v[70:73], v114 offset:7616
	s_load_dwordx2 s[4:5], s[0:1], 0xb8
	s_waitcnt vmcnt(7) lgkmcnt(0)
	v_pk_add_f32 v[68:69], v[72:73], v[158:159]
	v_pk_add_f32 v[66:67], v[70:71], v[156:157]
	v_lshl_add_u64 v[70:71], s[4:5], 0, v[74:75]
	global_store_dwordx4 v[70:71], v[66:69], off offset:256 nt
.LBB0_1311:
	s_or_b64 exec, exec, s[2:3]
	s_or_b32 s2, s55, 32
	v_add_u32_e32 v102, s2, v183
	v_min_i32_e32 v66, 0x7fff, v102
	v_add_u32_e32 v68, 8, v102
	v_add_u32_e32 v70, 9, v102
	v_add_u32_e32 v72, 10, v102
	v_ashrrev_i32_e32 v66, 12, v66
	v_min_i32_e32 v68, 0x7fff, v68
	v_min_i32_e32 v70, 0x7fff, v70
	v_min_i32_e32 v72, 0x7fff, v72
	v_mul_hi_i32_i24_e32 v67, 0x3000, v66
	v_mul_i32_i24_e32 v66, 0x3000, v66
	v_ashrrev_i32_e32 v68, 12, v68
	v_ashrrev_i32_e32 v70, 12, v70
	v_ashrrev_i32_e32 v72, 12, v72
	v_lshl_add_u64 v[66:67], s[24:25], 0, v[66:67]
	v_mul_hi_i32_i24_e32 v69, 0x3000, v68
	v_mul_i32_i24_e32 v68, 0x3000, v68
	v_mul_hi_i32_i24_e32 v71, 0x3000, v70
	v_mul_i32_i24_e32 v70, 0x3000, v70
	v_mul_hi_i32_i24_e32 v73, 0x3000, v72
	v_mul_i32_i24_e32 v72, 0x3000, v72
	v_lshl_add_u64 v[66:67], v[66:67], 0, s[18:19]
	v_lshl_add_u64 v[68:69], s[24:25], 0, v[68:69]
	v_lshl_add_u64 v[70:71], s[24:25], 0, v[70:71]
	v_lshl_add_u64 v[72:73], s[24:25], 0, v[72:73]
	v_lshl_add_u64 v[74:75], v[66:67], 0, v[180:181]
	v_lshl_add_u64 v[68:69], v[68:69], 0, s[18:19]
	v_lshl_add_u64 v[70:71], v[70:71], 0, s[18:19]
	v_lshl_add_u64 v[72:73], v[72:73], 0, s[18:19]
	v_lshl_add_u64 v[76:77], v[68:69], 0, v[180:181]
	v_lshl_add_u64 v[78:79], v[70:71], 0, v[180:181]
	v_lshl_add_u64 v[80:81], v[72:73], 0, v[180:181]
	global_load_dword v103, v[74:75], off
	global_load_dword v104, v[74:75], off offset:128
	global_load_dword v105, v[76:77], off
	global_load_dword v106, v[76:77], off offset:128
	global_load_dword v107, v[78:79], off
	global_load_dword v108, v[78:79], off offset:128
	global_load_dword v109, v[80:81], off
	global_load_dword v110, v[80:81], off offset:128
	v_add_u32_e32 v74, 11, v102
	v_add_u32_e32 v82, 18, v102
	v_min_i32_e32 v74, 0x7fff, v74
	v_add_u32_e32 v76, 16, v102
	v_add_u32_e32 v80, 17, v102
	v_min_i32_e32 v82, 0x7fff, v82
	v_ashrrev_i32_e32 v74, 12, v74
	v_min_i32_e32 v76, 0x7fff, v76
	v_min_i32_e32 v80, 0x7fff, v80
	v_ashrrev_i32_e32 v82, 12, v82
	v_mul_hi_i32_i24_e32 v75, 0x3000, v74
	v_mul_i32_i24_e32 v74, 0x3000, v74
	v_ashrrev_i32_e32 v76, 12, v76
	v_ashrrev_i32_e32 v80, 12, v80
	v_mul_hi_i32_i24_e32 v83, 0x3000, v82
	v_mul_i32_i24_e32 v82, 0x3000, v82
	v_lshl_add_u64 v[74:75], s[24:25], 0, v[74:75]
	v_mul_hi_i32_i24_e32 v77, 0x3000, v76
	v_mul_i32_i24_e32 v76, 0x3000, v76
	v_mul_hi_i32_i24_e32 v81, 0x3000, v80
	v_mul_i32_i24_e32 v80, 0x3000, v80
	v_lshl_add_u64 v[82:83], s[24:25], 0, v[82:83]
	v_lshl_add_u64 v[74:75], v[74:75], 0, s[18:19]
	v_lshl_add_u64 v[76:77], s[24:25], 0, v[76:77]
	v_lshl_add_u64 v[80:81], s[24:25], 0, v[80:81]
	v_lshl_add_u64 v[82:83], v[82:83], 0, s[18:19]
	v_lshl_add_u64 v[78:79], v[74:75], 0, v[180:181]
	v_lshl_add_u64 v[76:77], v[76:77], 0, s[18:19]
	v_lshl_add_u64 v[80:81], v[80:81], 0, s[18:19]
	v_lshl_add_u64 v[88:89], v[82:83], 0, v[180:181]
	v_lshl_add_u64 v[84:85], v[76:77], 0, v[180:181]
	v_lshl_add_u64 v[86:87], v[80:81], 0, v[180:181]
	global_load_dword v111, v[78:79], off
	global_load_dword v112, v[78:79], off offset:128
	global_load_dword v113, v[84:85], off
	global_load_dword v122, v[84:85], off offset:128
	global_load_dword v123, v[86:87], off
	global_load_dword v124, v[86:87], off offset:128
	global_load_dword v125, v[88:89], off
	global_load_dword v126, v[88:89], off offset:128
	v_add_u32_e32 v78, 19, v102
	v_add_u32_e32 v88, 25, v102
	v_add_u32_e32 v90, 26, v102
	v_min_i32_e32 v78, 0x7fff, v78
	v_add_u32_e32 v86, 24, v102
	v_min_i32_e32 v88, 0x7fff, v88
	v_min_i32_e32 v90, 0x7fff, v90
	v_ashrrev_i32_e32 v78, 12, v78
	v_min_i32_e32 v86, 0x7fff, v86
	v_ashrrev_i32_e32 v88, 12, v88
	v_ashrrev_i32_e32 v90, 12, v90
	v_mul_hi_i32_i24_e32 v79, 0x3000, v78
	v_mul_i32_i24_e32 v78, 0x3000, v78
	v_ashrrev_i32_e32 v86, 12, v86
	v_mul_hi_i32_i24_e32 v89, 0x3000, v88
	v_mul_i32_i24_e32 v88, 0x3000, v88
	v_mul_hi_i32_i24_e32 v91, 0x3000, v90
	v_mul_i32_i24_e32 v90, 0x3000, v90
	v_lshl_add_u64 v[78:79], s[24:25], 0, v[78:79]
	v_mul_hi_i32_i24_e32 v87, 0x3000, v86
	v_mul_i32_i24_e32 v86, 0x3000, v86
	v_lshl_add_u64 v[88:89], s[24:25], 0, v[88:89]
	v_lshl_add_u64 v[90:91], s[24:25], 0, v[90:91]
	v_lshl_add_u64 v[84:85], v[78:79], 0, s[18:19]
	v_lshl_add_u64 v[86:87], s[24:25], 0, v[86:87]
	v_lshl_add_u64 v[88:89], v[88:89], 0, s[18:19]
	v_lshl_add_u64 v[90:91], v[90:91], 0, s[18:19]
	v_lshl_add_u64 v[78:79], v[84:85], 0, v[180:181]
	v_lshl_add_u64 v[86:87], v[86:87], 0, s[18:19]
	v_lshl_add_u64 v[94:95], v[88:89], 0, v[180:181]
	v_lshl_add_u64 v[100:101], v[90:91], 0, v[180:181]
	v_lshl_add_u64 v[92:93], v[86:87], 0, v[180:181]
	global_load_dword v127, v[78:79], off
	global_load_dword v160, v[78:79], off offset:128
	global_load_dword v161, v[92:93], off
	global_load_dword v164, v[92:93], off offset:128
	global_load_dword v165, v[94:95], off
	s_nop 0
	global_load_dword v94, v[94:95], off offset:128
	s_nop 0
	global_load_dword v95, v[100:101], off
	s_nop 0
	global_load_dword v100, v[100:101], off offset:128
	v_add_u32_e32 v78, 27, v102
	v_min_i32_e32 v78, 0x7fff, v78
	v_ashrrev_i32_e32 v78, 12, v78
	v_mul_hi_i32_i24_e32 v79, 0x3000, v78
	v_mul_i32_i24_e32 v78, 0x3000, v78
	v_lshl_add_u64 v[78:79], s[24:25], 0, v[78:79]
	v_lshl_add_u64 v[92:93], v[78:79], 0, s[18:19]
	v_lshl_add_u64 v[78:79], v[92:93], 0, v[180:181]
	global_load_dword v101, v[78:79], off
	s_nop 0
	global_load_dword v79, v[78:79], off offset:128
	s_waitcnt vmcnt(25)
	v_mul_f32_e32 v48, v48, v103
	s_waitcnt vmcnt(24)
	v_mul_f32_e32 v32, v32, v104
	ds_write2_b32 v162, v48, v32 offset1:32
	v_mul_f32_e32 v32, v49, v103
	v_mul_f32_e32 v33, v33, v104
	ds_write2_b32 v162, v32, v33 offset0:68 offset1:100
	v_mul_f32_e32 v32, v50, v103
	v_mul_f32_e32 v33, v34, v104
	ds_write2_b32 v162, v32, v33 offset0:136 offset1:168
	v_mul_f32_e32 v32, v51, v103
	v_mul_f32_e32 v33, v35, v104
	ds_write2_b32 v162, v32, v33 offset0:204 offset1:236
	s_waitcnt vmcnt(23)
	v_mul_f32_e32 v32, v52, v105
	s_waitcnt vmcnt(22)
	v_mul_f32_e32 v33, v36, v106
	ds_write2_b32 v115, v32, v33 offset0:32 offset1:64
	s_waitcnt vmcnt(21)
	v_mul_f32_e32 v32, v53, v107
	s_waitcnt vmcnt(20)
	v_mul_f32_e32 v33, v37, v108
	ds_write2_b32 v115, v32, v33 offset0:100 offset1:132
	s_waitcnt vmcnt(19)
	v_mul_f32_e32 v32, v54, v109
	s_waitcnt vmcnt(18)
	v_mul_f32_e32 v33, v38, v110
	ds_write2_b32 v115, v32, v33 offset0:168 offset1:200
	v_add_u32_e32 v78, s2, v163
	v_cmp_gt_i32_e32 vcc, s38, v78
	s_waitcnt vmcnt(17)
	v_mul_f32_e32 v32, v55, v111
	s_waitcnt vmcnt(16)
	v_mul_f32_e32 v33, v39, v112
	ds_write2_b32 v116, v32, v33 offset0:108 offset1:140
	s_waitcnt vmcnt(15)
	v_mul_f32_e32 v32, v56, v113
	s_waitcnt vmcnt(14)
	v_mul_f32_e32 v33, v40, v122
	ds_write2_b32 v117, v32, v33 offset0:64 offset1:96
	s_waitcnt vmcnt(13)
	v_mul_f32_e32 v32, v57, v123
	s_waitcnt vmcnt(12)
	v_mul_f32_e32 v33, v41, v124
	ds_write2_b32 v117, v32, v33 offset0:132 offset1:164
	s_waitcnt vmcnt(11)
	v_mul_f32_e32 v32, v58, v125
	s_waitcnt vmcnt(10)
	v_mul_f32_e32 v33, v42, v126
	ds_write2_b32 v117, v32, v33 offset0:200 offset1:232
	s_waitcnt vmcnt(9)
	v_mul_f32_e32 v32, v59, v127
	s_waitcnt vmcnt(8)
	v_mul_f32_e32 v33, v43, v160
	ds_write2_b32 v118, v32, v33 offset0:12 offset1:44
	s_waitcnt vmcnt(7)
	v_mul_f32_e32 v32, v60, v161
	s_waitcnt vmcnt(6)
	v_mul_f32_e32 v33, v44, v164
	ds_write2_b32 v119, v32, v33 offset0:96 offset1:128
	s_waitcnt vmcnt(5)
	v_mul_f32_e32 v32, v61, v165
	s_waitcnt vmcnt(4)
	v_mul_f32_e32 v33, v45, v94
	ds_write2_b32 v119, v32, v33 offset0:164 offset1:196
	s_waitcnt vmcnt(3)
	v_mul_f32_e32 v32, v62, v95
	s_waitcnt vmcnt(2)
	v_mul_f32_e32 v33, v46, v100
	ds_write2_b32 v120, v32, v33 offset0:104 offset1:136
	s_waitcnt vmcnt(1)
	v_mul_f32_e32 v32, v63, v101
	s_waitcnt vmcnt(0)
	v_mul_f32_e32 v33, v47, v79
	v_ashrrev_i32_e32 v79, 31, v78
	ds_write2_b32 v121, v32, v33 offset0:44 offset1:76
	v_add_u32_e32 v128, 0, v78
	v_ashrrev_i32_e32 v129, 31, v128
	v_lshlrev_b64 v[128:129], 10, v[128:129]
	v_lshl_add_u64 v[128:129], v[128:129], 0, v[96:97]
	v_lshlrev_b64 v[128:129], 2, v[128:129]
	v_lshl_add_u64 v[128:129], s[16:17], 0, v[128:129]
	global_load_dwordx4 v[128:131], v[128:129], off nt
	v_add_u32_e32 v132, 4, v78
	v_ashrrev_i32_e32 v133, 31, v132
	v_lshlrev_b64 v[132:133], 10, v[132:133]
	v_lshl_add_u64 v[132:133], v[132:133], 0, v[96:97]
	v_lshlrev_b64 v[132:133], 2, v[132:133]
	v_lshl_add_u64 v[132:133], s[16:17], 0, v[132:133]
	global_load_dwordx4 v[132:135], v[132:133], off nt
	v_add_u32_e32 v136, 8, v78
	v_ashrrev_i32_e32 v137, 31, v136
	v_lshlrev_b64 v[136:137], 10, v[136:137]
	v_lshl_add_u64 v[136:137], v[136:137], 0, v[96:97]
	v_lshlrev_b64 v[136:137], 2, v[136:137]
	v_lshl_add_u64 v[136:137], s[16:17], 0, v[136:137]
	global_load_dwordx4 v[136:139], v[136:137], off nt
	v_add_u32_e32 v140, 12, v78
	v_ashrrev_i32_e32 v141, 31, v140
	v_lshlrev_b64 v[140:141], 10, v[140:141]
	v_lshl_add_u64 v[140:141], v[140:141], 0, v[96:97]
	v_lshlrev_b64 v[140:141], 2, v[140:141]
	v_lshl_add_u64 v[140:141], s[16:17], 0, v[140:141]
	global_load_dwordx4 v[140:143], v[140:141], off nt
	v_add_u32_e32 v144, 16, v78
	v_ashrrev_i32_e32 v145, 31, v144
	v_lshlrev_b64 v[144:145], 10, v[144:145]
	v_lshl_add_u64 v[144:145], v[144:145], 0, v[96:97]
	v_lshlrev_b64 v[144:145], 2, v[144:145]
	v_lshl_add_u64 v[144:145], s[16:17], 0, v[144:145]
	global_load_dwordx4 v[144:147], v[144:145], off nt
	v_add_u32_e32 v148, 20, v78
	v_ashrrev_i32_e32 v149, 31, v148
	v_lshlrev_b64 v[148:149], 10, v[148:149]
	v_lshl_add_u64 v[148:149], v[148:149], 0, v[96:97]
	v_lshlrev_b64 v[148:149], 2, v[148:149]
	v_lshl_add_u64 v[148:149], s[16:17], 0, v[148:149]
	global_load_dwordx4 v[148:151], v[148:149], off nt
	v_add_u32_e32 v152, 24, v78
	v_ashrrev_i32_e32 v153, 31, v152
	v_lshlrev_b64 v[152:153], 10, v[152:153]
	v_lshl_add_u64 v[152:153], v[152:153], 0, v[96:97]
	v_lshlrev_b64 v[152:153], 2, v[152:153]
	v_lshl_add_u64 v[152:153], s[16:17], 0, v[152:153]
	global_load_dwordx4 v[152:155], v[152:153], off nt
	v_add_u32_e32 v156, 28, v78
	v_ashrrev_i32_e32 v157, 31, v156
	v_lshlrev_b64 v[156:157], 10, v[156:157]
	v_lshl_add_u64 v[156:157], v[156:157], 0, v[96:97]
	v_lshlrev_b64 v[156:157], 2, v[156:157]
	v_lshl_add_u64 v[156:157], s[16:17], 0, v[156:157]
	global_load_dwordx4 v[156:159], v[156:157], off nt
	s_and_saveexec_b64 s[2:3], vcc
	s_cbranch_execz .LBB0_1313
	v_lshlrev_b64 v[32:33], 10, v[78:79]
	v_lshl_add_u64 v[32:33], v[32:33], 0, v[96:97]
	v_lshlrev_b64 v[40:41], 2, v[32:33]
	v_lshl_add_u64 v[32:33], s[16:17], 0, v[40:41]
	ds_read_b128 v[36:39], v114
	s_load_dwordx2 s[4:5], s[0:1], 0xb8
	s_waitcnt vmcnt(7) lgkmcnt(0)
	v_pk_add_f32 v[34:35], v[38:39], v[130:131]
	v_pk_add_f32 v[32:33], v[36:37], v[128:129]
	v_lshl_add_u64 v[36:37], s[4:5], 0, v[40:41]
	global_store_dwordx4 v[36:37], v[32:35], off nt
.LBB0_1313:
	s_or_b64 exec, exec, s[2:3]
	s_nop 0
	v_add_u32_e32 v32, 4, v78
	v_cmp_gt_i32_e64 s[2:3], s39, v78
	v_ashrrev_i32_e32 v33, 31, v32
	s_and_saveexec_b64 s[4:5], s[2:3]
	s_cbranch_execz .LBB0_1315
	v_lshlrev_b64 v[34:35], 10, v[32:33]
	v_lshl_add_u64 v[34:35], v[34:35], 0, v[96:97]
	v_lshlrev_b64 v[42:43], 2, v[34:35]
	v_lshl_add_u64 v[34:35], s[16:17], 0, v[42:43]
	ds_read_b128 v[38:41], v114 offset:1088
	s_load_dwordx2 s[6:7], s[0:1], 0xb8
	s_waitcnt vmcnt(7) lgkmcnt(0)
	v_pk_add_f32 v[36:37], v[40:41], v[134:135]
	v_pk_add_f32 v[34:35], v[38:39], v[132:133]
	v_lshl_add_u64 v[38:39], s[6:7], 0, v[42:43]
	global_store_dwordx4 v[38:39], v[34:37], off nt
.LBB0_1315:
	s_or_b64 exec, exec, s[4:5]
	s_nop 0
	v_add_u32_e32 v34, 8, v78
	v_cmp_gt_i32_e64 s[4:5], s48, v78
	v_ashrrev_i32_e32 v35, 31, v34
	s_and_saveexec_b64 s[6:7], s[4:5]
	s_cbranch_execz .LBB0_1317
	v_lshlrev_b64 v[36:37], 10, v[34:35]
	v_lshl_add_u64 v[36:37], v[36:37], 0, v[96:97]
	v_lshlrev_b64 v[44:45], 2, v[36:37]
	v_lshl_add_u64 v[36:37], s[16:17], 0, v[44:45]
	ds_read_b128 v[40:43], v114 offset:2176
	s_load_dwordx2 s[8:9], s[0:1], 0xb8
	s_waitcnt vmcnt(7) lgkmcnt(0)
	v_pk_add_f32 v[38:39], v[42:43], v[138:139]
	v_pk_add_f32 v[36:37], v[40:41], v[136:137]
	v_lshl_add_u64 v[40:41], s[8:9], 0, v[44:45]
	global_store_dwordx4 v[40:41], v[36:39], off nt
.LBB0_1317:
	s_or_b64 exec, exec, s[6:7]
	s_nop 0
	v_add_u32_e32 v36, 12, v78
	v_cmp_gt_i32_e64 s[6:7], s49, v78
	v_ashrrev_i32_e32 v37, 31, v36
	s_and_saveexec_b64 s[8:9], s[6:7]
	s_cbranch_execz .LBB0_1319
	v_lshlrev_b64 v[38:39], 10, v[36:37]
	v_lshl_add_u64 v[38:39], v[38:39], 0, v[96:97]
	v_lshlrev_b64 v[46:47], 2, v[38:39]
	v_lshl_add_u64 v[38:39], s[16:17], 0, v[46:47]
	ds_read_b128 v[42:45], v114 offset:3264
	s_load_dwordx2 s[10:11], s[0:1], 0xb8
	s_waitcnt vmcnt(7) lgkmcnt(0)
	v_pk_add_f32 v[40:41], v[44:45], v[142:143]
	v_pk_add_f32 v[38:39], v[42:43], v[140:141]
	v_lshl_add_u64 v[42:43], s[10:11], 0, v[46:47]
	global_store_dwordx4 v[42:43], v[38:41], off nt
.LBB0_1319:
	s_or_b64 exec, exec, s[8:9]
	s_nop 0
	v_add_u32_e32 v38, 16, v78
	v_cmp_gt_i32_e64 s[8:9], s50, v78
	v_ashrrev_i32_e32 v39, 31, v38
	s_and_saveexec_b64 s[10:11], s[8:9]
	s_cbranch_execz .LBB0_1321
	v_lshlrev_b64 v[40:41], 10, v[38:39]
	v_lshl_add_u64 v[40:41], v[40:41], 0, v[96:97]
	v_lshlrev_b64 v[48:49], 2, v[40:41]
	v_lshl_add_u64 v[40:41], s[16:17], 0, v[48:49]
	ds_read_b128 v[44:47], v114 offset:4352
	s_load_dwordx2 s[12:13], s[0:1], 0xb8
	s_waitcnt vmcnt(7) lgkmcnt(0)
	v_pk_add_f32 v[42:43], v[46:47], v[146:147]
	v_pk_add_f32 v[40:41], v[44:45], v[144:145]
	v_lshl_add_u64 v[44:45], s[12:13], 0, v[48:49]
	global_store_dwordx4 v[44:45], v[40:43], off nt
.LBB0_1321:
	s_or_b64 exec, exec, s[10:11]
	s_nop 0
	v_add_u32_e32 v40, 20, v78
	v_cmp_gt_i32_e64 s[10:11], s51, v78
	v_ashrrev_i32_e32 v41, 31, v40
	s_and_saveexec_b64 s[12:13], s[10:11]
	s_cbranch_execz .LBB0_1323
	v_lshlrev_b64 v[42:43], 10, v[40:41]
	v_lshl_add_u64 v[42:43], v[42:43], 0, v[96:97]
	v_lshlrev_b64 v[50:51], 2, v[42:43]
	v_lshl_add_u64 v[42:43], s[16:17], 0, v[50:51]
	ds_read_b128 v[46:49], v114 offset:5440
	s_load_dwordx2 s[14:15], s[0:1], 0xb8
	s_waitcnt vmcnt(7) lgkmcnt(0)
	v_pk_add_f32 v[44:45], v[48:49], v[150:151]
	v_pk_add_f32 v[42:43], v[46:47], v[148:149]
	v_lshl_add_u64 v[46:47], s[14:15], 0, v[50:51]
	global_store_dwordx4 v[46:47], v[42:45], off nt
.LBB0_1323:
	s_or_b64 exec, exec, s[12:13]
	s_nop 0
	v_add_u32_e32 v42, 24, v78
	v_cmp_gt_i32_e64 s[12:13], s52, v78
	v_ashrrev_i32_e32 v43, 31, v42
	s_and_saveexec_b64 s[14:15], s[12:13]
	s_cbranch_execz .LBB0_1325
	v_lshlrev_b64 v[44:45], 10, v[42:43]
	v_lshl_add_u64 v[44:45], v[44:45], 0, v[96:97]
	v_lshlrev_b64 v[52:53], 2, v[44:45]
	v_lshl_add_u64 v[44:45], s[16:17], 0, v[52:53]
	ds_read_b128 v[48:51], v114 offset:6528
	s_load_dwordx2 s[24:25], s[0:1], 0xb8
	s_waitcnt vmcnt(7) lgkmcnt(0)
	v_pk_add_f32 v[46:47], v[50:51], v[154:155]
	v_pk_add_f32 v[44:45], v[48:49], v[152:153]
	v_lshl_add_u64 v[48:49], s[24:25], 0, v[52:53]
	global_store_dwordx4 v[48:49], v[44:47], off nt
.LBB0_1325:
	s_or_b64 exec, exec, s[14:15]
	s_nop 0
	v_add_u32_e32 v44, 28, v78
	v_cmp_gt_i32_e64 s[14:15], s53, v78
	v_ashrrev_i32_e32 v45, 31, v44
	s_and_saveexec_b64 s[24:25], s[14:15]
	s_cbranch_execz .LBB0_1327
	v_lshlrev_b64 v[46:47], 10, v[44:45]
	v_lshl_add_u64 v[46:47], v[46:47], 0, v[96:97]
	v_lshlrev_b64 v[54:55], 2, v[46:47]
	v_lshl_add_u64 v[46:47], s[16:17], 0, v[54:55]
	ds_read_b128 v[50:53], v114 offset:7616
	s_load_dwordx2 s[26:27], s[0:1], 0xb8
	s_waitcnt vmcnt(7) lgkmcnt(0)
	v_pk_add_f32 v[48:49], v[52:53], v[158:159]
	v_pk_add_f32 v[46:47], v[50:51], v[156:157]
	v_lshl_add_u64 v[50:51], s[26:27], 0, v[54:55]
	global_store_dwordx4 v[50:51], v[46:49], off nt
.LBB0_1327:
	s_or_b64 exec, exec, s[24:25]
	s_nop 0
	v_lshl_add_u64 v[46:47], v[66:67], 0, v[98:99]
	v_lshl_add_u64 v[48:49], v[68:69], 0, v[98:99]
	v_lshl_add_u64 v[50:51], v[70:71], 0, v[98:99]
	v_lshl_add_u64 v[52:53], v[72:73], 0, v[98:99]
	global_load_dword v54, v[46:47], off
	global_load_dword v55, v[46:47], off offset:128
	global_load_dword v56, v[48:49], off
	global_load_dword v57, v[48:49], off offset:128
	global_load_dword v58, v[50:51], off
	global_load_dword v59, v[50:51], off offset:128
	global_load_dword v60, v[52:53], off
	global_load_dword v61, v[52:53], off offset:128
	v_lshl_add_u64 v[46:47], v[74:75], 0, v[98:99]
	v_lshl_add_u64 v[48:49], v[76:77], 0, v[98:99]
	v_lshl_add_u64 v[50:51], v[80:81], 0, v[98:99]
	v_lshl_add_u64 v[52:53], v[82:83], 0, v[98:99]
	global_load_dword v62, v[46:47], off
	global_load_dword v63, v[46:47], off offset:128
	global_load_dword v66, v[48:49], off
	global_load_dword v67, v[48:49], off offset:128
	global_load_dword v68, v[50:51], off
	global_load_dword v69, v[50:51], off offset:128
	global_load_dword v70, v[52:53], off
	global_load_dword v71, v[52:53], off offset:128
	v_lshl_add_u64 v[46:47], v[84:85], 0, v[98:99]
	v_lshl_add_u64 v[48:49], v[86:87], 0, v[98:99]
	v_lshl_add_u64 v[50:51], v[88:89], 0, v[98:99]
	v_lshl_add_u64 v[52:53], v[90:91], 0, v[98:99]
	global_load_dword v72, v[46:47], off
	global_load_dword v73, v[46:47], off offset:128
	global_load_dword v74, v[48:49], off
	s_nop 0
	global_load_dword v48, v[48:49], off offset:128
	s_nop 0
	global_load_dword v49, v[50:51], off
	s_nop 0
	global_load_dword v50, v[50:51], off offset:128
	s_nop 0
	global_load_dword v51, v[52:53], off
	s_nop 0
	global_load_dword v52, v[52:53], off offset:128
	v_lshl_add_u64 v[46:47], v[92:93], 0, v[98:99]
	global_load_dword v53, v[46:47], off
	s_nop 0
	global_load_dword v46, v[46:47], off offset:128
	s_waitcnt vmcnt(25)
	v_mul_f32_e32 v16, v16, v54
	s_waitcnt vmcnt(24)
	v_mul_f32_e32 v0, v0, v55
	v_mul_f32_e32 v1, v1, v55
	v_mul_f32_e32 v17, v17, v54
	v_mul_f32_e32 v18, v18, v54
	v_mul_f32_e32 v2, v2, v55
	v_mul_f32_e32 v19, v19, v54
	v_mul_f32_e32 v3, v3, v55
	s_waitcnt vmcnt(23)
	v_mul_f32_e32 v20, v20, v56
	s_waitcnt vmcnt(22)
	v_mul_f32_e32 v4, v4, v57
	s_waitcnt vmcnt(21)
	v_mul_f32_e32 v21, v21, v58
	s_waitcnt vmcnt(20)
	v_mul_f32_e32 v5, v5, v59
	s_waitcnt vmcnt(19)
	v_mul_f32_e32 v22, v22, v60
	s_waitcnt vmcnt(18)
	v_mul_f32_e32 v6, v6, v61
	s_waitcnt vmcnt(17)
	v_mul_f32_e32 v23, v23, v62
	s_waitcnt vmcnt(16)
	v_mul_f32_e32 v7, v7, v63
	s_waitcnt vmcnt(15)
	v_mul_f32_e32 v24, v24, v66
	s_waitcnt vmcnt(14)
	v_mul_f32_e32 v8, v8, v67
	s_waitcnt vmcnt(13)
	v_mul_f32_e32 v25, v25, v68
	s_waitcnt vmcnt(12)
	v_mul_f32_e32 v9, v9, v69
	s_waitcnt vmcnt(11)
	v_mul_f32_e32 v26, v26, v70
	s_waitcnt vmcnt(10)
	v_mul_f32_e32 v10, v10, v71
	s_waitcnt vmcnt(9)
	v_mul_f32_e32 v27, v27, v72
	s_waitcnt vmcnt(8)
	v_mul_f32_e32 v11, v11, v73
	s_waitcnt vmcnt(7)
	v_mul_f32_e32 v28, v28, v74
	s_waitcnt vmcnt(6)
	v_mul_f32_e32 v12, v12, v48
	s_waitcnt vmcnt(5)
	v_mul_f32_e32 v29, v29, v49
	s_waitcnt vmcnt(4)
	v_mul_f32_e32 v13, v13, v50
	s_waitcnt vmcnt(3)
	v_mul_f32_e32 v30, v30, v51
	s_waitcnt vmcnt(2)
	v_mul_f32_e32 v14, v14, v52
	ds_write2_b32 v162, v16, v0 offset1:32
	ds_write2_b32 v162, v17, v1 offset0:68 offset1:100
	ds_write2_b32 v162, v18, v2 offset0:136 offset1:168
	ds_write2_b32 v162, v19, v3 offset0:204 offset1:236
	ds_write2_b32 v115, v20, v4 offset0:32 offset1:64
	ds_write2_b32 v115, v21, v5 offset0:100 offset1:132
	ds_write2_b32 v115, v22, v6 offset0:168 offset1:200
	ds_write2_b32 v116, v23, v7 offset0:108 offset1:140
	ds_write2_b32 v117, v24, v8 offset0:64 offset1:96
	ds_write2_b32 v117, v25, v9 offset0:132 offset1:164
	ds_write2_b32 v117, v26, v10 offset0:200 offset1:232
	ds_write2_b32 v118, v27, v11 offset0:12 offset1:44
	ds_write2_b32 v119, v28, v12 offset0:96 offset1:128
	ds_write2_b32 v119, v29, v13 offset0:164 offset1:196
	ds_write2_b32 v120, v30, v14 offset0:104 offset1:136
	s_waitcnt vmcnt(1)
	v_mul_f32_e32 v0, v31, v53
	s_waitcnt vmcnt(0)
	v_mul_f32_e32 v1, v15, v46
	ds_write2_b32 v121, v0, v1 offset0:44 offset1:76
	v_add_u32_e32 v128, 0, v78
	v_ashrrev_i32_e32 v129, 31, v128
	v_lshlrev_b64 v[128:129], 10, v[128:129]
	v_lshl_add_u64 v[128:129], v[128:129], 0, v[64:65]
	v_lshlrev_b64 v[128:129], 2, v[128:129]
	v_lshl_add_u64 v[128:129], s[16:17], 0, v[128:129]
	global_load_dwordx4 v[128:131], v[128:129], off offset:256 nt
	v_add_u32_e32 v132, 4, v78
	v_ashrrev_i32_e32 v133, 31, v132
	v_lshlrev_b64 v[132:133], 10, v[132:133]
	v_lshl_add_u64 v[132:133], v[132:133], 0, v[64:65]
	v_lshlrev_b64 v[132:133], 2, v[132:133]
	v_lshl_add_u64 v[132:133], s[16:17], 0, v[132:133]
	global_load_dwordx4 v[132:135], v[132:133], off offset:256 nt
	v_add_u32_e32 v136, 8, v78
	v_ashrrev_i32_e32 v137, 31, v136
	v_lshlrev_b64 v[136:137], 10, v[136:137]
	v_lshl_add_u64 v[136:137], v[136:137], 0, v[64:65]
	v_lshlrev_b64 v[136:137], 2, v[136:137]
	v_lshl_add_u64 v[136:137], s[16:17], 0, v[136:137]
	global_load_dwordx4 v[136:139], v[136:137], off offset:256 nt
	v_add_u32_e32 v140, 12, v78
	v_ashrrev_i32_e32 v141, 31, v140
	v_lshlrev_b64 v[140:141], 10, v[140:141]
	v_lshl_add_u64 v[140:141], v[140:141], 0, v[64:65]
	v_lshlrev_b64 v[140:141], 2, v[140:141]
	v_lshl_add_u64 v[140:141], s[16:17], 0, v[140:141]
	global_load_dwordx4 v[140:143], v[140:141], off offset:256 nt
	v_add_u32_e32 v144, 16, v78
	v_ashrrev_i32_e32 v145, 31, v144
	v_lshlrev_b64 v[144:145], 10, v[144:145]
	v_lshl_add_u64 v[144:145], v[144:145], 0, v[64:65]
	v_lshlrev_b64 v[144:145], 2, v[144:145]
	v_lshl_add_u64 v[144:145], s[16:17], 0, v[144:145]
	global_load_dwordx4 v[144:147], v[144:145], off offset:256 nt
	v_add_u32_e32 v148, 20, v78
	v_ashrrev_i32_e32 v149, 31, v148
	v_lshlrev_b64 v[148:149], 10, v[148:149]
	v_lshl_add_u64 v[148:149], v[148:149], 0, v[64:65]
	v_lshlrev_b64 v[148:149], 2, v[148:149]
	v_lshl_add_u64 v[148:149], s[16:17], 0, v[148:149]
	global_load_dwordx4 v[148:151], v[148:149], off offset:256 nt
	v_add_u32_e32 v152, 24, v78
	v_ashrrev_i32_e32 v153, 31, v152
	v_lshlrev_b64 v[152:153], 10, v[152:153]
	v_lshl_add_u64 v[152:153], v[152:153], 0, v[64:65]
	v_lshlrev_b64 v[152:153], 2, v[152:153]
	v_lshl_add_u64 v[152:153], s[16:17], 0, v[152:153]
	global_load_dwordx4 v[152:155], v[152:153], off offset:256 nt
	v_add_u32_e32 v156, 28, v78
	v_ashrrev_i32_e32 v157, 31, v156
	v_lshlrev_b64 v[156:157], 10, v[156:157]
	v_lshl_add_u64 v[156:157], v[156:157], 0, v[64:65]
	v_lshlrev_b64 v[156:157], 2, v[156:157]
	v_lshl_add_u64 v[156:157], s[16:17], 0, v[156:157]
	global_load_dwordx4 v[156:159], v[156:157], off offset:256 nt
	s_and_saveexec_b64 s[24:25], vcc
	s_cbranch_execz .LBB0_1335
	v_lshlrev_b64 v[0:1], 10, v[78:79]
	v_lshl_add_u64 v[0:1], v[0:1], 0, v[64:65]
	v_lshlrev_b64 v[8:9], 2, v[0:1]
	v_lshl_add_u64 v[0:1], s[16:17], 0, v[8:9]
	ds_read_b128 v[4:7], v114
	s_load_dwordx2 s[26:27], s[0:1], 0xb8
	s_waitcnt vmcnt(7) lgkmcnt(0)
	v_pk_add_f32 v[2:3], v[6:7], v[130:131]
	v_pk_add_f32 v[0:1], v[4:5], v[128:129]
	v_lshl_add_u64 v[4:5], s[26:27], 0, v[8:9]
	global_store_dwordx4 v[4:5], v[0:3], off offset:256 nt
	s_or_b64 exec, exec, s[24:25]
	s_and_saveexec_b64 s[24:25], s[2:3]
	s_cbranch_execnz .LBB0_1336

.LBB0_1330:
	v_lshlrev_b64 v[0:1], 10, v[34:35]
	v_lshl_add_u64 v[0:1], v[0:1], 0, v[64:65]
	v_lshlrev_b64 v[8:9], 2, v[0:1]
	v_lshl_add_u64 v[0:1], s[16:17], 0, v[8:9]
	ds_read_b128 v[4:7], v114 offset:2176
	s_load_dwordx2 s[4:5], s[0:1], 0xb8
	s_waitcnt vmcnt(7) lgkmcnt(0)
	v_pk_add_f32 v[2:3], v[6:7], v[138:139]
	v_pk_add_f32 v[0:1], v[4:5], v[136:137]
	v_lshl_add_u64 v[4:5], s[4:5], 0, v[8:9]
	global_store_dwordx4 v[4:5], v[0:3], off offset:256 nt
	s_or_b64 exec, exec, s[2:3]
	s_and_saveexec_b64 s[2:3], s[6:7]
	s_cbranch_execnz .LBB0_1338

.LBB0_1332:
	v_lshlrev_b64 v[0:1], 10, v[38:39]
	v_lshl_add_u64 v[0:1], v[0:1], 0, v[64:65]
	v_lshlrev_b64 v[8:9], 2, v[0:1]
	v_lshl_add_u64 v[0:1], s[16:17], 0, v[8:9]
	ds_read_b128 v[4:7], v114 offset:4352
	s_load_dwordx2 s[4:5], s[0:1], 0xb8
	s_waitcnt vmcnt(7) lgkmcnt(0)
	v_pk_add_f32 v[2:3], v[6:7], v[146:147]
	v_pk_add_f32 v[0:1], v[4:5], v[144:145]
	v_lshl_add_u64 v[4:5], s[4:5], 0, v[8:9]
	global_store_dwordx4 v[4:5], v[0:3], off offset:256 nt
	s_or_b64 exec, exec, s[2:3]
	s_and_saveexec_b64 s[2:3], s[10:11]
	s_cbranch_execnz .LBB0_1340

.LBB0_1334:
	v_lshlrev_b64 v[0:1], 10, v[42:43]
	v_lshl_add_u64 v[0:1], v[0:1], 0, v[64:65]
	v_lshlrev_b64 v[8:9], 2, v[0:1]
	v_lshl_add_u64 v[0:1], s[16:17], 0, v[8:9]
	ds_read_b128 v[4:7], v114 offset:6528
	s_load_dwordx2 s[4:5], s[0:1], 0xb8
	s_waitcnt vmcnt(7) lgkmcnt(0)
	v_pk_add_f32 v[2:3], v[6:7], v[154:155]
	v_pk_add_f32 v[0:1], v[4:5], v[152:153]
	v_lshl_add_u64 v[4:5], s[4:5], 0, v[8:9]
	global_store_dwordx4 v[4:5], v[0:3], off offset:256 nt
	s_or_b64 exec, exec, s[2:3]
	s_and_saveexec_b64 s[2:3], s[14:15]
	s_cbranch_execz .LBB0_1274
	s_branch .LBB0_1342

.LBB0_1336:
	v_lshlrev_b64 v[0:1], 10, v[32:33]
	v_lshl_add_u64 v[0:1], v[0:1], 0, v[64:65]
	v_lshlrev_b64 v[8:9], 2, v[0:1]
	v_lshl_add_u64 v[0:1], s[16:17], 0, v[8:9]
	ds_read_b128 v[4:7], v114 offset:1088
	s_load_dwordx2 s[2:3], s[0:1], 0xb8
	s_waitcnt vmcnt(7) lgkmcnt(0)
	v_pk_add_f32 v[2:3], v[6:7], v[134:135]
	v_pk_add_f32 v[0:1], v[4:5], v[132:133]
	v_lshl_add_u64 v[4:5], s[2:3], 0, v[8:9]
	global_store_dwordx4 v[4:5], v[0:3], off offset:256 nt
	s_or_b64 exec, exec, s[24:25]
	s_and_saveexec_b64 s[2:3], s[4:5]
	s_cbranch_execnz .LBB0_1330

.LBB0_1338:
	v_lshlrev_b64 v[0:1], 10, v[36:37]
	v_lshl_add_u64 v[0:1], v[0:1], 0, v[64:65]
	v_lshlrev_b64 v[8:9], 2, v[0:1]
	v_lshl_add_u64 v[0:1], s[16:17], 0, v[8:9]
	ds_read_b128 v[4:7], v114 offset:3264
	s_load_dwordx2 s[4:5], s[0:1], 0xb8
	s_waitcnt vmcnt(7) lgkmcnt(0)
	v_pk_add_f32 v[2:3], v[6:7], v[142:143]
	v_pk_add_f32 v[0:1], v[4:5], v[140:141]
	v_lshl_add_u64 v[4:5], s[4:5], 0, v[8:9]
	global_store_dwordx4 v[4:5], v[0:3], off offset:256 nt
	s_or_b64 exec, exec, s[2:3]
	s_and_saveexec_b64 s[2:3], s[8:9]
	s_cbranch_execnz .LBB0_1332

.LBB0_1340:
	v_lshlrev_b64 v[0:1], 10, v[40:41]
	v_lshl_add_u64 v[0:1], v[0:1], 0, v[64:65]
	v_lshlrev_b64 v[8:9], 2, v[0:1]
	v_lshl_add_u64 v[0:1], s[16:17], 0, v[8:9]
	ds_read_b128 v[4:7], v114 offset:5440
	s_load_dwordx2 s[4:5], s[0:1], 0xb8
	s_waitcnt vmcnt(7) lgkmcnt(0)
	v_pk_add_f32 v[2:3], v[6:7], v[150:151]
	v_pk_add_f32 v[0:1], v[4:5], v[148:149]
	v_lshl_add_u64 v[4:5], s[4:5], 0, v[8:9]
	global_store_dwordx4 v[4:5], v[0:3], off offset:256 nt
	s_or_b64 exec, exec, s[2:3]
	s_and_saveexec_b64 s[2:3], s[12:13]
	s_cbranch_execnz .LBB0_1334

.LBB0_1342:
	v_lshlrev_b64 v[0:1], 10, v[44:45]
	v_lshl_add_u64 v[0:1], v[0:1], 0, v[64:65]
	v_lshlrev_b64 v[8:9], 2, v[0:1]
	v_lshl_add_u64 v[0:1], s[16:17], 0, v[8:9]
	ds_read_b128 v[4:7], v114 offset:7616
	s_load_dwordx2 s[4:5], s[0:1], 0xb8
	s_waitcnt vmcnt(7) lgkmcnt(0)
	v_pk_add_f32 v[2:3], v[6:7], v[158:159]
	v_pk_add_f32 v[0:1], v[4:5], v[156:157]
	v_lshl_add_u64 v[4:5], s[4:5], 0, v[8:9]
	global_store_dwordx4 v[4:5], v[0:3], off offset:256 nt
	s_branch .LBB0_1274

.LBB0_2223:
	ds_read_b128 v[128:131], v238
	ds_read_b128 v[136:139], v253
	ds_read_b128 v[132:135], v238 offset:4096
	ds_read_b128 v[140:143], v253 offset:4096
	ds_read_b128 v[144:147], v253 offset:8192
	ds_read_b128 v[148:151], v253 offset:12288
	s_waitcnt lgkmcnt(6)
	v_mfma_f32_32x32x16_bf16 v[112:127], v[188:191], v[196:199], v[112:127]
	v_mfma_f32_32x32x16_bf16 v[48:63], v[192:195], v[196:199], v[48:63]
	v_mfma_f32_32x32x16_bf16 v[96:111], v[188:191], v[200:203], v[96:111]
	v_mfma_f32_32x32x16_bf16 v[32:47], v[192:195], v[200:203], v[32:47]
	v_mfma_f32_32x32x16_bf16 v[80:95], v[188:191], v[204:207], v[80:95]
	v_mfma_f32_32x32x16_bf16 v[16:31], v[192:195], v[204:207], v[16:31]
	v_mfma_f32_32x32x16_bf16 v[64:79], v[188:191], v[226:229], v[64:79]
	v_mfma_f32_32x32x16_bf16 v[0:15], v[192:195], v[226:229], v[0:15]
	ds_read_b128 v[188:191], v239
	ds_read_b128 v[196:199], v254
	ds_read_b128 v[192:195], v239 offset:4096
	ds_read_b128 v[200:203], v254 offset:4096
	ds_read_b128 v[204:207], v254 offset:8192
	ds_read_b128 v[226:229], v254 offset:12288
	s_waitcnt lgkmcnt(6)
	v_mfma_f32_32x32x16_bf16 v[112:127], v[128:131], v[136:139], v[112:127]
	v_mfma_f32_32x32x16_bf16 v[48:63], v[132:135], v[136:139], v[48:63]
	v_mfma_f32_32x32x16_bf16 v[96:111], v[128:131], v[140:143], v[96:111]
	v_mfma_f32_32x32x16_bf16 v[32:47], v[132:135], v[140:143], v[32:47]
	v_mfma_f32_32x32x16_bf16 v[80:95], v[128:131], v[144:147], v[80:95]
	v_mfma_f32_32x32x16_bf16 v[16:31], v[132:135], v[144:147], v[16:31]
	v_mfma_f32_32x32x16_bf16 v[64:79], v[128:131], v[148:151], v[64:79]
	v_mfma_f32_32x32x16_bf16 v[0:15], v[132:135], v[148:151], v[0:15]
	ds_read_b128 v[128:131], v240
	ds_read_b128 v[136:139], v255
	ds_read_b128 v[132:135], v240 offset:4096
	ds_read_b128 v[140:143], v255 offset:4096
	ds_read_b128 v[144:147], v255 offset:8192
	ds_read_b128 v[148:151], v255 offset:12288
	s_waitcnt lgkmcnt(6)
	v_mfma_f32_32x32x16_bf16 v[112:127], v[188:191], v[196:199], v[112:127]
	v_mfma_f32_32x32x16_bf16 v[48:63], v[192:195], v[196:199], v[48:63]
	v_mfma_f32_32x32x16_bf16 v[96:111], v[188:191], v[200:203], v[96:111]
	v_mfma_f32_32x32x16_bf16 v[32:47], v[192:195], v[200:203], v[32:47]
	v_mfma_f32_32x32x16_bf16 v[80:95], v[188:191], v[204:207], v[80:95]
	v_mfma_f32_32x32x16_bf16 v[16:31], v[192:195], v[204:207], v[16:31]
	v_mfma_f32_32x32x16_bf16 v[64:79], v[188:191], v[226:229], v[64:79]
	v_mfma_f32_32x32x16_bf16 v[0:15], v[192:195], v[226:229], v[0:15]
	s_waitcnt vmcnt(0) lgkmcnt(0)
	s_barrier
	v_mfma_f32_32x32x16_bf16 v[112:127], v[128:131], v[136:139], v[112:127]
	v_mfma_f32_32x32x16_bf16 v[48:63], v[132:135], v[136:139], v[48:63]
	v_mfma_f32_32x32x16_bf16 v[96:111], v[128:131], v[140:143], v[96:111]
	v_mfma_f32_32x32x16_bf16 v[32:47], v[132:135], v[140:143], v[32:47]
	v_mfma_f32_32x32x16_bf16 v[80:95], v[128:131], v[144:147], v[80:95]
	v_mfma_f32_32x32x16_bf16 v[16:31], v[132:135], v[144:147], v[16:31]
	v_mfma_f32_32x32x16_bf16 v[64:79], v[128:131], v[148:151], v[64:79]
	v_mfma_f32_32x32x16_bf16 v[0:15], v[132:135], v[148:151], v[0:15]
	s_lshl_b32 s2, s5, 8
	s_sub_i32 s2, s2, s6
	v_mov_b32_e32 v168, v214
	s_add_i32 s55, s4, s30
	s_or_b32 s26, s2, s31
	s_ashr_i32 s27, s26, 31
	s_load_dwordx2 s[24:25], s[0:1], 0x140
	v_ashrrev_i32_e32 v180, 3, v168
	v_and_b32_e32 v183, -4, v180
	v_add_u32_e32 v225, s55, v183
	v_add_u32_e32 v190, 8, v225
	v_min_i32_e32 v190, 0x7fff, v190
	v_ashrrev_i32_e32 v190, 12, v190
	v_add_u32_e32 v190, 8, v190
	v_mul_hi_i32_i24_e32 v191, 0x3000, v190
	v_mul_i32_i24_e32 v190, 0x3000, v190
	v_min_i32_e32 v184, 0x7fff, v225
	v_ashrrev_i32_e32 v184, 12, v184
	v_and_b32_e32 v182, 31, v168
	v_add_u32_e32 v184, 8, v184
	v_or_b32_e32 v180, s26, v182
	v_mul_hi_i32_i24_e32 v185, 0x3000, v184
	v_mul_i32_i24_e32 v184, 0x3000, v184
	v_ashrrev_i32_e32 v181, 31, v180
	s_waitcnt lgkmcnt(0)
	v_lshl_add_u64 v[184:185], s[24:25], 0, v[184:185]
	v_lshl_add_u64 v[184:185], v[184:185], 0, s[18:19]
	v_lshlrev_b64 v[180:181], 2, v[180:181]
	v_lshl_add_u64 v[196:197], v[184:185], 0, v[180:181]
	v_lshl_add_u64 v[186:187], s[24:25], 0, v[190:191]
	v_add_u32_e32 v188, 9, v225
	v_add_u32_e32 v190, 10, v225
	v_min_i32_e32 v188, 0x7fff, v188
	v_min_i32_e32 v190, 0x7fff, v190
	v_ashrrev_i32_e32 v188, 12, v188
	v_ashrrev_i32_e32 v190, 12, v190
	v_add_u32_e32 v188, 8, v188
	v_add_u32_e32 v190, 8, v190
	v_mul_hi_i32_i24_e32 v189, 0x3000, v188
	v_mul_i32_i24_e32 v188, 0x3000, v188
	v_mul_hi_i32_i24_e32 v191, 0x3000, v190
	v_mul_i32_i24_e32 v190, 0x3000, v190
	v_lshl_add_u64 v[188:189], s[24:25], 0, v[188:189]
	v_lshl_add_u64 v[190:191], s[24:25], 0, v[190:191]
	v_lshl_add_u64 v[186:187], v[186:187], 0, s[18:19]
	v_lshl_add_u64 v[188:189], v[188:189], 0, s[18:19]
	v_lshl_add_u64 v[190:191], v[190:191], 0, s[18:19]
	v_lshl_add_u64 v[206:207], v[186:187], 0, v[180:181]
	v_add_u32_e32 v208, 18, v225
	v_min_i32_e32 v208, 0x7fff, v208
	v_ashrrev_i32_e32 v208, 12, v208
	v_add_u32_e32 v208, 8, v208
	v_mul_hi_i32_i24_e32 v209, 0x3000, v208
	v_mul_i32_i24_e32 v208, 0x3000, v208
	v_lshl_add_u64 v[208:209], s[24:25], 0, v[208:209]
	v_lshl_add_u64 v[202:203], v[188:189], 0, v[180:181]
	v_lshl_add_u64 v[204:205], v[190:191], 0, v[180:181]
	global_load_dword v232, v[196:197], off
	global_load_dword v233, v[196:197], off offset:128
	global_load_dword v242, v[206:207], off
	global_load_dword v243, v[206:207], off offset:128
	global_load_dword v244, v[202:203], off
	global_load_dword v245, v[202:203], off offset:128
	global_load_dword v246, v[204:205], off
	global_load_dword v247, v[204:205], off offset:128
	v_add_u32_e32 v196, 17, v225
	v_min_i32_e32 v196, 0x7fff, v196
	v_ashrrev_i32_e32 v196, 12, v196
	v_add_u32_e32 v196, 8, v196
	v_mul_hi_i32_i24_e32 v197, 0x3000, v196
	v_mul_i32_i24_e32 v196, 0x3000, v196
	v_lshl_add_u64 v[196:197], s[24:25], 0, v[196:197]
	v_lshl_add_u64 v[196:197], v[196:197], 0, s[18:19]
	v_lshl_add_u64 v[206:207], v[196:197], 0, v[180:181]
	s_waitcnt vmcnt(7)
	s_nop 5
	v_mul_f32_e32 v112, v112, v232
	v_add_u32_e32 v192, 11, v225
	v_add_u32_e32 v194, 16, v225
	v_min_i32_e32 v192, 0x7fff, v192
	v_min_i32_e32 v194, 0x7fff, v194
	v_ashrrev_i32_e32 v192, 12, v192
	v_ashrrev_i32_e32 v194, 12, v194
	v_add_u32_e32 v192, 8, v192
	v_add_u32_e32 v194, 8, v194
	v_mul_hi_i32_i24_e32 v193, 0x3000, v192
	v_mul_i32_i24_e32 v192, 0x3000, v192
	v_mul_hi_i32_i24_e32 v195, 0x3000, v194
	v_mul_i32_i24_e32 v194, 0x3000, v194
	v_lshl_add_u64 v[192:193], s[24:25], 0, v[192:193]
	v_lshl_add_u64 v[194:195], s[24:25], 0, v[194:195]
	v_lshl_add_u64 v[192:193], v[192:193], 0, s[18:19]
	v_lshl_add_u64 v[194:195], v[194:195], 0, s[18:19]
	v_lshl_add_u64 v[202:203], v[192:193], 0, v[180:181]
	v_lshl_add_u64 v[204:205], v[194:195], 0, v[180:181]
	s_waitcnt vmcnt(6)
	s_nop 5
	v_mul_f32_e32 v96, v96, v233
	v_mul_f32_e32 v97, v97, v233
	v_lshl_add_u64 v[198:199], v[208:209], 0, s[18:19]
	v_lshl_add_u64 v[200:201], v[198:199], 0, v[180:181]
	global_load_dword v234, v[202:203], off
	global_load_dword v235, v[202:203], off offset:128
	global_load_dword v236, v[204:205], off
	global_load_dword v237, v[204:205], off offset:128
	global_load_dword v238, v[206:207], off
	global_load_dword v239, v[206:207], off offset:128
	global_load_dword v240, v[200:201], off
	global_load_dword v241, v[200:201], off offset:128
	v_add_u32_e32 v200, 19, v225
	v_add_u32_e32 v204, 25, v225
	v_add_u32_e32 v206, 26, v225
	v_min_i32_e32 v200, 0x7fff, v200
	v_add_u32_e32 v202, 24, v225
	v_min_i32_e32 v204, 0x7fff, v204
	v_min_i32_e32 v206, 0x7fff, v206
	v_ashrrev_i32_e32 v200, 12, v200
	v_min_i32_e32 v202, 0x7fff, v202
	v_ashrrev_i32_e32 v204, 12, v204
	v_ashrrev_i32_e32 v206, 12, v206
	v_add_u32_e32 v200, 8, v200
	v_ashrrev_i32_e32 v202, 12, v202
	v_add_u32_e32 v204, 8, v204
	v_add_u32_e32 v206, 8, v206
	v_mul_hi_i32_i24_e32 v201, 0x3000, v200
	v_mul_i32_i24_e32 v200, 0x3000, v200
	v_add_u32_e32 v202, 8, v202
	v_mul_hi_i32_i24_e32 v205, 0x3000, v204
	v_mul_i32_i24_e32 v204, 0x3000, v204
	v_mul_hi_i32_i24_e32 v207, 0x3000, v206
	v_mul_i32_i24_e32 v206, 0x3000, v206
	v_lshl_add_u64 v[200:201], s[24:25], 0, v[200:201]
	v_mul_hi_i32_i24_e32 v203, 0x3000, v202
	v_mul_i32_i24_e32 v202, 0x3000, v202
	v_lshl_add_u64 v[204:205], s[24:25], 0, v[204:205]
	v_lshl_add_u64 v[206:207], s[24:25], 0, v[206:207]
	v_lshl_add_u64 v[200:201], v[200:201], 0, s[18:19]
	v_lshl_add_u64 v[202:203], s[24:25], 0, v[202:203]
	v_lshl_add_u64 v[204:205], v[204:205], 0, s[18:19]
	v_lshl_add_u64 v[206:207], v[206:207], 0, s[18:19]
	v_lshl_add_u64 v[208:209], v[200:201], 0, v[180:181]
	v_lshl_add_u64 v[202:203], v[202:203], 0, s[18:19]
	v_lshl_add_u64 v[228:229], v[204:205], 0, v[180:181]
	v_lshl_add_u64 v[230:231], v[206:207], 0, v[180:181]
	v_lshl_add_u64 v[226:227], v[202:203], 0, v[180:181]
	global_load_dword v248, v[208:209], off
	global_load_dword v249, v[208:209], off offset:128
	global_load_dword v250, v[226:227], off
	global_load_dword v251, v[226:227], off offset:128
	global_load_dword v252, v[228:229], off
	s_nop 0
	global_load_dword v228, v[228:229], off offset:128
	s_nop 0
	global_load_dword v229, v[230:231], off
	s_nop 0
	global_load_dword v230, v[230:231], off offset:128
	v_add_u32_e32 v208, 27, v225
	v_min_i32_e32 v208, 0x7fff, v208
	v_ashrrev_i32_e32 v208, 12, v208
	v_add_u32_e32 v208, 8, v208
	v_mul_hi_i32_i24_e32 v209, 0x3000, v208
	v_mul_i32_i24_e32 v208, 0x3000, v208
	v_lshl_add_u64 v[208:209], s[24:25], 0, v[208:209]
	v_lshl_add_u64 v[208:209], v[208:209], 0, s[18:19]
	v_lshl_add_u64 v[226:227], v[208:209], 0, v[180:181]
	global_load_dword v225, v[226:227], off
	s_nop 0
	global_load_dword v226, v[226:227], off offset:128
	v_mad_u64_u32 v[160:161], s[2:3], v183, s36, v[182:183]
	v_lshl_add_u32 v162, v160, 2, s34
	ds_write2_b32 v162, v112, v96 offset1:32
	v_mul_f32_e32 v96, v113, v232
	ds_write2_b32 v162, v96, v97 offset0:68 offset1:100
	v_mul_f32_e32 v96, v114, v232
	v_mul_f32_e32 v97, v98, v233
	ds_write2_b32 v162, v96, v97 offset0:136 offset1:168
	v_mul_f32_e32 v96, v115, v232
	v_mul_f32_e32 v97, v99, v233
	ds_write2_b32 v162, v96, v97 offset0:204 offset1:236
	s_waitcnt vmcnt(23)
	v_mul_f32_e32 v96, v116, v242
	s_waitcnt vmcnt(22)
	v_mul_f32_e32 v97, v100, v243
	v_add_u32_e32 v115, 0x800, v162
	ds_write2_b32 v115, v96, v97 offset0:32 offset1:64
	s_waitcnt vmcnt(21)
	v_mul_f32_e32 v96, v117, v244
	s_waitcnt vmcnt(20)
	v_mul_f32_e32 v97, v101, v245
	ds_write2_b32 v115, v96, v97 offset0:100 offset1:132
	s_waitcnt vmcnt(19)
	v_mul_f32_e32 v96, v118, v246
	s_waitcnt vmcnt(18)
	v_mul_f32_e32 v97, v102, v247
	ds_write2_b32 v115, v96, v97 offset0:168 offset1:200
	v_add_u32_e32 v116, 0xa00, v162
	v_add_u32_e32 v117, 0x1000, v162
	s_waitcnt vmcnt(17)
	v_mul_f32_e32 v96, v119, v234
	s_waitcnt vmcnt(16)
	v_mul_f32_e32 v97, v103, v235
	ds_write2_b32 v116, v96, v97 offset0:108 offset1:140
	s_waitcnt vmcnt(15)
	v_mul_f32_e32 v96, v120, v236
	s_waitcnt vmcnt(14)
	v_mul_f32_e32 v97, v104, v237
	ds_write2_b32 v117, v96, v97 offset0:64 offset1:96
	s_waitcnt vmcnt(13)
	v_mul_f32_e32 v96, v121, v238
	s_waitcnt vmcnt(12)
	v_mul_f32_e32 v97, v105, v239
	ds_write2_b32 v117, v96, v97 offset0:132 offset1:164
	s_waitcnt vmcnt(11)
	v_mul_f32_e32 v96, v122, v240
	s_waitcnt vmcnt(10)
	v_mul_f32_e32 v97, v106, v241
	ds_write2_b32 v117, v96, v97 offset0:200 offset1:232
	v_add_u32_e32 v118, 0x1400, v162
	v_add_u32_e32 v119, 0x1800, v162
	v_ashrrev_i32_e32 v163, 4, v168
	v_and_b32_e32 v160, 15, v168
	v_add_u32_e32 v120, 0x1a00, v162
	v_mul_lo_u32 v164, v163, s37
	v_lshl_add_u32 v165, v160, 4, s34
	v_lshlrev_b32_e32 v168, 2, v160
	v_add_u32_e32 v160, s55, v163
	v_add_u32_e32 v121, 0x1c00, v162
	v_cmp_gt_i32_e32 vcc, s38, v160
	v_ashrrev_i32_e32 v161, 31, v160
	v_add_u32_e32 v114, v165, v164
	s_waitcnt vmcnt(9)
	v_mul_f32_e32 v96, v123, v248
	s_waitcnt vmcnt(8)
	v_mul_f32_e32 v97, v107, v249
	ds_write2_b32 v118, v96, v97 offset0:12 offset1:44
	s_waitcnt vmcnt(7)
	v_mul_f32_e32 v96, v124, v250
	s_waitcnt vmcnt(6)
	v_mul_f32_e32 v97, v108, v251
	ds_write2_b32 v119, v96, v97 offset0:96 offset1:128
	s_waitcnt vmcnt(5)
	v_mul_f32_e32 v96, v125, v252
	s_waitcnt vmcnt(4)
	v_mul_f32_e32 v97, v109, v228
	ds_write2_b32 v119, v96, v97 offset0:164 offset1:196
	s_waitcnt vmcnt(3)
	v_mul_f32_e32 v96, v126, v229
	s_waitcnt vmcnt(2)
	v_mul_f32_e32 v97, v110, v230
	ds_write2_b32 v120, v96, v97 offset0:104 offset1:136
	s_waitcnt vmcnt(1)
	v_mul_f32_e32 v96, v127, v225
	s_waitcnt vmcnt(0)
	v_mul_f32_e32 v97, v111, v226
	ds_write2_b32 v121, v96, v97 offset0:44 offset1:76
	v_or_b32_e32 v96, s26, v168
	v_mov_b32_e32 v97, s27
	v_add_u32_e32 v128, 0, v160
	v_ashrrev_i32_e32 v129, 31, v128
	v_lshlrev_b64 v[128:129], 12, v[128:129]
	v_lshl_add_u64 v[128:129], s[16:17], 0, v[128:129]
	v_lshl_add_u64 v[128:129], v[96:97], 2, v[128:129]
	global_load_dwordx4 v[128:131], v[128:129], off nt
	v_add_u32_e32 v132, 4, v160
	v_ashrrev_i32_e32 v133, 31, v132
	v_lshlrev_b64 v[132:133], 12, v[132:133]
	v_lshl_add_u64 v[132:133], s[16:17], 0, v[132:133]
	v_lshl_add_u64 v[132:133], v[96:97], 2, v[132:133]
	global_load_dwordx4 v[132:135], v[132:133], off nt
	v_add_u32_e32 v136, 8, v160
	v_ashrrev_i32_e32 v137, 31, v136
	v_lshlrev_b64 v[136:137], 12, v[136:137]
	v_lshl_add_u64 v[136:137], s[16:17], 0, v[136:137]
	v_lshl_add_u64 v[136:137], v[96:97], 2, v[136:137]
	global_load_dwordx4 v[136:139], v[136:137], off nt
	v_add_u32_e32 v140, 12, v160
	v_ashrrev_i32_e32 v141, 31, v140
	v_lshlrev_b64 v[140:141], 12, v[140:141]
	v_lshl_add_u64 v[140:141], s[16:17], 0, v[140:141]
	v_lshl_add_u64 v[140:141], v[96:97], 2, v[140:141]
	global_load_dwordx4 v[140:143], v[140:141], off nt
	v_add_u32_e32 v144, 16, v160
	v_ashrrev_i32_e32 v145, 31, v144
	v_lshlrev_b64 v[144:145], 12, v[144:145]
	v_lshl_add_u64 v[144:145], s[16:17], 0, v[144:145]
	v_lshl_add_u64 v[144:145], v[96:97], 2, v[144:145]
	global_load_dwordx4 v[144:147], v[144:145], off nt
	v_add_u32_e32 v148, 20, v160
	v_ashrrev_i32_e32 v149, 31, v148
	v_lshlrev_b64 v[148:149], 12, v[148:149]
	v_lshl_add_u64 v[148:149], s[16:17], 0, v[148:149]
	v_lshl_add_u64 v[148:149], v[96:97], 2, v[148:149]
	global_load_dwordx4 v[148:151], v[148:149], off nt
	v_add_u32_e32 v152, 24, v160
	v_ashrrev_i32_e32 v153, 31, v152
	v_lshlrev_b64 v[152:153], 12, v[152:153]
	v_lshl_add_u64 v[152:153], s[16:17], 0, v[152:153]
	v_lshl_add_u64 v[152:153], v[96:97], 2, v[152:153]
	global_load_dwordx4 v[152:155], v[152:153], off nt
	v_add_u32_e32 v156, 28, v160
	v_ashrrev_i32_e32 v157, 31, v156
	v_lshlrev_b64 v[156:157], 12, v[156:157]
	v_lshl_add_u64 v[156:157], s[16:17], 0, v[156:157]
	v_lshl_add_u64 v[156:157], v[96:97], 2, v[156:157]
	global_load_dwordx4 v[156:159], v[156:157], off nt
	s_and_saveexec_b64 s[2:3], vcc
	s_cbranch_execz .LBB0_2225
	v_lshlrev_b64 v[98:99], 12, v[160:161]
	v_lshl_add_u64 v[98:99], s[16:17], 0, v[98:99]
	v_lshl_add_u64 v[106:107], v[96:97], 2, v[98:99]
	ds_read_b128 v[102:105], v114
	s_waitcnt vmcnt(7) lgkmcnt(0)
	v_pk_add_f32 v[100:101], v[104:105], v[130:131]
	v_pk_add_f32 v[98:99], v[102:103], v[128:129]
	global_store_dwordx4 v[106:107], v[98:101], off nt
.LBB0_2225:
	s_or_b64 exec, exec, s[2:3]
	s_nop 0
	v_add_u32_e32 v100, 4, v160
	v_cmp_gt_i32_e64 s[2:3], s39, v160
	v_ashrrev_i32_e32 v101, 31, v100
	s_and_saveexec_b64 s[4:5], s[2:3]
	s_cbranch_execz .LBB0_2227
	v_lshlrev_b64 v[98:99], 12, v[100:101]
	v_lshl_add_u64 v[98:99], s[16:17], 0, v[98:99]
	v_lshl_add_u64 v[98:99], v[96:97], 2, v[98:99]
	ds_read_b128 v[106:109], v114 offset:1088
	s_waitcnt vmcnt(7) lgkmcnt(0)
	v_pk_add_f32 v[104:105], v[108:109], v[134:135]
	v_pk_add_f32 v[102:103], v[106:107], v[132:133]
	global_store_dwordx4 v[98:99], v[102:105], off nt
.LBB0_2227:
	s_or_b64 exec, exec, s[4:5]
	s_nop 0
	v_add_u32_e32 v102, 8, v160
	v_cmp_gt_i32_e64 s[4:5], s48, v160
	v_ashrrev_i32_e32 v103, 31, v102
	s_and_saveexec_b64 s[6:7], s[4:5]
	s_cbranch_execz .LBB0_2229
	v_lshlrev_b64 v[98:99], 12, v[102:103]
	v_lshl_add_u64 v[98:99], s[16:17], 0, v[98:99]
	v_lshl_add_u64 v[98:99], v[96:97], 2, v[98:99]
	ds_read_b128 v[108:111], v114 offset:2176
	s_waitcnt vmcnt(7) lgkmcnt(0)
	v_pk_add_f32 v[106:107], v[110:111], v[138:139]
	v_pk_add_f32 v[104:105], v[108:109], v[136:137]
	global_store_dwordx4 v[98:99], v[104:107], off nt
.LBB0_2229:
	s_or_b64 exec, exec, s[6:7]
	s_nop 0
	v_add_u32_e32 v104, 12, v160
	v_cmp_gt_i32_e64 s[6:7], s49, v160
	v_ashrrev_i32_e32 v105, 31, v104
	s_and_saveexec_b64 s[8:9], s[6:7]
	s_cbranch_execz .LBB0_2231
	v_lshlrev_b64 v[98:99], 12, v[104:105]
	v_lshl_add_u64 v[98:99], s[16:17], 0, v[98:99]
	v_lshl_add_u64 v[98:99], v[96:97], 2, v[98:99]
	ds_read_b128 v[110:113], v114 offset:3264
	s_waitcnt vmcnt(7) lgkmcnt(0)
	v_pk_add_f32 v[108:109], v[112:113], v[142:143]
	v_pk_add_f32 v[106:107], v[110:111], v[140:141]
	global_store_dwordx4 v[98:99], v[106:109], off nt
.LBB0_2231:
	s_or_b64 exec, exec, s[8:9]
	s_nop 0
	v_add_u32_e32 v106, 16, v160
	v_cmp_gt_i32_e64 s[8:9], s50, v160
	v_ashrrev_i32_e32 v107, 31, v106
	s_and_saveexec_b64 s[10:11], s[8:9]
	s_cbranch_execz .LBB0_2233
	v_lshlrev_b64 v[98:99], 12, v[106:107]
	v_lshl_add_u64 v[98:99], s[16:17], 0, v[98:99]
	v_lshl_add_u64 v[98:99], v[96:97], 2, v[98:99]
	ds_read_b128 v[122:125], v114 offset:4352
	s_waitcnt vmcnt(7) lgkmcnt(0)
	v_pk_add_f32 v[110:111], v[124:125], v[146:147]
	v_pk_add_f32 v[108:109], v[122:123], v[144:145]
	global_store_dwordx4 v[98:99], v[108:111], off nt
.LBB0_2233:
	s_or_b64 exec, exec, s[10:11]
	s_nop 0
	v_add_u32_e32 v108, 20, v160
	v_cmp_gt_i32_e64 s[10:11], s51, v160
	v_ashrrev_i32_e32 v109, 31, v108
	s_and_saveexec_b64 s[12:13], s[10:11]
	s_cbranch_execz .LBB0_2235
	v_lshlrev_b64 v[98:99], 12, v[108:109]
	v_lshl_add_u64 v[98:99], s[16:17], 0, v[98:99]
	v_lshl_add_u64 v[98:99], v[96:97], 2, v[98:99]
	ds_read_b128 v[122:125], v114 offset:5440
	s_waitcnt vmcnt(7) lgkmcnt(0)
	v_pk_add_f32 v[112:113], v[124:125], v[150:151]
	v_pk_add_f32 v[110:111], v[122:123], v[148:149]
	global_store_dwordx4 v[98:99], v[110:113], off nt
.LBB0_2235:
	s_or_b64 exec, exec, s[12:13]
	s_nop 0
	v_add_u32_e32 v110, 24, v160
	v_cmp_gt_i32_e64 s[12:13], s52, v160
	v_ashrrev_i32_e32 v111, 31, v110
	s_and_saveexec_b64 s[14:15], s[12:13]
	s_cbranch_execz .LBB0_2237
	v_lshlrev_b64 v[98:99], 12, v[110:111]
	v_lshl_add_u64 v[98:99], s[16:17], 0, v[98:99]
	v_lshl_add_u64 v[98:99], v[96:97], 2, v[98:99]
	ds_read_b128 v[164:167], v114 offset:6528
	s_waitcnt vmcnt(7) lgkmcnt(0)
	v_pk_add_f32 v[124:125], v[166:167], v[154:155]
	v_pk_add_f32 v[122:123], v[164:165], v[152:153]
	global_store_dwordx4 v[98:99], v[122:125], off nt
.LBB0_2237:
	s_or_b64 exec, exec, s[14:15]
	v_add_u32_e32 v112, 28, v160
	v_cmp_gt_i32_e64 s[14:15], s53, v160
	v_ashrrev_i32_e32 v113, 31, v112
	s_and_saveexec_b64 s[28:29], s[14:15]
	s_cbranch_execz .LBB0_2239
	v_lshlrev_b64 v[98:99], 12, v[112:113]
	v_lshl_add_u64 v[98:99], s[16:17], 0, v[98:99]
	v_lshl_add_u64 v[98:99], v[96:97], 2, v[98:99]
	ds_read_b128 v[164:167], v114 offset:7616
	s_waitcnt vmcnt(7) lgkmcnt(0)
	v_pk_add_f32 v[124:125], v[166:167], v[158:159]
	v_pk_add_f32 v[122:123], v[164:165], v[156:157]
	global_store_dwordx4 v[98:99], v[122:125], off nt
.LBB0_2239:
	s_or_b64 exec, exec, s[28:29]
	v_add3_u32 v98, v182, s26, 64
	v_ashrrev_i32_e32 v99, 31, v98
	v_lshlrev_b64 v[98:99], 2, v[98:99]
	v_lshl_add_u64 v[122:123], v[184:185], 0, v[98:99]
	v_lshl_add_u64 v[124:125], v[186:187], 0, v[98:99]
	v_lshl_add_u64 v[126:127], v[188:189], 0, v[98:99]
	v_lshl_add_u64 v[164:165], v[190:191], 0, v[98:99]
	global_load_dword v166, v[122:123], off
	global_load_dword v167, v[122:123], off offset:128
	global_load_dword v182, v[124:125], off
	global_load_dword v184, v[124:125], off offset:128
	global_load_dword v185, v[126:127], off
	global_load_dword v186, v[126:127], off offset:128
	global_load_dword v187, v[164:165], off
	global_load_dword v188, v[164:165], off offset:128
	v_lshl_add_u64 v[122:123], v[192:193], 0, v[98:99]
	v_lshl_add_u64 v[124:125], v[194:195], 0, v[98:99]
	v_lshl_add_u64 v[126:127], v[196:197], 0, v[98:99]
	v_lshl_add_u64 v[164:165], v[198:199], 0, v[98:99]
	global_load_dword v189, v[122:123], off
	global_load_dword v190, v[122:123], off offset:128
	global_load_dword v191, v[124:125], off
	global_load_dword v192, v[124:125], off offset:128
	global_load_dword v193, v[126:127], off
	global_load_dword v194, v[126:127], off offset:128
	global_load_dword v195, v[164:165], off
	global_load_dword v196, v[164:165], off offset:128
	v_lshl_add_u64 v[122:123], v[200:201], 0, v[98:99]
	v_lshl_add_u64 v[124:125], v[202:203], 0, v[98:99]
	v_lshl_add_u64 v[126:127], v[204:205], 0, v[98:99]
	v_lshl_add_u64 v[164:165], v[206:207], 0, v[98:99]
	global_load_dword v197, v[122:123], off
	global_load_dword v198, v[122:123], off offset:128
	global_load_dword v199, v[124:125], off
	s_nop 0
	global_load_dword v124, v[124:125], off offset:128
	s_nop 0
	global_load_dword v125, v[126:127], off
	s_nop 0
	global_load_dword v126, v[126:127], off offset:128
	s_nop 0
	global_load_dword v127, v[164:165], off
	s_nop 0
	global_load_dword v164, v[164:165], off offset:128
	v_lshl_add_u64 v[122:123], v[208:209], 0, v[98:99]
	global_load_dword v165, v[122:123], off
	s_nop 0
	global_load_dword v122, v[122:123], off offset:128
	s_waitcnt vmcnt(25)
	v_mul_f32_e32 v80, v80, v166
	s_waitcnt vmcnt(24)
	v_mul_f32_e32 v64, v64, v167
	v_mul_f32_e32 v65, v65, v167
	v_mul_f32_e32 v81, v81, v166
	v_mul_f32_e32 v82, v82, v166
	v_mul_f32_e32 v66, v66, v167
	v_mul_f32_e32 v83, v83, v166
	v_mul_f32_e32 v67, v67, v167
	s_waitcnt vmcnt(23)
	v_mul_f32_e32 v84, v84, v182
	s_waitcnt vmcnt(22)
	v_mul_f32_e32 v68, v68, v184
	s_waitcnt vmcnt(21)
	v_mul_f32_e32 v85, v85, v185
	s_waitcnt vmcnt(20)
	v_mul_f32_e32 v69, v69, v186
	s_waitcnt vmcnt(19)
	v_mul_f32_e32 v86, v86, v187
	s_waitcnt vmcnt(18)
	v_mul_f32_e32 v70, v70, v188
	s_waitcnt vmcnt(17)
	v_mul_f32_e32 v87, v87, v189
	s_waitcnt vmcnt(16)
	v_mul_f32_e32 v71, v71, v190
	s_waitcnt vmcnt(15)
	v_mul_f32_e32 v88, v88, v191
	s_waitcnt vmcnt(14)
	v_mul_f32_e32 v72, v72, v192
	s_waitcnt vmcnt(13)
	v_mul_f32_e32 v89, v89, v193
	s_waitcnt vmcnt(12)
	v_mul_f32_e32 v73, v73, v194
	s_waitcnt vmcnt(11)
	v_mul_f32_e32 v90, v90, v195
	s_waitcnt vmcnt(10)
	v_mul_f32_e32 v74, v74, v196
	s_waitcnt vmcnt(9)
	v_mul_f32_e32 v91, v91, v197
	s_waitcnt vmcnt(8)
	v_mul_f32_e32 v75, v75, v198
	s_waitcnt vmcnt(7)
	v_mul_f32_e32 v92, v92, v199
	s_waitcnt vmcnt(6)
	v_mul_f32_e32 v76, v76, v124
	s_waitcnt vmcnt(5)
	v_mul_f32_e32 v93, v93, v125
	s_waitcnt vmcnt(4)
	v_mul_f32_e32 v77, v77, v126
	s_waitcnt vmcnt(3)
	v_mul_f32_e32 v94, v94, v127
	s_waitcnt vmcnt(2)
	v_mul_f32_e32 v78, v78, v164
	ds_write2_b32 v162, v80, v64 offset1:32
	ds_write2_b32 v162, v81, v65 offset0:68 offset1:100
	ds_write2_b32 v162, v82, v66 offset0:136 offset1:168
	ds_write2_b32 v162, v83, v67 offset0:204 offset1:236
	ds_write2_b32 v115, v84, v68 offset0:32 offset1:64
	ds_write2_b32 v115, v85, v69 offset0:100 offset1:132
	ds_write2_b32 v115, v86, v70 offset0:168 offset1:200
	ds_write2_b32 v116, v87, v71 offset0:108 offset1:140
	ds_write2_b32 v117, v88, v72 offset0:64 offset1:96
	ds_write2_b32 v117, v89, v73 offset0:132 offset1:164
	ds_write2_b32 v117, v90, v74 offset0:200 offset1:232
	ds_write2_b32 v118, v91, v75 offset0:12 offset1:44
	ds_write2_b32 v119, v92, v76 offset0:96 offset1:128
	ds_write2_b32 v119, v93, v77 offset0:164 offset1:196
	ds_write2_b32 v120, v94, v78 offset0:104 offset1:136
	s_waitcnt vmcnt(1)
	v_mul_f32_e32 v64, v95, v165
	s_waitcnt vmcnt(0)
	v_mul_f32_e32 v65, v79, v122
	ds_write2_b32 v121, v64, v65 offset0:44 offset1:76
	v_lshl_add_u64 v[64:65], v[168:169], 0, s[26:27]
	v_add_u32_e32 v128, 0, v160
	v_ashrrev_i32_e32 v129, 31, v128
	v_lshlrev_b64 v[128:129], 12, v[128:129]
	v_lshl_add_u64 v[128:129], s[16:17], 0, v[128:129]
	v_lshl_add_u64 v[128:129], v[64:65], 2, v[128:129]
	global_load_dwordx4 v[128:131], v[128:129], off offset:256 nt
	v_add_u32_e32 v132, 4, v160
	v_ashrrev_i32_e32 v133, 31, v132
	v_lshlrev_b64 v[132:133], 12, v[132:133]
	v_lshl_add_u64 v[132:133], s[16:17], 0, v[132:133]
	v_lshl_add_u64 v[132:133], v[64:65], 2, v[132:133]
	global_load_dwordx4 v[132:135], v[132:133], off offset:256 nt
	v_add_u32_e32 v136, 8, v160
	v_ashrrev_i32_e32 v137, 31, v136
	v_lshlrev_b64 v[136:137], 12, v[136:137]
	v_lshl_add_u64 v[136:137], s[16:17], 0, v[136:137]
	v_lshl_add_u64 v[136:137], v[64:65], 2, v[136:137]
	global_load_dwordx4 v[136:139], v[136:137], off offset:256 nt
	v_add_u32_e32 v140, 12, v160
	v_ashrrev_i32_e32 v141, 31, v140
	v_lshlrev_b64 v[140:141], 12, v[140:141]
	v_lshl_add_u64 v[140:141], s[16:17], 0, v[140:141]
	v_lshl_add_u64 v[140:141], v[64:65], 2, v[140:141]
	global_load_dwordx4 v[140:143], v[140:141], off offset:256 nt
	v_add_u32_e32 v144, 16, v160
	v_ashrrev_i32_e32 v145, 31, v144
	v_lshlrev_b64 v[144:145], 12, v[144:145]
	v_lshl_add_u64 v[144:145], s[16:17], 0, v[144:145]
	v_lshl_add_u64 v[144:145], v[64:65], 2, v[144:145]
	global_load_dwordx4 v[144:147], v[144:145], off offset:256 nt
	v_add_u32_e32 v148, 20, v160
	v_ashrrev_i32_e32 v149, 31, v148
	v_lshlrev_b64 v[148:149], 12, v[148:149]
	v_lshl_add_u64 v[148:149], s[16:17], 0, v[148:149]
	v_lshl_add_u64 v[148:149], v[64:65], 2, v[148:149]
	global_load_dwordx4 v[148:151], v[148:149], off offset:256 nt
	v_add_u32_e32 v152, 24, v160
	v_ashrrev_i32_e32 v153, 31, v152
	v_lshlrev_b64 v[152:153], 12, v[152:153]
	v_lshl_add_u64 v[152:153], s[16:17], 0, v[152:153]
	v_lshl_add_u64 v[152:153], v[64:65], 2, v[152:153]
	global_load_dwordx4 v[152:155], v[152:153], off offset:256 nt
	v_add_u32_e32 v156, 28, v160
	v_ashrrev_i32_e32 v157, 31, v156
	v_lshlrev_b64 v[156:157], 12, v[156:157]
	v_lshl_add_u64 v[156:157], s[16:17], 0, v[156:157]
	v_lshl_add_u64 v[156:157], v[64:65], 2, v[156:157]
	global_load_dwordx4 v[156:159], v[156:157], off offset:256 nt
	s_and_saveexec_b64 s[26:27], vcc
	s_cbranch_execz .LBB0_2247
	v_lshlrev_b64 v[66:67], 12, v[160:161]
	v_lshl_add_u64 v[66:67], s[16:17], 0, v[66:67]
	v_lshl_add_u64 v[74:75], v[64:65], 2, v[66:67]
	ds_read_b128 v[70:73], v114
	s_waitcnt vmcnt(7) lgkmcnt(0)
	v_pk_add_f32 v[68:69], v[72:73], v[130:131]
	v_pk_add_f32 v[66:67], v[70:71], v[128:129]
	global_store_dwordx4 v[74:75], v[66:69], off offset:256 nt
	s_or_b64 exec, exec, s[26:27]
	s_and_saveexec_b64 s[26:27], s[2:3]
	s_cbranch_execnz .LBB0_2248

.LBB0_2242:
	v_lshlrev_b64 v[66:67], 12, v[102:103]
	v_lshl_add_u64 v[66:67], s[16:17], 0, v[66:67]
	v_lshl_add_u64 v[74:75], v[64:65], 2, v[66:67]
	ds_read_b128 v[70:73], v114 offset:2176
	s_waitcnt vmcnt(7) lgkmcnt(0)
	v_pk_add_f32 v[68:69], v[72:73], v[138:139]
	v_pk_add_f32 v[66:67], v[70:71], v[136:137]
	global_store_dwordx4 v[74:75], v[66:69], off offset:256 nt
	s_or_b64 exec, exec, s[2:3]
	s_and_saveexec_b64 s[2:3], s[6:7]
	s_cbranch_execnz .LBB0_2250

.LBB0_2244:
	v_lshlrev_b64 v[66:67], 12, v[106:107]
	v_lshl_add_u64 v[66:67], s[16:17], 0, v[66:67]
	v_lshl_add_u64 v[74:75], v[64:65], 2, v[66:67]
	ds_read_b128 v[70:73], v114 offset:4352
	s_waitcnt vmcnt(7) lgkmcnt(0)
	v_pk_add_f32 v[68:69], v[72:73], v[146:147]
	v_pk_add_f32 v[66:67], v[70:71], v[144:145]
	global_store_dwordx4 v[74:75], v[66:69], off offset:256 nt
	s_or_b64 exec, exec, s[2:3]
	s_and_saveexec_b64 s[2:3], s[10:11]
	s_cbranch_execnz .LBB0_2252

.LBB0_2246:
	v_lshlrev_b64 v[66:67], 12, v[110:111]
	v_lshl_add_u64 v[66:67], s[16:17], 0, v[66:67]
	v_lshl_add_u64 v[74:75], v[64:65], 2, v[66:67]
	ds_read_b128 v[70:73], v114 offset:6528
	s_waitcnt vmcnt(7) lgkmcnt(0)
	v_pk_add_f32 v[68:69], v[72:73], v[154:155]
	v_pk_add_f32 v[66:67], v[70:71], v[152:153]
	global_store_dwordx4 v[74:75], v[66:69], off offset:256 nt
	s_or_b64 exec, exec, s[2:3]
	s_and_saveexec_b64 s[2:3], s[14:15]
	s_cbranch_execnz .LBB0_2254
	s_branch .LBB0_2255

.LBB0_2248:
	v_lshlrev_b64 v[66:67], 12, v[100:101]
	v_lshl_add_u64 v[66:67], s[16:17], 0, v[66:67]
	v_lshl_add_u64 v[74:75], v[64:65], 2, v[66:67]
	ds_read_b128 v[70:73], v114 offset:1088
	s_waitcnt vmcnt(7) lgkmcnt(0)
	v_pk_add_f32 v[68:69], v[72:73], v[134:135]
	v_pk_add_f32 v[66:67], v[70:71], v[132:133]
	global_store_dwordx4 v[74:75], v[66:69], off offset:256 nt
	s_or_b64 exec, exec, s[26:27]
	s_and_saveexec_b64 s[2:3], s[4:5]
	s_cbranch_execnz .LBB0_2242

.LBB0_2250:
	v_lshlrev_b64 v[66:67], 12, v[104:105]
	v_lshl_add_u64 v[66:67], s[16:17], 0, v[66:67]
	v_lshl_add_u64 v[74:75], v[64:65], 2, v[66:67]
	ds_read_b128 v[70:73], v114 offset:3264
	s_waitcnt vmcnt(7) lgkmcnt(0)
	v_pk_add_f32 v[68:69], v[72:73], v[142:143]
	v_pk_add_f32 v[66:67], v[70:71], v[140:141]
	global_store_dwordx4 v[74:75], v[66:69], off offset:256 nt
	s_or_b64 exec, exec, s[2:3]
	s_and_saveexec_b64 s[2:3], s[8:9]
	s_cbranch_execnz .LBB0_2244

.LBB0_2252:
	v_lshlrev_b64 v[66:67], 12, v[108:109]
	v_lshl_add_u64 v[66:67], s[16:17], 0, v[66:67]
	v_lshl_add_u64 v[74:75], v[64:65], 2, v[66:67]
	ds_read_b128 v[70:73], v114 offset:5440
	s_waitcnt vmcnt(7) lgkmcnt(0)
	v_pk_add_f32 v[68:69], v[72:73], v[150:151]
	v_pk_add_f32 v[66:67], v[70:71], v[148:149]
	global_store_dwordx4 v[74:75], v[66:69], off offset:256 nt
	s_or_b64 exec, exec, s[2:3]
	s_and_saveexec_b64 s[2:3], s[12:13]
	s_cbranch_execnz .LBB0_2246

.LBB0_2254:
	v_lshlrev_b64 v[66:67], 12, v[112:113]
	v_lshl_add_u64 v[66:67], s[16:17], 0, v[66:67]
	v_lshl_add_u64 v[74:75], v[64:65], 2, v[66:67]
	ds_read_b128 v[70:73], v114 offset:7616
	s_waitcnt vmcnt(7) lgkmcnt(0)
	v_pk_add_f32 v[68:69], v[72:73], v[158:159]
	v_pk_add_f32 v[66:67], v[70:71], v[156:157]
	global_store_dwordx4 v[74:75], v[66:69], off offset:256 nt
.LBB0_2255:
	s_or_b64 exec, exec, s[2:3]
	s_or_b32 s2, s55, 32
	v_add_u32_e32 v102, s2, v183
	v_min_i32_e32 v66, 0x7fff, v102
	v_add_u32_e32 v68, 8, v102
	v_add_u32_e32 v70, 9, v102
	v_add_u32_e32 v72, 10, v102
	v_ashrrev_i32_e32 v66, 12, v66
	v_min_i32_e32 v68, 0x7fff, v68
	v_min_i32_e32 v70, 0x7fff, v70
	v_min_i32_e32 v72, 0x7fff, v72
	v_add_u32_e32 v66, 8, v66
	v_ashrrev_i32_e32 v68, 12, v68
	v_ashrrev_i32_e32 v70, 12, v70
	v_ashrrev_i32_e32 v72, 12, v72
	v_mul_hi_i32_i24_e32 v67, 0x3000, v66
	v_mul_i32_i24_e32 v66, 0x3000, v66
	v_add_u32_e32 v68, 8, v68
	v_add_u32_e32 v70, 8, v70
	v_add_u32_e32 v72, 8, v72
	v_lshl_add_u64 v[66:67], s[24:25], 0, v[66:67]
	v_mul_hi_i32_i24_e32 v69, 0x3000, v68
	v_mul_i32_i24_e32 v68, 0x3000, v68
	v_mul_hi_i32_i24_e32 v71, 0x3000, v70
	v_mul_i32_i24_e32 v70, 0x3000, v70
	v_mul_hi_i32_i24_e32 v73, 0x3000, v72
	v_mul_i32_i24_e32 v72, 0x3000, v72
	v_lshl_add_u64 v[66:67], v[66:67], 0, s[18:19]
	v_lshl_add_u64 v[68:69], s[24:25], 0, v[68:69]
	v_lshl_add_u64 v[70:71], s[24:25], 0, v[70:71]
	v_lshl_add_u64 v[72:73], s[24:25], 0, v[72:73]
	v_lshl_add_u64 v[74:75], v[66:67], 0, v[180:181]
	v_lshl_add_u64 v[68:69], v[68:69], 0, s[18:19]
	v_lshl_add_u64 v[70:71], v[70:71], 0, s[18:19]
	v_lshl_add_u64 v[72:73], v[72:73], 0, s[18:19]
	v_lshl_add_u64 v[76:77], v[68:69], 0, v[180:181]
	v_lshl_add_u64 v[78:79], v[70:71], 0, v[180:181]
	v_lshl_add_u64 v[80:81], v[72:73], 0, v[180:181]
	global_load_dword v103, v[74:75], off
	global_load_dword v104, v[74:75], off offset:128
	global_load_dword v105, v[76:77], off
	global_load_dword v106, v[76:77], off offset:128
	global_load_dword v107, v[78:79], off
	global_load_dword v108, v[78:79], off offset:128
	global_load_dword v109, v[80:81], off
	global_load_dword v110, v[80:81], off offset:128
	v_add_u32_e32 v74, 11, v102
	v_add_u32_e32 v82, 18, v102
	v_min_i32_e32 v74, 0x7fff, v74
	v_add_u32_e32 v76, 16, v102
	v_add_u32_e32 v78, 17, v102
	v_min_i32_e32 v82, 0x7fff, v82
	v_ashrrev_i32_e32 v74, 12, v74
	v_min_i32_e32 v76, 0x7fff, v76
	v_min_i32_e32 v78, 0x7fff, v78
	v_ashrrev_i32_e32 v82, 12, v82
	v_add_u32_e32 v74, 8, v74
	v_ashrrev_i32_e32 v76, 12, v76
	v_ashrrev_i32_e32 v78, 12, v78
	v_add_u32_e32 v82, 8, v82
	v_mul_hi_i32_i24_e32 v75, 0x3000, v74
	v_mul_i32_i24_e32 v74, 0x3000, v74
	v_add_u32_e32 v76, 8, v76
	v_add_u32_e32 v78, 8, v78
	v_mul_hi_i32_i24_e32 v83, 0x3000, v82
	v_mul_i32_i24_e32 v82, 0x3000, v82
	v_lshl_add_u64 v[74:75], s[24:25], 0, v[74:75]
	v_mul_hi_i32_i24_e32 v77, 0x3000, v76
	v_mul_i32_i24_e32 v76, 0x3000, v76
	v_mul_hi_i32_i24_e32 v79, 0x3000, v78
	v_mul_i32_i24_e32 v78, 0x3000, v78
	v_lshl_add_u64 v[82:83], s[24:25], 0, v[82:83]
	v_lshl_add_u64 v[74:75], v[74:75], 0, s[18:19]
	v_lshl_add_u64 v[76:77], s[24:25], 0, v[76:77]
	v_lshl_add_u64 v[78:79], s[24:25], 0, v[78:79]
	v_lshl_add_u64 v[82:83], v[82:83], 0, s[18:19]
	v_lshl_add_u64 v[80:81], v[74:75], 0, v[180:181]
	v_lshl_add_u64 v[76:77], v[76:77], 0, s[18:19]
	v_lshl_add_u64 v[78:79], v[78:79], 0, s[18:19]
	v_lshl_add_u64 v[88:89], v[82:83], 0, v[180:181]
	v_lshl_add_u64 v[84:85], v[76:77], 0, v[180:181]
	v_lshl_add_u64 v[86:87], v[78:79], 0, v[180:181]
	global_load_dword v111, v[80:81], off
	global_load_dword v112, v[80:81], off offset:128
	global_load_dword v113, v[84:85], off
	global_load_dword v122, v[84:85], off offset:128
	global_load_dword v123, v[86:87], off
	global_load_dword v124, v[86:87], off offset:128
	global_load_dword v125, v[88:89], off
	global_load_dword v126, v[88:89], off offset:128
	v_add_u32_e32 v80, 19, v102
	v_add_u32_e32 v88, 25, v102
	v_add_u32_e32 v90, 26, v102
	v_min_i32_e32 v80, 0x7fff, v80
	v_add_u32_e32 v86, 24, v102
	v_min_i32_e32 v88, 0x7fff, v88
	v_min_i32_e32 v90, 0x7fff, v90
	v_ashrrev_i32_e32 v80, 12, v80
	v_min_i32_e32 v86, 0x7fff, v86
	v_ashrrev_i32_e32 v88, 12, v88
	v_ashrrev_i32_e32 v90, 12, v90
	v_add_u32_e32 v80, 8, v80
	v_ashrrev_i32_e32 v86, 12, v86
	v_add_u32_e32 v88, 8, v88
	v_add_u32_e32 v90, 8, v90
	v_mul_hi_i32_i24_e32 v81, 0x3000, v80
	v_mul_i32_i24_e32 v80, 0x3000, v80
	v_add_u32_e32 v86, 8, v86
	v_mul_hi_i32_i24_e32 v89, 0x3000, v88
	v_mul_i32_i24_e32 v88, 0x3000, v88
	v_mul_hi_i32_i24_e32 v91, 0x3000, v90
	v_mul_i32_i24_e32 v90, 0x3000, v90
	v_lshl_add_u64 v[80:81], s[24:25], 0, v[80:81]
	v_mul_hi_i32_i24_e32 v87, 0x3000, v86
	v_mul_i32_i24_e32 v86, 0x3000, v86
	v_lshl_add_u64 v[88:89], s[24:25], 0, v[88:89]
	v_lshl_add_u64 v[90:91], s[24:25], 0, v[90:91]
	v_lshl_add_u64 v[84:85], v[80:81], 0, s[18:19]
	v_lshl_add_u64 v[86:87], s[24:25], 0, v[86:87]
	v_lshl_add_u64 v[88:89], v[88:89], 0, s[18:19]
	v_lshl_add_u64 v[90:91], v[90:91], 0, s[18:19]
	v_lshl_add_u64 v[80:81], v[84:85], 0, v[180:181]
	v_lshl_add_u64 v[86:87], v[86:87], 0, s[18:19]
	v_lshl_add_u64 v[94:95], v[88:89], 0, v[180:181]
	v_lshl_add_u64 v[100:101], v[90:91], 0, v[180:181]
	v_lshl_add_u64 v[92:93], v[86:87], 0, v[180:181]
	global_load_dword v127, v[80:81], off
	global_load_dword v160, v[80:81], off offset:128
	global_load_dword v161, v[92:93], off
	global_load_dword v164, v[92:93], off offset:128
	global_load_dword v165, v[94:95], off
	s_nop 0
	global_load_dword v94, v[94:95], off offset:128
	s_nop 0
	global_load_dword v95, v[100:101], off
	s_nop 0
	global_load_dword v100, v[100:101], off offset:128
	v_add_u32_e32 v80, 27, v102
	v_min_i32_e32 v80, 0x7fff, v80
	v_ashrrev_i32_e32 v80, 12, v80
	v_add_u32_e32 v80, 8, v80
	v_mul_hi_i32_i24_e32 v81, 0x3000, v80
	v_mul_i32_i24_e32 v80, 0x3000, v80
	v_lshl_add_u64 v[80:81], s[24:25], 0, v[80:81]
	v_lshl_add_u64 v[92:93], v[80:81], 0, s[18:19]
	v_lshl_add_u64 v[80:81], v[92:93], 0, v[180:181]
	global_load_dword v101, v[80:81], off
	s_nop 0
	global_load_dword v81, v[80:81], off offset:128
	s_waitcnt vmcnt(25)
	v_mul_f32_e32 v48, v48, v103
	s_waitcnt vmcnt(24)
	v_mul_f32_e32 v32, v32, v104
	ds_write2_b32 v162, v48, v32 offset1:32
	v_mul_f32_e32 v32, v49, v103
	v_mul_f32_e32 v33, v33, v104
	ds_write2_b32 v162, v32, v33 offset0:68 offset1:100
	v_mul_f32_e32 v32, v50, v103
	v_mul_f32_e32 v33, v34, v104
	ds_write2_b32 v162, v32, v33 offset0:136 offset1:168
	v_mul_f32_e32 v32, v51, v103
	v_mul_f32_e32 v33, v35, v104
	ds_write2_b32 v162, v32, v33 offset0:204 offset1:236
	s_waitcnt vmcnt(23)
	v_mul_f32_e32 v32, v52, v105
	s_waitcnt vmcnt(22)
	v_mul_f32_e32 v33, v36, v106
	ds_write2_b32 v115, v32, v33 offset0:32 offset1:64
	s_waitcnt vmcnt(21)
	v_mul_f32_e32 v32, v53, v107
	s_waitcnt vmcnt(20)
	v_mul_f32_e32 v33, v37, v108
	ds_write2_b32 v115, v32, v33 offset0:100 offset1:132
	s_waitcnt vmcnt(19)
	v_mul_f32_e32 v32, v54, v109
	s_waitcnt vmcnt(18)
	v_mul_f32_e32 v33, v38, v110
	ds_write2_b32 v115, v32, v33 offset0:168 offset1:200
	v_add_u32_e32 v80, s2, v163
	v_cmp_gt_i32_e32 vcc, s38, v80
	s_waitcnt vmcnt(17)
	v_mul_f32_e32 v32, v55, v111
	s_waitcnt vmcnt(16)
	v_mul_f32_e32 v33, v39, v112
	ds_write2_b32 v116, v32, v33 offset0:108 offset1:140
	s_waitcnt vmcnt(15)
	v_mul_f32_e32 v32, v56, v113
	s_waitcnt vmcnt(14)
	v_mul_f32_e32 v33, v40, v122
	ds_write2_b32 v117, v32, v33 offset0:64 offset1:96
	s_waitcnt vmcnt(13)
	v_mul_f32_e32 v32, v57, v123
	s_waitcnt vmcnt(12)
	v_mul_f32_e32 v33, v41, v124
	ds_write2_b32 v117, v32, v33 offset0:132 offset1:164
	s_waitcnt vmcnt(11)
	v_mul_f32_e32 v32, v58, v125
	s_waitcnt vmcnt(10)
	v_mul_f32_e32 v33, v42, v126
	ds_write2_b32 v117, v32, v33 offset0:200 offset1:232
	s_waitcnt vmcnt(9)
	v_mul_f32_e32 v32, v59, v127
	s_waitcnt vmcnt(8)
	v_mul_f32_e32 v33, v43, v160
	ds_write2_b32 v118, v32, v33 offset0:12 offset1:44
	s_waitcnt vmcnt(7)
	v_mul_f32_e32 v32, v60, v161
	s_waitcnt vmcnt(6)
	v_mul_f32_e32 v33, v44, v164
	ds_write2_b32 v119, v32, v33 offset0:96 offset1:128
	s_waitcnt vmcnt(5)
	v_mul_f32_e32 v32, v61, v165
	s_waitcnt vmcnt(4)
	v_mul_f32_e32 v33, v45, v94
	ds_write2_b32 v119, v32, v33 offset0:164 offset1:196
	s_waitcnt vmcnt(3)
	v_mul_f32_e32 v32, v62, v95
	s_waitcnt vmcnt(2)
	v_mul_f32_e32 v33, v46, v100
	ds_write2_b32 v120, v32, v33 offset0:104 offset1:136
	s_waitcnt vmcnt(1)
	v_mul_f32_e32 v32, v63, v101
	s_waitcnt vmcnt(0)
	v_mul_f32_e32 v33, v47, v81
	v_ashrrev_i32_e32 v81, 31, v80
	ds_write2_b32 v121, v32, v33 offset0:44 offset1:76
	v_add_u32_e32 v128, 0, v80
	v_ashrrev_i32_e32 v129, 31, v128
	v_lshlrev_b64 v[128:129], 12, v[128:129]
	v_lshl_add_u64 v[128:129], s[16:17], 0, v[128:129]
	v_lshl_add_u64 v[128:129], v[96:97], 2, v[128:129]
	global_load_dwordx4 v[128:131], v[128:129], off nt
	v_add_u32_e32 v132, 4, v80
	v_ashrrev_i32_e32 v133, 31, v132
	v_lshlrev_b64 v[132:133], 12, v[132:133]
	v_lshl_add_u64 v[132:133], s[16:17], 0, v[132:133]
	v_lshl_add_u64 v[132:133], v[96:97], 2, v[132:133]
	global_load_dwordx4 v[132:135], v[132:133], off nt
	v_add_u32_e32 v136, 8, v80
	v_ashrrev_i32_e32 v137, 31, v136
	v_lshlrev_b64 v[136:137], 12, v[136:137]
	v_lshl_add_u64 v[136:137], s[16:17], 0, v[136:137]
	v_lshl_add_u64 v[136:137], v[96:97], 2, v[136:137]
	global_load_dwordx4 v[136:139], v[136:137], off nt
	v_add_u32_e32 v140, 12, v80
	v_ashrrev_i32_e32 v141, 31, v140
	v_lshlrev_b64 v[140:141], 12, v[140:141]
	v_lshl_add_u64 v[140:141], s[16:17], 0, v[140:141]
	v_lshl_add_u64 v[140:141], v[96:97], 2, v[140:141]
	global_load_dwordx4 v[140:143], v[140:141], off nt
	v_add_u32_e32 v144, 16, v80
	v_ashrrev_i32_e32 v145, 31, v144
	v_lshlrev_b64 v[144:145], 12, v[144:145]
	v_lshl_add_u64 v[144:145], s[16:17], 0, v[144:145]
	v_lshl_add_u64 v[144:145], v[96:97], 2, v[144:145]
	global_load_dwordx4 v[144:147], v[144:145], off nt
	v_add_u32_e32 v148, 20, v80
	v_ashrrev_i32_e32 v149, 31, v148
	v_lshlrev_b64 v[148:149], 12, v[148:149]
	v_lshl_add_u64 v[148:149], s[16:17], 0, v[148:149]
	v_lshl_add_u64 v[148:149], v[96:97], 2, v[148:149]
	global_load_dwordx4 v[148:151], v[148:149], off nt
	v_add_u32_e32 v152, 24, v80
	v_ashrrev_i32_e32 v153, 31, v152
	v_lshlrev_b64 v[152:153], 12, v[152:153]
	v_lshl_add_u64 v[152:153], s[16:17], 0, v[152:153]
	v_lshl_add_u64 v[152:153], v[96:97], 2, v[152:153]
	global_load_dwordx4 v[152:155], v[152:153], off nt
	v_add_u32_e32 v156, 28, v80
	v_ashrrev_i32_e32 v157, 31, v156
	v_lshlrev_b64 v[156:157], 12, v[156:157]
	v_lshl_add_u64 v[156:157], s[16:17], 0, v[156:157]
	v_lshl_add_u64 v[156:157], v[96:97], 2, v[156:157]
	global_load_dwordx4 v[156:159], v[156:157], off nt
	s_and_saveexec_b64 s[2:3], vcc
	s_cbranch_execz .LBB0_2257
	v_lshlrev_b64 v[32:33], 12, v[80:81]
	v_lshl_add_u64 v[32:33], s[16:17], 0, v[32:33]
	v_lshl_add_u64 v[40:41], v[96:97], 2, v[32:33]
	ds_read_b128 v[36:39], v114
	s_waitcnt vmcnt(7) lgkmcnt(0)
	v_pk_add_f32 v[34:35], v[38:39], v[130:131]
	v_pk_add_f32 v[32:33], v[36:37], v[128:129]
	global_store_dwordx4 v[40:41], v[32:35], off nt
.LBB0_2257:
	s_or_b64 exec, exec, s[2:3]
	s_nop 0
	v_add_u32_e32 v32, 4, v80
	v_cmp_gt_i32_e64 s[2:3], s39, v80
	v_ashrrev_i32_e32 v33, 31, v32
	s_and_saveexec_b64 s[4:5], s[2:3]
	s_cbranch_execz .LBB0_2259
	v_lshlrev_b64 v[34:35], 12, v[32:33]
	v_lshl_add_u64 v[34:35], s[16:17], 0, v[34:35]
	v_lshl_add_u64 v[42:43], v[96:97], 2, v[34:35]
	ds_read_b128 v[38:41], v114 offset:1088
	s_waitcnt vmcnt(7) lgkmcnt(0)
	v_pk_add_f32 v[36:37], v[40:41], v[134:135]
	v_pk_add_f32 v[34:35], v[38:39], v[132:133]
	global_store_dwordx4 v[42:43], v[34:37], off nt
.LBB0_2259:
	s_or_b64 exec, exec, s[4:5]
	s_nop 0
	v_add_u32_e32 v34, 8, v80
	v_cmp_gt_i32_e64 s[4:5], s48, v80
	v_ashrrev_i32_e32 v35, 31, v34
	s_and_saveexec_b64 s[6:7], s[4:5]
	s_cbranch_execz .LBB0_2261
	v_lshlrev_b64 v[36:37], 12, v[34:35]
	v_lshl_add_u64 v[36:37], s[16:17], 0, v[36:37]
	v_lshl_add_u64 v[44:45], v[96:97], 2, v[36:37]
	ds_read_b128 v[40:43], v114 offset:2176
	s_waitcnt vmcnt(7) lgkmcnt(0)
	v_pk_add_f32 v[38:39], v[42:43], v[138:139]
	v_pk_add_f32 v[36:37], v[40:41], v[136:137]
	global_store_dwordx4 v[44:45], v[36:39], off nt
.LBB0_2261:
	s_or_b64 exec, exec, s[6:7]
	s_nop 0
	v_add_u32_e32 v36, 12, v80
	v_cmp_gt_i32_e64 s[6:7], s49, v80
	v_ashrrev_i32_e32 v37, 31, v36
	s_and_saveexec_b64 s[8:9], s[6:7]
	s_cbranch_execz .LBB0_2263
	v_lshlrev_b64 v[38:39], 12, v[36:37]
	v_lshl_add_u64 v[38:39], s[16:17], 0, v[38:39]
	v_lshl_add_u64 v[46:47], v[96:97], 2, v[38:39]
	ds_read_b128 v[42:45], v114 offset:3264
	s_waitcnt vmcnt(7) lgkmcnt(0)
	v_pk_add_f32 v[40:41], v[44:45], v[142:143]
	v_pk_add_f32 v[38:39], v[42:43], v[140:141]
	global_store_dwordx4 v[46:47], v[38:41], off nt
.LBB0_2263:
	s_or_b64 exec, exec, s[8:9]
	s_nop 0
	v_add_u32_e32 v38, 16, v80
	v_cmp_gt_i32_e64 s[8:9], s50, v80
	v_ashrrev_i32_e32 v39, 31, v38
	s_and_saveexec_b64 s[10:11], s[8:9]
	s_cbranch_execz .LBB0_2265
	v_lshlrev_b64 v[40:41], 12, v[38:39]
	v_lshl_add_u64 v[40:41], s[16:17], 0, v[40:41]
	v_lshl_add_u64 v[48:49], v[96:97], 2, v[40:41]
	ds_read_b128 v[44:47], v114 offset:4352
	s_waitcnt vmcnt(7) lgkmcnt(0)
	v_pk_add_f32 v[42:43], v[46:47], v[146:147]
	v_pk_add_f32 v[40:41], v[44:45], v[144:145]
	global_store_dwordx4 v[48:49], v[40:43], off nt
.LBB0_2265:
	s_or_b64 exec, exec, s[10:11]
	s_nop 0
	v_add_u32_e32 v40, 20, v80
	v_cmp_gt_i32_e64 s[10:11], s51, v80
	v_ashrrev_i32_e32 v41, 31, v40
	s_and_saveexec_b64 s[12:13], s[10:11]
	s_cbranch_execz .LBB0_2267
	v_lshlrev_b64 v[42:43], 12, v[40:41]
	v_lshl_add_u64 v[42:43], s[16:17], 0, v[42:43]
	v_lshl_add_u64 v[50:51], v[96:97], 2, v[42:43]
	ds_read_b128 v[46:49], v114 offset:5440
	s_waitcnt vmcnt(7) lgkmcnt(0)
	v_pk_add_f32 v[44:45], v[48:49], v[150:151]
	v_pk_add_f32 v[42:43], v[46:47], v[148:149]
	global_store_dwordx4 v[50:51], v[42:45], off nt
.LBB0_2267:
	s_or_b64 exec, exec, s[12:13]
	s_nop 0
	v_add_u32_e32 v42, 24, v80
	v_cmp_gt_i32_e64 s[12:13], s52, v80
	v_ashrrev_i32_e32 v43, 31, v42
	s_and_saveexec_b64 s[14:15], s[12:13]
	s_cbranch_execz .LBB0_2269
	v_lshlrev_b64 v[44:45], 12, v[42:43]
	v_lshl_add_u64 v[44:45], s[16:17], 0, v[44:45]
	v_lshl_add_u64 v[52:53], v[96:97], 2, v[44:45]
	ds_read_b128 v[48:51], v114 offset:6528
	s_waitcnt vmcnt(7) lgkmcnt(0)
	v_pk_add_f32 v[46:47], v[50:51], v[154:155]
	v_pk_add_f32 v[44:45], v[48:49], v[152:153]
	global_store_dwordx4 v[52:53], v[44:47], off nt
.LBB0_2269:
	s_or_b64 exec, exec, s[14:15]
	s_nop 0
	v_add_u32_e32 v44, 28, v80
	v_cmp_gt_i32_e64 s[14:15], s53, v80
	v_ashrrev_i32_e32 v45, 31, v44
	s_and_saveexec_b64 s[24:25], s[14:15]
	s_cbranch_execz .LBB0_2271
	v_lshlrev_b64 v[46:47], 12, v[44:45]
	v_lshl_add_u64 v[46:47], s[16:17], 0, v[46:47]
	v_lshl_add_u64 v[54:55], v[96:97], 2, v[46:47]
	ds_read_b128 v[50:53], v114 offset:7616
	s_waitcnt vmcnt(7) lgkmcnt(0)
	v_pk_add_f32 v[48:49], v[52:53], v[158:159]
	v_pk_add_f32 v[46:47], v[50:51], v[156:157]
	global_store_dwordx4 v[54:55], v[46:49], off nt
.LBB0_2271:
	s_or_b64 exec, exec, s[24:25]
	s_nop 0
	v_lshl_add_u64 v[46:47], v[66:67], 0, v[98:99]
	v_lshl_add_u64 v[48:49], v[68:69], 0, v[98:99]
	v_lshl_add_u64 v[50:51], v[70:71], 0, v[98:99]
	v_lshl_add_u64 v[52:53], v[72:73], 0, v[98:99]
	global_load_dword v54, v[46:47], off
	global_load_dword v55, v[46:47], off offset:128
	global_load_dword v56, v[48:49], off
	global_load_dword v57, v[48:49], off offset:128
	global_load_dword v58, v[50:51], off
	global_load_dword v59, v[50:51], off offset:128
	global_load_dword v60, v[52:53], off
	global_load_dword v61, v[52:53], off offset:128
	v_lshl_add_u64 v[46:47], v[74:75], 0, v[98:99]
	v_lshl_add_u64 v[48:49], v[76:77], 0, v[98:99]
	v_lshl_add_u64 v[50:51], v[78:79], 0, v[98:99]
	v_lshl_add_u64 v[52:53], v[82:83], 0, v[98:99]
	global_load_dword v62, v[46:47], off
	global_load_dword v63, v[46:47], off offset:128
	global_load_dword v66, v[48:49], off
	global_load_dword v67, v[48:49], off offset:128
	global_load_dword v68, v[50:51], off
	global_load_dword v69, v[50:51], off offset:128
	global_load_dword v70, v[52:53], off
	global_load_dword v71, v[52:53], off offset:128
	v_lshl_add_u64 v[46:47], v[84:85], 0, v[98:99]
	v_lshl_add_u64 v[48:49], v[86:87], 0, v[98:99]
	v_lshl_add_u64 v[50:51], v[88:89], 0, v[98:99]
	v_lshl_add_u64 v[52:53], v[90:91], 0, v[98:99]
	global_load_dword v72, v[46:47], off
	global_load_dword v73, v[46:47], off offset:128
	global_load_dword v74, v[48:49], off
	s_nop 0
	global_load_dword v48, v[48:49], off offset:128
	s_nop 0
	global_load_dword v49, v[50:51], off
	s_nop 0
	global_load_dword v50, v[50:51], off offset:128
	s_nop 0
	global_load_dword v51, v[52:53], off
	s_nop 0
	global_load_dword v52, v[52:53], off offset:128
	v_lshl_add_u64 v[46:47], v[92:93], 0, v[98:99]
	global_load_dword v53, v[46:47], off
	s_nop 0
	global_load_dword v46, v[46:47], off offset:128
	s_waitcnt vmcnt(25)
	v_mul_f32_e32 v16, v16, v54
	s_waitcnt vmcnt(24)
	v_mul_f32_e32 v0, v0, v55
	v_mul_f32_e32 v1, v1, v55
	v_mul_f32_e32 v17, v17, v54
	v_mul_f32_e32 v18, v18, v54
	v_mul_f32_e32 v2, v2, v55
	v_mul_f32_e32 v19, v19, v54
	v_mul_f32_e32 v3, v3, v55
	s_waitcnt vmcnt(23)
	v_mul_f32_e32 v20, v20, v56
	s_waitcnt vmcnt(22)
	v_mul_f32_e32 v4, v4, v57
	s_waitcnt vmcnt(21)
	v_mul_f32_e32 v21, v21, v58
	s_waitcnt vmcnt(20)
	v_mul_f32_e32 v5, v5, v59
	s_waitcnt vmcnt(19)
	v_mul_f32_e32 v22, v22, v60
	s_waitcnt vmcnt(18)
	v_mul_f32_e32 v6, v6, v61
	s_waitcnt vmcnt(17)
	v_mul_f32_e32 v23, v23, v62
	s_waitcnt vmcnt(16)
	v_mul_f32_e32 v7, v7, v63
	s_waitcnt vmcnt(15)
	v_mul_f32_e32 v24, v24, v66
	s_waitcnt vmcnt(14)
	v_mul_f32_e32 v8, v8, v67
	s_waitcnt vmcnt(13)
	v_mul_f32_e32 v25, v25, v68
	s_waitcnt vmcnt(12)
	v_mul_f32_e32 v9, v9, v69
	s_waitcnt vmcnt(11)
	v_mul_f32_e32 v26, v26, v70
	s_waitcnt vmcnt(10)
	v_mul_f32_e32 v10, v10, v71
	s_waitcnt vmcnt(9)
	v_mul_f32_e32 v27, v27, v72
	s_waitcnt vmcnt(8)
	v_mul_f32_e32 v11, v11, v73
	s_waitcnt vmcnt(7)
	v_mul_f32_e32 v28, v28, v74
	s_waitcnt vmcnt(6)
	v_mul_f32_e32 v12, v12, v48
	s_waitcnt vmcnt(5)
	v_mul_f32_e32 v29, v29, v49
	s_waitcnt vmcnt(4)
	v_mul_f32_e32 v13, v13, v50
	s_waitcnt vmcnt(3)
	v_mul_f32_e32 v30, v30, v51
	s_waitcnt vmcnt(2)
	v_mul_f32_e32 v14, v14, v52
	ds_write2_b32 v162, v16, v0 offset1:32
	ds_write2_b32 v162, v17, v1 offset0:68 offset1:100
	ds_write2_b32 v162, v18, v2 offset0:136 offset1:168
	ds_write2_b32 v162, v19, v3 offset0:204 offset1:236
	ds_write2_b32 v115, v20, v4 offset0:32 offset1:64
	ds_write2_b32 v115, v21, v5 offset0:100 offset1:132
	ds_write2_b32 v115, v22, v6 offset0:168 offset1:200
	ds_write2_b32 v116, v23, v7 offset0:108 offset1:140
	ds_write2_b32 v117, v24, v8 offset0:64 offset1:96
	ds_write2_b32 v117, v25, v9 offset0:132 offset1:164
	ds_write2_b32 v117, v26, v10 offset0:200 offset1:232
	ds_write2_b32 v118, v27, v11 offset0:12 offset1:44
	ds_write2_b32 v119, v28, v12 offset0:96 offset1:128
	ds_write2_b32 v119, v29, v13 offset0:164 offset1:196
	ds_write2_b32 v120, v30, v14 offset0:104 offset1:136
	s_waitcnt vmcnt(1)
	v_mul_f32_e32 v0, v31, v53
	s_waitcnt vmcnt(0)
	v_mul_f32_e32 v1, v15, v46
	ds_write2_b32 v121, v0, v1 offset0:44 offset1:76
	v_add_u32_e32 v128, 0, v80
	v_ashrrev_i32_e32 v129, 31, v128
	v_lshlrev_b64 v[128:129], 12, v[128:129]
	v_lshl_add_u64 v[128:129], s[16:17], 0, v[128:129]
	v_lshl_add_u64 v[128:129], v[64:65], 2, v[128:129]
	global_load_dwordx4 v[128:131], v[128:129], off offset:256 nt
	v_add_u32_e32 v132, 4, v80
	v_ashrrev_i32_e32 v133, 31, v132
	v_lshlrev_b64 v[132:133], 12, v[132:133]
	v_lshl_add_u64 v[132:133], s[16:17], 0, v[132:133]
	v_lshl_add_u64 v[132:133], v[64:65], 2, v[132:133]
	global_load_dwordx4 v[132:135], v[132:133], off offset:256 nt
	v_add_u32_e32 v136, 8, v80
	v_ashrrev_i32_e32 v137, 31, v136
	v_lshlrev_b64 v[136:137], 12, v[136:137]
	v_lshl_add_u64 v[136:137], s[16:17], 0, v[136:137]
	v_lshl_add_u64 v[136:137], v[64:65], 2, v[136:137]
	global_load_dwordx4 v[136:139], v[136:137], off offset:256 nt
	v_add_u32_e32 v140, 12, v80
	v_ashrrev_i32_e32 v141, 31, v140
	v_lshlrev_b64 v[140:141], 12, v[140:141]
	v_lshl_add_u64 v[140:141], s[16:17], 0, v[140:141]
	v_lshl_add_u64 v[140:141], v[64:65], 2, v[140:141]
	global_load_dwordx4 v[140:143], v[140:141], off offset:256 nt
	v_add_u32_e32 v144, 16, v80
	v_ashrrev_i32_e32 v145, 31, v144
	v_lshlrev_b64 v[144:145], 12, v[144:145]
	v_lshl_add_u64 v[144:145], s[16:17], 0, v[144:145]
	v_lshl_add_u64 v[144:145], v[64:65], 2, v[144:145]
	global_load_dwordx4 v[144:147], v[144:145], off offset:256 nt
	v_add_u32_e32 v148, 20, v80
	v_ashrrev_i32_e32 v149, 31, v148
	v_lshlrev_b64 v[148:149], 12, v[148:149]
	v_lshl_add_u64 v[148:149], s[16:17], 0, v[148:149]
	v_lshl_add_u64 v[148:149], v[64:65], 2, v[148:149]
	global_load_dwordx4 v[148:151], v[148:149], off offset:256 nt
	v_add_u32_e32 v152, 24, v80
	v_ashrrev_i32_e32 v153, 31, v152
	v_lshlrev_b64 v[152:153], 12, v[152:153]
	v_lshl_add_u64 v[152:153], s[16:17], 0, v[152:153]
	v_lshl_add_u64 v[152:153], v[64:65], 2, v[152:153]
	global_load_dwordx4 v[152:155], v[152:153], off offset:256 nt
	v_add_u32_e32 v156, 28, v80
	v_ashrrev_i32_e32 v157, 31, v156
	v_lshlrev_b64 v[156:157], 12, v[156:157]
	v_lshl_add_u64 v[156:157], s[16:17], 0, v[156:157]
	v_lshl_add_u64 v[156:157], v[64:65], 2, v[156:157]
	global_load_dwordx4 v[156:159], v[156:157], off offset:256 nt
	s_and_saveexec_b64 s[24:25], vcc
	s_cbranch_execz .LBB0_2279
	v_lshlrev_b64 v[0:1], 12, v[80:81]
	v_lshl_add_u64 v[0:1], s[16:17], 0, v[0:1]
	v_lshl_add_u64 v[8:9], v[64:65], 2, v[0:1]
	ds_read_b128 v[4:7], v114
	s_waitcnt vmcnt(7) lgkmcnt(0)
	v_pk_add_f32 v[2:3], v[6:7], v[130:131]
	v_pk_add_f32 v[0:1], v[4:5], v[128:129]
	global_store_dwordx4 v[8:9], v[0:3], off offset:256 nt
	s_or_b64 exec, exec, s[24:25]
	s_and_saveexec_b64 s[24:25], s[2:3]
	s_cbranch_execnz .LBB0_2280

.LBB0_2274:
	v_lshlrev_b64 v[0:1], 12, v[34:35]
	v_lshl_add_u64 v[0:1], s[16:17], 0, v[0:1]
	v_lshl_add_u64 v[8:9], v[64:65], 2, v[0:1]
	ds_read_b128 v[4:7], v114 offset:2176
	s_waitcnt vmcnt(7) lgkmcnt(0)
	v_pk_add_f32 v[2:3], v[6:7], v[138:139]
	v_pk_add_f32 v[0:1], v[4:5], v[136:137]
	global_store_dwordx4 v[8:9], v[0:3], off offset:256 nt
	s_or_b64 exec, exec, s[2:3]
	s_and_saveexec_b64 s[2:3], s[6:7]
	s_cbranch_execnz .LBB0_2282

.LBB0_2276:
	v_lshlrev_b64 v[0:1], 12, v[38:39]
	v_lshl_add_u64 v[0:1], s[16:17], 0, v[0:1]
	v_lshl_add_u64 v[8:9], v[64:65], 2, v[0:1]
	ds_read_b128 v[4:7], v114 offset:4352
	s_waitcnt vmcnt(7) lgkmcnt(0)
	v_pk_add_f32 v[2:3], v[6:7], v[146:147]
	v_pk_add_f32 v[0:1], v[4:5], v[144:145]
	global_store_dwordx4 v[8:9], v[0:3], off offset:256 nt
	s_or_b64 exec, exec, s[2:3]
	s_and_saveexec_b64 s[2:3], s[10:11]
	s_cbranch_execnz .LBB0_2284

.LBB0_2278:
	v_lshlrev_b64 v[0:1], 12, v[42:43]
	v_lshl_add_u64 v[0:1], s[16:17], 0, v[0:1]
	v_lshl_add_u64 v[8:9], v[64:65], 2, v[0:1]
	ds_read_b128 v[4:7], v114 offset:6528
	s_waitcnt vmcnt(7) lgkmcnt(0)
	v_pk_add_f32 v[2:3], v[6:7], v[154:155]
	v_pk_add_f32 v[0:1], v[4:5], v[152:153]
	global_store_dwordx4 v[8:9], v[0:3], off offset:256 nt
	s_or_b64 exec, exec, s[2:3]
	s_and_saveexec_b64 s[2:3], s[14:15]
	s_cbranch_execz .LBB0_2218
	s_branch .LBB0_2286

.LBB0_2280:
	v_lshlrev_b64 v[0:1], 12, v[32:33]
	v_lshl_add_u64 v[0:1], s[16:17], 0, v[0:1]
	v_lshl_add_u64 v[8:9], v[64:65], 2, v[0:1]
	ds_read_b128 v[4:7], v114 offset:1088
	s_waitcnt vmcnt(7) lgkmcnt(0)
	v_pk_add_f32 v[2:3], v[6:7], v[134:135]
	v_pk_add_f32 v[0:1], v[4:5], v[132:133]
	global_store_dwordx4 v[8:9], v[0:3], off offset:256 nt
	s_or_b64 exec, exec, s[24:25]
	s_and_saveexec_b64 s[2:3], s[4:5]
	s_cbranch_execnz .LBB0_2274

.LBB0_2282:
	v_lshlrev_b64 v[0:1], 12, v[36:37]
	v_lshl_add_u64 v[0:1], s[16:17], 0, v[0:1]
	v_lshl_add_u64 v[8:9], v[64:65], 2, v[0:1]
	ds_read_b128 v[4:7], v114 offset:3264
	s_waitcnt vmcnt(7) lgkmcnt(0)
	v_pk_add_f32 v[2:3], v[6:7], v[142:143]
	v_pk_add_f32 v[0:1], v[4:5], v[140:141]
	global_store_dwordx4 v[8:9], v[0:3], off offset:256 nt
	s_or_b64 exec, exec, s[2:3]
	s_and_saveexec_b64 s[2:3], s[8:9]
	s_cbranch_execnz .LBB0_2276

.LBB0_2284:
	v_lshlrev_b64 v[0:1], 12, v[40:41]
	v_lshl_add_u64 v[0:1], s[16:17], 0, v[0:1]
	v_lshl_add_u64 v[8:9], v[64:65], 2, v[0:1]
	ds_read_b128 v[4:7], v114 offset:5440
	s_waitcnt vmcnt(7) lgkmcnt(0)
	v_pk_add_f32 v[2:3], v[6:7], v[150:151]
	v_pk_add_f32 v[0:1], v[4:5], v[148:149]
	global_store_dwordx4 v[8:9], v[0:3], off offset:256 nt
	s_or_b64 exec, exec, s[2:3]
	s_and_saveexec_b64 s[2:3], s[12:13]
	s_cbranch_execnz .LBB0_2278

.LBB0_2286:
	v_lshlrev_b64 v[0:1], 12, v[44:45]
	v_lshl_add_u64 v[0:1], s[16:17], 0, v[0:1]
	v_lshl_add_u64 v[8:9], v[64:65], 2, v[0:1]
	ds_read_b128 v[4:7], v114 offset:7616
	s_waitcnt vmcnt(7) lgkmcnt(0)
	v_pk_add_f32 v[2:3], v[6:7], v[158:159]
	v_pk_add_f32 v[0:1], v[4:5], v[156:157]
	global_store_dwordx4 v[8:9], v[0:3], off offset:256 nt
	s_branch .LBB0_2218

.LBB0_4482:
	ds_read_b128 v[128:131], v238
	ds_read_b128 v[136:139], v253
	ds_read_b128 v[132:135], v238 offset:4096
	ds_read_b128 v[140:143], v253 offset:4096
	ds_read_b128 v[144:147], v253 offset:8192
	ds_read_b128 v[148:151], v253 offset:12288
	s_waitcnt lgkmcnt(6)
	v_mfma_f32_32x32x16_bf16 v[112:127], v[188:191], v[196:199], v[112:127]
	v_mfma_f32_32x32x16_bf16 v[48:63], v[192:195], v[196:199], v[48:63]
	v_mfma_f32_32x32x16_bf16 v[96:111], v[188:191], v[200:203], v[96:111]
	v_mfma_f32_32x32x16_bf16 v[32:47], v[192:195], v[200:203], v[32:47]
	v_mfma_f32_32x32x16_bf16 v[80:95], v[188:191], v[204:207], v[80:95]
	v_mfma_f32_32x32x16_bf16 v[16:31], v[192:195], v[204:207], v[16:31]
	v_mfma_f32_32x32x16_bf16 v[64:79], v[188:191], v[226:229], v[64:79]
	v_mfma_f32_32x32x16_bf16 v[0:15], v[192:195], v[226:229], v[0:15]
	ds_read_b128 v[188:191], v239
	ds_read_b128 v[196:199], v254
	ds_read_b128 v[192:195], v239 offset:4096
	ds_read_b128 v[200:203], v254 offset:4096
	ds_read_b128 v[204:207], v254 offset:8192
	ds_read_b128 v[226:229], v254 offset:12288
	s_waitcnt lgkmcnt(6)
	v_mfma_f32_32x32x16_bf16 v[112:127], v[128:131], v[136:139], v[112:127]
	v_mfma_f32_32x32x16_bf16 v[48:63], v[132:135], v[136:139], v[48:63]
	v_mfma_f32_32x32x16_bf16 v[96:111], v[128:131], v[140:143], v[96:111]
	v_mfma_f32_32x32x16_bf16 v[32:47], v[132:135], v[140:143], v[32:47]
	v_mfma_f32_32x32x16_bf16 v[80:95], v[128:131], v[144:147], v[80:95]
	v_mfma_f32_32x32x16_bf16 v[16:31], v[132:135], v[144:147], v[16:31]
	v_mfma_f32_32x32x16_bf16 v[64:79], v[128:131], v[148:151], v[64:79]
	v_mfma_f32_32x32x16_bf16 v[0:15], v[132:135], v[148:151], v[0:15]
	ds_read_b128 v[128:131], v240
	ds_read_b128 v[136:139], v255
	ds_read_b128 v[132:135], v240 offset:4096
	ds_read_b128 v[140:143], v255 offset:4096
	ds_read_b128 v[144:147], v255 offset:8192
	ds_read_b128 v[148:151], v255 offset:12288
	s_waitcnt lgkmcnt(6)
	v_mfma_f32_32x32x16_bf16 v[112:127], v[188:191], v[196:199], v[112:127]
	v_mfma_f32_32x32x16_bf16 v[48:63], v[192:195], v[196:199], v[48:63]
	v_mfma_f32_32x32x16_bf16 v[96:111], v[188:191], v[200:203], v[96:111]
	v_mfma_f32_32x32x16_bf16 v[32:47], v[192:195], v[200:203], v[32:47]
	v_mfma_f32_32x32x16_bf16 v[80:95], v[188:191], v[204:207], v[80:95]
	v_mfma_f32_32x32x16_bf16 v[16:31], v[192:195], v[204:207], v[16:31]
	v_mfma_f32_32x32x16_bf16 v[64:79], v[188:191], v[226:229], v[64:79]
	v_mfma_f32_32x32x16_bf16 v[0:15], v[192:195], v[226:229], v[0:15]
	s_waitcnt vmcnt(0) lgkmcnt(0)
	s_barrier
	v_mfma_f32_32x32x16_bf16 v[112:127], v[128:131], v[136:139], v[112:127]
	v_mfma_f32_32x32x16_bf16 v[48:63], v[132:135], v[136:139], v[48:63]
	v_mfma_f32_32x32x16_bf16 v[96:111], v[128:131], v[140:143], v[96:111]
	v_mfma_f32_32x32x16_bf16 v[32:47], v[132:135], v[140:143], v[32:47]
	v_mfma_f32_32x32x16_bf16 v[80:95], v[128:131], v[144:147], v[80:95]
	v_mfma_f32_32x32x16_bf16 v[16:31], v[132:135], v[144:147], v[16:31]
	v_mfma_f32_32x32x16_bf16 v[64:79], v[128:131], v[148:151], v[64:79]
	v_mfma_f32_32x32x16_bf16 v[0:15], v[132:135], v[148:151], v[0:15]
	s_lshl_b32 s2, s5, 8
	s_sub_i32 s2, s2, s6
	v_mov_b32_e32 v168, v214
	s_add_i32 s55, s4, s30
	s_or_b32 s26, s2, s31
	s_ashr_i32 s27, s26, 31
	s_load_dwordx2 s[24:25], s[0:1], 0x140
	v_ashrrev_i32_e32 v180, 3, v168
	v_and_b32_e32 v183, -4, v180
	v_add_u32_e32 v225, s55, v183
	v_add_u32_e32 v190, 8, v225
	v_min_i32_e32 v190, 0x7fff, v190
	v_ashrrev_i32_e32 v190, 12, v190
	v_add_u32_e32 v190, 16, v190
	v_mul_hi_i32_i24_e32 v191, 0x3000, v190
	v_mul_i32_i24_e32 v190, 0x3000, v190
	v_min_i32_e32 v184, 0x7fff, v225
	v_ashrrev_i32_e32 v184, 12, v184
	v_and_b32_e32 v182, 31, v168
	v_add_u32_e32 v184, 16, v184
	v_or_b32_e32 v180, s26, v182
	v_mul_hi_i32_i24_e32 v185, 0x3000, v184
	v_mul_i32_i24_e32 v184, 0x3000, v184
	v_ashrrev_i32_e32 v181, 31, v180
	s_waitcnt lgkmcnt(0)
	v_lshl_add_u64 v[184:185], s[24:25], 0, v[184:185]
	v_lshl_add_u64 v[184:185], v[184:185], 0, s[18:19]
	v_lshlrev_b64 v[180:181], 2, v[180:181]
	v_lshl_add_u64 v[196:197], v[184:185], 0, v[180:181]
	v_lshl_add_u64 v[186:187], s[24:25], 0, v[190:191]
	v_add_u32_e32 v188, 9, v225
	v_add_u32_e32 v190, 10, v225
	v_min_i32_e32 v188, 0x7fff, v188
	v_min_i32_e32 v190, 0x7fff, v190
	v_ashrrev_i32_e32 v188, 12, v188
	v_ashrrev_i32_e32 v190, 12, v190
	v_add_u32_e32 v188, 16, v188
	v_add_u32_e32 v190, 16, v190
	v_mul_hi_i32_i24_e32 v189, 0x3000, v188
	v_mul_i32_i24_e32 v188, 0x3000, v188
	v_mul_hi_i32_i24_e32 v191, 0x3000, v190
	v_mul_i32_i24_e32 v190, 0x3000, v190
	v_lshl_add_u64 v[188:189], s[24:25], 0, v[188:189]
	v_lshl_add_u64 v[190:191], s[24:25], 0, v[190:191]
	v_lshl_add_u64 v[186:187], v[186:187], 0, s[18:19]
	v_lshl_add_u64 v[188:189], v[188:189], 0, s[18:19]
	v_lshl_add_u64 v[190:191], v[190:191], 0, s[18:19]
	v_lshl_add_u64 v[206:207], v[186:187], 0, v[180:181]
	v_add_u32_e32 v208, 18, v225
	v_min_i32_e32 v208, 0x7fff, v208
	v_ashrrev_i32_e32 v208, 12, v208
	v_add_u32_e32 v208, 16, v208
	v_mul_hi_i32_i24_e32 v209, 0x3000, v208
	v_mul_i32_i24_e32 v208, 0x3000, v208
	v_lshl_add_u64 v[208:209], s[24:25], 0, v[208:209]
	v_lshl_add_u64 v[202:203], v[188:189], 0, v[180:181]
	v_lshl_add_u64 v[204:205], v[190:191], 0, v[180:181]
	global_load_dword v232, v[196:197], off
	global_load_dword v233, v[196:197], off offset:128
	global_load_dword v242, v[206:207], off
	global_load_dword v243, v[206:207], off offset:128
	global_load_dword v244, v[202:203], off
	global_load_dword v245, v[202:203], off offset:128
	global_load_dword v246, v[204:205], off
	global_load_dword v247, v[204:205], off offset:128
	v_add_u32_e32 v196, 17, v225
	v_min_i32_e32 v196, 0x7fff, v196
	v_ashrrev_i32_e32 v196, 12, v196
	v_add_u32_e32 v196, 16, v196
	v_mul_hi_i32_i24_e32 v197, 0x3000, v196
	v_mul_i32_i24_e32 v196, 0x3000, v196
	v_lshl_add_u64 v[196:197], s[24:25], 0, v[196:197]
	v_lshl_add_u64 v[196:197], v[196:197], 0, s[18:19]
	v_lshl_add_u64 v[206:207], v[196:197], 0, v[180:181]
	s_waitcnt vmcnt(7)
	s_nop 5
	v_mul_f32_e32 v112, v112, v232
	v_add_u32_e32 v192, 11, v225
	v_add_u32_e32 v194, 16, v225
	v_min_i32_e32 v192, 0x7fff, v192
	v_min_i32_e32 v194, 0x7fff, v194
	v_ashrrev_i32_e32 v192, 12, v192
	v_ashrrev_i32_e32 v194, 12, v194
	v_add_u32_e32 v192, 16, v192
	v_add_u32_e32 v194, 16, v194
	v_mul_hi_i32_i24_e32 v193, 0x3000, v192
	v_mul_i32_i24_e32 v192, 0x3000, v192
	v_mul_hi_i32_i24_e32 v195, 0x3000, v194
	v_mul_i32_i24_e32 v194, 0x3000, v194
	v_lshl_add_u64 v[192:193], s[24:25], 0, v[192:193]
	v_lshl_add_u64 v[194:195], s[24:25], 0, v[194:195]
	v_lshl_add_u64 v[192:193], v[192:193], 0, s[18:19]
	v_lshl_add_u64 v[194:195], v[194:195], 0, s[18:19]
	v_lshl_add_u64 v[202:203], v[192:193], 0, v[180:181]
	v_lshl_add_u64 v[204:205], v[194:195], 0, v[180:181]
	s_waitcnt vmcnt(6)
	s_nop 5
	v_mul_f32_e32 v96, v96, v233
	v_mul_f32_e32 v97, v97, v233
	v_lshl_add_u64 v[198:199], v[208:209], 0, s[18:19]
	v_lshl_add_u64 v[200:201], v[198:199], 0, v[180:181]
	global_load_dword v234, v[202:203], off
	global_load_dword v235, v[202:203], off offset:128
	global_load_dword v236, v[204:205], off
	global_load_dword v237, v[204:205], off offset:128
	global_load_dword v238, v[206:207], off
	global_load_dword v239, v[206:207], off offset:128
	global_load_dword v240, v[200:201], off
	global_load_dword v241, v[200:201], off offset:128
	v_add_u32_e32 v200, 19, v225
	v_add_u32_e32 v204, 25, v225
	v_add_u32_e32 v206, 26, v225
	v_min_i32_e32 v200, 0x7fff, v200
	v_add_u32_e32 v202, 24, v225
	v_min_i32_e32 v204, 0x7fff, v204
	v_min_i32_e32 v206, 0x7fff, v206
	v_ashrrev_i32_e32 v200, 12, v200
	v_min_i32_e32 v202, 0x7fff, v202
	v_ashrrev_i32_e32 v204, 12, v204
	v_ashrrev_i32_e32 v206, 12, v206
	v_add_u32_e32 v200, 16, v200
	v_ashrrev_i32_e32 v202, 12, v202
	v_add_u32_e32 v204, 16, v204
	v_add_u32_e32 v206, 16, v206
	v_mul_hi_i32_i24_e32 v201, 0x3000, v200
	v_mul_i32_i24_e32 v200, 0x3000, v200
	v_add_u32_e32 v202, 16, v202
	v_mul_hi_i32_i24_e32 v205, 0x3000, v204
	v_mul_i32_i24_e32 v204, 0x3000, v204
	v_mul_hi_i32_i24_e32 v207, 0x3000, v206
	v_mul_i32_i24_e32 v206, 0x3000, v206
	v_lshl_add_u64 v[200:201], s[24:25], 0, v[200:201]
	v_mul_hi_i32_i24_e32 v203, 0x3000, v202
	v_mul_i32_i24_e32 v202, 0x3000, v202
	v_lshl_add_u64 v[204:205], s[24:25], 0, v[204:205]
	v_lshl_add_u64 v[206:207], s[24:25], 0, v[206:207]
	v_lshl_add_u64 v[200:201], v[200:201], 0, s[18:19]
	v_lshl_add_u64 v[202:203], s[24:25], 0, v[202:203]
	v_lshl_add_u64 v[204:205], v[204:205], 0, s[18:19]
	v_lshl_add_u64 v[206:207], v[206:207], 0, s[18:19]
	v_lshl_add_u64 v[208:209], v[200:201], 0, v[180:181]
	v_lshl_add_u64 v[202:203], v[202:203], 0, s[18:19]
	v_lshl_add_u64 v[228:229], v[204:205], 0, v[180:181]
	v_lshl_add_u64 v[230:231], v[206:207], 0, v[180:181]
	v_lshl_add_u64 v[226:227], v[202:203], 0, v[180:181]
	global_load_dword v248, v[208:209], off
	global_load_dword v249, v[208:209], off offset:128
	global_load_dword v250, v[226:227], off
	global_load_dword v251, v[226:227], off offset:128
	global_load_dword v252, v[228:229], off
	s_nop 0
	global_load_dword v228, v[228:229], off offset:128
	s_nop 0
	global_load_dword v229, v[230:231], off
	s_nop 0
	global_load_dword v230, v[230:231], off offset:128
	v_add_u32_e32 v208, 27, v225
	v_min_i32_e32 v208, 0x7fff, v208
	v_ashrrev_i32_e32 v208, 12, v208
	v_add_u32_e32 v208, 16, v208
	v_mul_hi_i32_i24_e32 v209, 0x3000, v208
	v_mul_i32_i24_e32 v208, 0x3000, v208
	v_lshl_add_u64 v[208:209], s[24:25], 0, v[208:209]
	v_lshl_add_u64 v[208:209], v[208:209], 0, s[18:19]
	v_lshl_add_u64 v[226:227], v[208:209], 0, v[180:181]
	global_load_dword v225, v[226:227], off
	s_nop 0
	global_load_dword v226, v[226:227], off offset:128
	v_mad_u64_u32 v[160:161], s[2:3], v183, s36, v[182:183]
	v_lshl_add_u32 v162, v160, 2, s34
	ds_write2_b32 v162, v112, v96 offset1:32
	v_mul_f32_e32 v96, v113, v232
	ds_write2_b32 v162, v96, v97 offset0:68 offset1:100
	v_mul_f32_e32 v96, v114, v232
	v_mul_f32_e32 v97, v98, v233
	ds_write2_b32 v162, v96, v97 offset0:136 offset1:168
	v_mul_f32_e32 v96, v115, v232
	v_mul_f32_e32 v97, v99, v233
	ds_write2_b32 v162, v96, v97 offset0:204 offset1:236
	s_waitcnt vmcnt(23)
	v_mul_f32_e32 v96, v116, v242
	s_waitcnt vmcnt(22)
	v_mul_f32_e32 v97, v100, v243
	v_add_u32_e32 v115, 0x800, v162
	ds_write2_b32 v115, v96, v97 offset0:32 offset1:64
	s_waitcnt vmcnt(21)
	v_mul_f32_e32 v96, v117, v244
	s_waitcnt vmcnt(20)
	v_mul_f32_e32 v97, v101, v245
	ds_write2_b32 v115, v96, v97 offset0:100 offset1:132
	s_waitcnt vmcnt(19)
	v_mul_f32_e32 v96, v118, v246
	s_waitcnt vmcnt(18)
	v_mul_f32_e32 v97, v102, v247
	ds_write2_b32 v115, v96, v97 offset0:168 offset1:200
	v_add_u32_e32 v116, 0xa00, v162
	v_add_u32_e32 v117, 0x1000, v162
	s_waitcnt vmcnt(17)
	v_mul_f32_e32 v96, v119, v234
	s_waitcnt vmcnt(16)
	v_mul_f32_e32 v97, v103, v235
	ds_write2_b32 v116, v96, v97 offset0:108 offset1:140
	s_waitcnt vmcnt(15)
	v_mul_f32_e32 v96, v120, v236
	s_waitcnt vmcnt(14)
	v_mul_f32_e32 v97, v104, v237
	ds_write2_b32 v117, v96, v97 offset0:64 offset1:96
	s_waitcnt vmcnt(13)
	v_mul_f32_e32 v96, v121, v238
	s_waitcnt vmcnt(12)
	v_mul_f32_e32 v97, v105, v239
	ds_write2_b32 v117, v96, v97 offset0:132 offset1:164
	s_waitcnt vmcnt(11)
	v_mul_f32_e32 v96, v122, v240
	s_waitcnt vmcnt(10)
	v_mul_f32_e32 v97, v106, v241
	ds_write2_b32 v117, v96, v97 offset0:200 offset1:232
	v_add_u32_e32 v118, 0x1400, v162
	v_add_u32_e32 v119, 0x1800, v162
	v_ashrrev_i32_e32 v163, 4, v168
	v_and_b32_e32 v160, 15, v168
	v_add_u32_e32 v120, 0x1a00, v162
	v_mul_lo_u32 v164, v163, s37
	v_lshl_add_u32 v165, v160, 4, s34
	v_lshlrev_b32_e32 v168, 2, v160
	v_add_u32_e32 v160, s55, v163
	v_add_u32_e32 v121, 0x1c00, v162
	v_cmp_gt_i32_e32 vcc, s38, v160
	v_ashrrev_i32_e32 v161, 31, v160
	v_add_u32_e32 v114, v165, v164
	s_waitcnt vmcnt(9)
	v_mul_f32_e32 v96, v123, v248
	s_waitcnt vmcnt(8)
	v_mul_f32_e32 v97, v107, v249
	ds_write2_b32 v118, v96, v97 offset0:12 offset1:44
	s_waitcnt vmcnt(7)
	v_mul_f32_e32 v96, v124, v250
	s_waitcnt vmcnt(6)
	v_mul_f32_e32 v97, v108, v251
	ds_write2_b32 v119, v96, v97 offset0:96 offset1:128
	s_waitcnt vmcnt(5)
	v_mul_f32_e32 v96, v125, v252
	s_waitcnt vmcnt(4)
	v_mul_f32_e32 v97, v109, v228
	ds_write2_b32 v119, v96, v97 offset0:164 offset1:196
	s_waitcnt vmcnt(3)
	v_mul_f32_e32 v96, v126, v229
	s_waitcnt vmcnt(2)
	v_mul_f32_e32 v97, v110, v230
	ds_write2_b32 v120, v96, v97 offset0:104 offset1:136
	s_waitcnt vmcnt(1)
	v_mul_f32_e32 v96, v127, v225
	s_waitcnt vmcnt(0)
	v_mul_f32_e32 v97, v111, v226
	ds_write2_b32 v121, v96, v97 offset0:44 offset1:76
	v_or_b32_e32 v96, s26, v168
	v_mov_b32_e32 v97, s27
	v_add_u32_e32 v128, 0, v160
	v_ashrrev_i32_e32 v129, 31, v128
	v_lshlrev_b64 v[128:129], 12, v[128:129]
	v_lshl_add_u64 v[128:129], s[16:17], 0, v[128:129]
	v_lshl_add_u64 v[128:129], v[96:97], 2, v[128:129]
	global_load_dwordx4 v[128:131], v[128:129], off nt
	v_add_u32_e32 v132, 4, v160
	v_ashrrev_i32_e32 v133, 31, v132
	v_lshlrev_b64 v[132:133], 12, v[132:133]
	v_lshl_add_u64 v[132:133], s[16:17], 0, v[132:133]
	v_lshl_add_u64 v[132:133], v[96:97], 2, v[132:133]
	global_load_dwordx4 v[132:135], v[132:133], off nt
	v_add_u32_e32 v136, 8, v160
	v_ashrrev_i32_e32 v137, 31, v136
	v_lshlrev_b64 v[136:137], 12, v[136:137]
	v_lshl_add_u64 v[136:137], s[16:17], 0, v[136:137]
	v_lshl_add_u64 v[136:137], v[96:97], 2, v[136:137]
	global_load_dwordx4 v[136:139], v[136:137], off nt
	v_add_u32_e32 v140, 12, v160
	v_ashrrev_i32_e32 v141, 31, v140
	v_lshlrev_b64 v[140:141], 12, v[140:141]
	v_lshl_add_u64 v[140:141], s[16:17], 0, v[140:141]
	v_lshl_add_u64 v[140:141], v[96:97], 2, v[140:141]
	global_load_dwordx4 v[140:143], v[140:141], off nt
	v_add_u32_e32 v144, 16, v160
	v_ashrrev_i32_e32 v145, 31, v144
	v_lshlrev_b64 v[144:145], 12, v[144:145]
	v_lshl_add_u64 v[144:145], s[16:17], 0, v[144:145]
	v_lshl_add_u64 v[144:145], v[96:97], 2, v[144:145]
	global_load_dwordx4 v[144:147], v[144:145], off nt
	v_add_u32_e32 v148, 20, v160
	v_ashrrev_i32_e32 v149, 31, v148
	v_lshlrev_b64 v[148:149], 12, v[148:149]
	v_lshl_add_u64 v[148:149], s[16:17], 0, v[148:149]
	v_lshl_add_u64 v[148:149], v[96:97], 2, v[148:149]
	global_load_dwordx4 v[148:151], v[148:149], off nt
	v_add_u32_e32 v152, 24, v160
	v_ashrrev_i32_e32 v153, 31, v152
	v_lshlrev_b64 v[152:153], 12, v[152:153]
	v_lshl_add_u64 v[152:153], s[16:17], 0, v[152:153]
	v_lshl_add_u64 v[152:153], v[96:97], 2, v[152:153]
	global_load_dwordx4 v[152:155], v[152:153], off nt
	v_add_u32_e32 v156, 28, v160
	v_ashrrev_i32_e32 v157, 31, v156
	v_lshlrev_b64 v[156:157], 12, v[156:157]
	v_lshl_add_u64 v[156:157], s[16:17], 0, v[156:157]
	v_lshl_add_u64 v[156:157], v[96:97], 2, v[156:157]
	global_load_dwordx4 v[156:159], v[156:157], off nt
	s_and_saveexec_b64 s[2:3], vcc
	s_cbranch_execz .LBB0_4484
	v_lshlrev_b64 v[98:99], 12, v[160:161]
	v_lshl_add_u64 v[98:99], s[16:17], 0, v[98:99]
	v_lshl_add_u64 v[106:107], v[96:97], 2, v[98:99]
	ds_read_b128 v[102:105], v114
	s_waitcnt vmcnt(7) lgkmcnt(0)
	v_pk_add_f32 v[100:101], v[104:105], v[130:131]
	v_pk_add_f32 v[98:99], v[102:103], v[128:129]
	global_store_dwordx4 v[106:107], v[98:101], off nt

.LBB0_4514:
	s_or_b64 exec, exec, s[2:3]
	s_or_b32 s2, s55, 32
	v_add_u32_e32 v102, s2, v183
	v_min_i32_e32 v66, 0x7fff, v102
	v_add_u32_e32 v68, 8, v102
	v_add_u32_e32 v70, 9, v102
	v_add_u32_e32 v72, 10, v102
	v_ashrrev_i32_e32 v66, 12, v66
	v_min_i32_e32 v68, 0x7fff, v68
	v_min_i32_e32 v70, 0x7fff, v70
	v_min_i32_e32 v72, 0x7fff, v72
	v_add_u32_e32 v66, 16, v66
	v_ashrrev_i32_e32 v68, 12, v68
	v_ashrrev_i32_e32 v70, 12, v70
	v_ashrrev_i32_e32 v72, 12, v72
	v_mul_hi_i32_i24_e32 v67, 0x3000, v66
	v_mul_i32_i24_e32 v66, 0x3000, v66
	v_add_u32_e32 v68, 16, v68
	v_add_u32_e32 v70, 16, v70
	v_add_u32_e32 v72, 16, v72
	v_lshl_add_u64 v[66:67], s[24:25], 0, v[66:67]
	v_mul_hi_i32_i24_e32 v69, 0x3000, v68
	v_mul_i32_i24_e32 v68, 0x3000, v68
	v_mul_hi_i32_i24_e32 v71, 0x3000, v70
	v_mul_i32_i24_e32 v70, 0x3000, v70
	v_mul_hi_i32_i24_e32 v73, 0x3000, v72
	v_mul_i32_i24_e32 v72, 0x3000, v72
	v_lshl_add_u64 v[66:67], v[66:67], 0, s[18:19]
	v_lshl_add_u64 v[68:69], s[24:25], 0, v[68:69]
	v_lshl_add_u64 v[70:71], s[24:25], 0, v[70:71]
	v_lshl_add_u64 v[72:73], s[24:25], 0, v[72:73]
	v_lshl_add_u64 v[74:75], v[66:67], 0, v[180:181]
	v_lshl_add_u64 v[68:69], v[68:69], 0, s[18:19]
	v_lshl_add_u64 v[70:71], v[70:71], 0, s[18:19]
	v_lshl_add_u64 v[72:73], v[72:73], 0, s[18:19]
	v_lshl_add_u64 v[76:77], v[68:69], 0, v[180:181]
	v_lshl_add_u64 v[78:79], v[70:71], 0, v[180:181]
	v_lshl_add_u64 v[80:81], v[72:73], 0, v[180:181]
	global_load_dword v103, v[74:75], off
	global_load_dword v104, v[74:75], off offset:128
	global_load_dword v105, v[76:77], off
	global_load_dword v106, v[76:77], off offset:128
	global_load_dword v107, v[78:79], off
	global_load_dword v108, v[78:79], off offset:128
	global_load_dword v109, v[80:81], off
	global_load_dword v110, v[80:81], off offset:128
	v_add_u32_e32 v74, 11, v102
	v_add_u32_e32 v82, 18, v102
	v_min_i32_e32 v74, 0x7fff, v74
	v_add_u32_e32 v76, 16, v102
	v_add_u32_e32 v78, 17, v102
	v_min_i32_e32 v82, 0x7fff, v82
	v_ashrrev_i32_e32 v74, 12, v74
	v_min_i32_e32 v76, 0x7fff, v76
	v_min_i32_e32 v78, 0x7fff, v78
	v_ashrrev_i32_e32 v82, 12, v82
	v_add_u32_e32 v74, 16, v74
	v_ashrrev_i32_e32 v76, 12, v76
	v_ashrrev_i32_e32 v78, 12, v78
	v_add_u32_e32 v82, 16, v82
	v_mul_hi_i32_i24_e32 v75, 0x3000, v74
	v_mul_i32_i24_e32 v74, 0x3000, v74
	v_add_u32_e32 v76, 16, v76
	v_add_u32_e32 v78, 16, v78
	v_mul_hi_i32_i24_e32 v83, 0x3000, v82
	v_mul_i32_i24_e32 v82, 0x3000, v82
	v_lshl_add_u64 v[74:75], s[24:25], 0, v[74:75]
	v_mul_hi_i32_i24_e32 v77, 0x3000, v76
	v_mul_i32_i24_e32 v76, 0x3000, v76
	v_mul_hi_i32_i24_e32 v79, 0x3000, v78
	v_mul_i32_i24_e32 v78, 0x3000, v78
	v_lshl_add_u64 v[82:83], s[24:25], 0, v[82:83]
	v_lshl_add_u64 v[74:75], v[74:75], 0, s[18:19]
	v_lshl_add_u64 v[76:77], s[24:25], 0, v[76:77]
	v_lshl_add_u64 v[78:79], s[24:25], 0, v[78:79]
	v_lshl_add_u64 v[82:83], v[82:83], 0, s[18:19]
	v_lshl_add_u64 v[80:81], v[74:75], 0, v[180:181]
	v_lshl_add_u64 v[76:77], v[76:77], 0, s[18:19]
	v_lshl_add_u64 v[78:79], v[78:79], 0, s[18:19]
	v_lshl_add_u64 v[88:89], v[82:83], 0, v[180:181]
	v_lshl_add_u64 v[84:85], v[76:77], 0, v[180:181]
	v_lshl_add_u64 v[86:87], v[78:79], 0, v[180:181]
	global_load_dword v111, v[80:81], off
	global_load_dword v112, v[80:81], off offset:128
	global_load_dword v113, v[84:85], off
	global_load_dword v122, v[84:85], off offset:128
	global_load_dword v123, v[86:87], off
	global_load_dword v124, v[86:87], off offset:128
	global_load_dword v125, v[88:89], off
	global_load_dword v126, v[88:89], off offset:128
	v_add_u32_e32 v80, 19, v102
	v_add_u32_e32 v88, 25, v102
	v_add_u32_e32 v90, 26, v102
	v_min_i32_e32 v80, 0x7fff, v80
	v_add_u32_e32 v86, 24, v102
	v_min_i32_e32 v88, 0x7fff, v88
	v_min_i32_e32 v90, 0x7fff, v90
	v_ashrrev_i32_e32 v80, 12, v80
	v_min_i32_e32 v86, 0x7fff, v86
	v_ashrrev_i32_e32 v88, 12, v88
	v_ashrrev_i32_e32 v90, 12, v90
	v_add_u32_e32 v80, 16, v80
	v_ashrrev_i32_e32 v86, 12, v86
	v_add_u32_e32 v88, 16, v88
	v_add_u32_e32 v90, 16, v90
	v_mul_hi_i32_i24_e32 v81, 0x3000, v80
	v_mul_i32_i24_e32 v80, 0x3000, v80
	v_add_u32_e32 v86, 16, v86
	v_mul_hi_i32_i24_e32 v89, 0x3000, v88
	v_mul_i32_i24_e32 v88, 0x3000, v88
	v_mul_hi_i32_i24_e32 v91, 0x3000, v90
	v_mul_i32_i24_e32 v90, 0x3000, v90
	v_lshl_add_u64 v[80:81], s[24:25], 0, v[80:81]
	v_mul_hi_i32_i24_e32 v87, 0x3000, v86
	v_mul_i32_i24_e32 v86, 0x3000, v86
	v_lshl_add_u64 v[88:89], s[24:25], 0, v[88:89]
	v_lshl_add_u64 v[90:91], s[24:25], 0, v[90:91]
	v_lshl_add_u64 v[84:85], v[80:81], 0, s[18:19]
	v_lshl_add_u64 v[86:87], s[24:25], 0, v[86:87]
	v_lshl_add_u64 v[88:89], v[88:89], 0, s[18:19]
	v_lshl_add_u64 v[90:91], v[90:91], 0, s[18:19]
	v_lshl_add_u64 v[80:81], v[84:85], 0, v[180:181]
	v_lshl_add_u64 v[86:87], v[86:87], 0, s[18:19]
	v_lshl_add_u64 v[94:95], v[88:89], 0, v[180:181]
	v_lshl_add_u64 v[100:101], v[90:91], 0, v[180:181]
	v_lshl_add_u64 v[92:93], v[86:87], 0, v[180:181]
	global_load_dword v127, v[80:81], off
	global_load_dword v160, v[80:81], off offset:128
	global_load_dword v161, v[92:93], off
	global_load_dword v164, v[92:93], off offset:128
	global_load_dword v165, v[94:95], off
	s_nop 0
	global_load_dword v94, v[94:95], off offset:128
	s_nop 0
	global_load_dword v95, v[100:101], off
	s_nop 0
	global_load_dword v100, v[100:101], off offset:128
	v_add_u32_e32 v80, 27, v102
	v_min_i32_e32 v80, 0x7fff, v80
	v_ashrrev_i32_e32 v80, 12, v80
	v_add_u32_e32 v80, 16, v80
	v_mul_hi_i32_i24_e32 v81, 0x3000, v80
	v_mul_i32_i24_e32 v80, 0x3000, v80
	v_lshl_add_u64 v[80:81], s[24:25], 0, v[80:81]
	v_lshl_add_u64 v[92:93], v[80:81], 0, s[18:19]
	v_lshl_add_u64 v[80:81], v[92:93], 0, v[180:181]
	global_load_dword v101, v[80:81], off
	s_nop 0
	global_load_dword v81, v[80:81], off offset:128
	s_waitcnt vmcnt(25)
	v_mul_f32_e32 v48, v48, v103
	s_waitcnt vmcnt(24)
	v_mul_f32_e32 v32, v32, v104
	ds_write2_b32 v162, v48, v32 offset1:32
	v_mul_f32_e32 v32, v49, v103
	v_mul_f32_e32 v33, v33, v104
	ds_write2_b32 v162, v32, v33 offset0:68 offset1:100
	v_mul_f32_e32 v32, v50, v103
	v_mul_f32_e32 v33, v34, v104
	ds_write2_b32 v162, v32, v33 offset0:136 offset1:168
	v_mul_f32_e32 v32, v51, v103
	v_mul_f32_e32 v33, v35, v104
	ds_write2_b32 v162, v32, v33 offset0:204 offset1:236
	s_waitcnt vmcnt(23)
	v_mul_f32_e32 v32, v52, v105
	s_waitcnt vmcnt(22)
	v_mul_f32_e32 v33, v36, v106
	ds_write2_b32 v115, v32, v33 offset0:32 offset1:64
	s_waitcnt vmcnt(21)
	v_mul_f32_e32 v32, v53, v107
	s_waitcnt vmcnt(20)
	v_mul_f32_e32 v33, v37, v108
	ds_write2_b32 v115, v32, v33 offset0:100 offset1:132
	s_waitcnt vmcnt(19)
	v_mul_f32_e32 v32, v54, v109
	s_waitcnt vmcnt(18)
	v_mul_f32_e32 v33, v38, v110
	ds_write2_b32 v115, v32, v33 offset0:168 offset1:200
	v_add_u32_e32 v80, s2, v163
	v_cmp_gt_i32_e32 vcc, s38, v80
	s_waitcnt vmcnt(17)
	v_mul_f32_e32 v32, v55, v111
	s_waitcnt vmcnt(16)
	v_mul_f32_e32 v33, v39, v112
	ds_write2_b32 v116, v32, v33 offset0:108 offset1:140
	s_waitcnt vmcnt(15)
	v_mul_f32_e32 v32, v56, v113
	s_waitcnt vmcnt(14)
	v_mul_f32_e32 v33, v40, v122
	ds_write2_b32 v117, v32, v33 offset0:64 offset1:96
	s_waitcnt vmcnt(13)
	v_mul_f32_e32 v32, v57, v123
	s_waitcnt vmcnt(12)
	v_mul_f32_e32 v33, v41, v124
	ds_write2_b32 v117, v32, v33 offset0:132 offset1:164
	s_waitcnt vmcnt(11)
	v_mul_f32_e32 v32, v58, v125
	s_waitcnt vmcnt(10)
	v_mul_f32_e32 v33, v42, v126
	ds_write2_b32 v117, v32, v33 offset0:200 offset1:232
	s_waitcnt vmcnt(9)
	v_mul_f32_e32 v32, v59, v127
	s_waitcnt vmcnt(8)
	v_mul_f32_e32 v33, v43, v160
	ds_write2_b32 v118, v32, v33 offset0:12 offset1:44
	s_waitcnt vmcnt(7)
	v_mul_f32_e32 v32, v60, v161
	s_waitcnt vmcnt(6)
	v_mul_f32_e32 v33, v44, v164
	ds_write2_b32 v119, v32, v33 offset0:96 offset1:128
	s_waitcnt vmcnt(5)
	v_mul_f32_e32 v32, v61, v165
	s_waitcnt vmcnt(4)
	v_mul_f32_e32 v33, v45, v94
	ds_write2_b32 v119, v32, v33 offset0:164 offset1:196
	s_waitcnt vmcnt(3)
	v_mul_f32_e32 v32, v62, v95
	s_waitcnt vmcnt(2)
	v_mul_f32_e32 v33, v46, v100
	ds_write2_b32 v120, v32, v33 offset0:104 offset1:136
	s_waitcnt vmcnt(1)
	v_mul_f32_e32 v32, v63, v101
	s_waitcnt vmcnt(0)
	v_mul_f32_e32 v33, v47, v81
	v_ashrrev_i32_e32 v81, 31, v80
	ds_write2_b32 v121, v32, v33 offset0:44 offset1:76
	v_add_u32_e32 v128, 0, v80
	v_ashrrev_i32_e32 v129, 31, v128
	v_lshlrev_b64 v[128:129], 12, v[128:129]
	v_lshl_add_u64 v[128:129], s[16:17], 0, v[128:129]
	v_lshl_add_u64 v[128:129], v[96:97], 2, v[128:129]
	global_load_dwordx4 v[128:131], v[128:129], off nt
	v_add_u32_e32 v132, 4, v80
	v_ashrrev_i32_e32 v133, 31, v132
	v_lshlrev_b64 v[132:133], 12, v[132:133]
	v_lshl_add_u64 v[132:133], s[16:17], 0, v[132:133]
	v_lshl_add_u64 v[132:133], v[96:97], 2, v[132:133]
	global_load_dwordx4 v[132:135], v[132:133], off nt
	v_add_u32_e32 v136, 8, v80
	v_ashrrev_i32_e32 v137, 31, v136
	v_lshlrev_b64 v[136:137], 12, v[136:137]
	v_lshl_add_u64 v[136:137], s[16:17], 0, v[136:137]
	v_lshl_add_u64 v[136:137], v[96:97], 2, v[136:137]
	global_load_dwordx4 v[136:139], v[136:137], off nt
	v_add_u32_e32 v140, 12, v80
	v_ashrrev_i32_e32 v141, 31, v140
	v_lshlrev_b64 v[140:141], 12, v[140:141]
	v_lshl_add_u64 v[140:141], s[16:17], 0, v[140:141]
	v_lshl_add_u64 v[140:141], v[96:97], 2, v[140:141]
	global_load_dwordx4 v[140:143], v[140:141], off nt
	v_add_u32_e32 v144, 16, v80
	v_ashrrev_i32_e32 v145, 31, v144
	v_lshlrev_b64 v[144:145], 12, v[144:145]
	v_lshl_add_u64 v[144:145], s[16:17], 0, v[144:145]
	v_lshl_add_u64 v[144:145], v[96:97], 2, v[144:145]
	global_load_dwordx4 v[144:147], v[144:145], off nt
	v_add_u32_e32 v148, 20, v80
	v_ashrrev_i32_e32 v149, 31, v148
	v_lshlrev_b64 v[148:149], 12, v[148:149]
	v_lshl_add_u64 v[148:149], s[16:17], 0, v[148:149]
	v_lshl_add_u64 v[148:149], v[96:97], 2, v[148:149]
	global_load_dwordx4 v[148:151], v[148:149], off nt
	v_add_u32_e32 v152, 24, v80
	v_ashrrev_i32_e32 v153, 31, v152
	v_lshlrev_b64 v[152:153], 12, v[152:153]
	v_lshl_add_u64 v[152:153], s[16:17], 0, v[152:153]
	v_lshl_add_u64 v[152:153], v[96:97], 2, v[152:153]
	global_load_dwordx4 v[152:155], v[152:153], off nt
	v_add_u32_e32 v156, 28, v80
	v_ashrrev_i32_e32 v157, 31, v156
	v_lshlrev_b64 v[156:157], 12, v[156:157]
	v_lshl_add_u64 v[156:157], s[16:17], 0, v[156:157]
	v_lshl_add_u64 v[156:157], v[96:97], 2, v[156:157]
	global_load_dwordx4 v[156:159], v[156:157], off nt
	s_and_saveexec_b64 s[2:3], vcc
	s_cbranch_execz .LBB0_4516
	v_lshlrev_b64 v[32:33], 12, v[80:81]
	v_lshl_add_u64 v[32:33], s[16:17], 0, v[32:33]
	v_lshl_add_u64 v[40:41], v[96:97], 2, v[32:33]
	ds_read_b128 v[36:39], v114
	s_waitcnt vmcnt(7) lgkmcnt(0)
	v_pk_add_f32 v[34:35], v[38:39], v[130:131]
	v_pk_add_f32 v[32:33], v[36:37], v[128:129]
	global_store_dwordx4 v[40:41], v[32:35], off nt

.LBB0_5644:
	ds_read_b128 v[128:131], v238
	ds_read_b128 v[136:139], v253
	ds_read_b128 v[132:135], v238 offset:4096
	ds_read_b128 v[140:143], v253 offset:4096
	ds_read_b128 v[144:147], v253 offset:8192
	ds_read_b128 v[148:151], v253 offset:12288
	s_waitcnt lgkmcnt(6)
	v_mfma_f32_32x32x16_bf16 v[112:127], v[188:191], v[196:199], v[112:127]
	v_mfma_f32_32x32x16_bf16 v[48:63], v[192:195], v[196:199], v[48:63]
	v_mfma_f32_32x32x16_bf16 v[96:111], v[188:191], v[200:203], v[96:111]
	v_mfma_f32_32x32x16_bf16 v[32:47], v[192:195], v[200:203], v[32:47]
	v_mfma_f32_32x32x16_bf16 v[80:95], v[188:191], v[204:207], v[80:95]
	v_mfma_f32_32x32x16_bf16 v[16:31], v[192:195], v[204:207], v[16:31]
	v_mfma_f32_32x32x16_bf16 v[64:79], v[188:191], v[226:229], v[64:79]
	v_mfma_f32_32x32x16_bf16 v[0:15], v[192:195], v[226:229], v[0:15]
	ds_read_b128 v[188:191], v239
	ds_read_b128 v[196:199], v254
	ds_read_b128 v[192:195], v239 offset:4096
	ds_read_b128 v[200:203], v254 offset:4096
	ds_read_b128 v[204:207], v254 offset:8192
	ds_read_b128 v[226:229], v254 offset:12288
	s_waitcnt lgkmcnt(6)
	v_mfma_f32_32x32x16_bf16 v[112:127], v[128:131], v[136:139], v[112:127]
	v_mfma_f32_32x32x16_bf16 v[48:63], v[132:135], v[136:139], v[48:63]
	v_mfma_f32_32x32x16_bf16 v[96:111], v[128:131], v[140:143], v[96:111]
	v_mfma_f32_32x32x16_bf16 v[32:47], v[132:135], v[140:143], v[32:47]
	v_mfma_f32_32x32x16_bf16 v[80:95], v[128:131], v[144:147], v[80:95]
	v_mfma_f32_32x32x16_bf16 v[16:31], v[132:135], v[144:147], v[16:31]
	v_mfma_f32_32x32x16_bf16 v[64:79], v[128:131], v[148:151], v[64:79]
	v_mfma_f32_32x32x16_bf16 v[0:15], v[132:135], v[148:151], v[0:15]
	ds_read_b128 v[128:131], v240
	ds_read_b128 v[136:139], v255
	ds_read_b128 v[132:135], v240 offset:4096
	ds_read_b128 v[140:143], v255 offset:4096
	ds_read_b128 v[144:147], v255 offset:8192
	ds_read_b128 v[148:151], v255 offset:12288
	s_waitcnt lgkmcnt(6)
	v_mfma_f32_32x32x16_bf16 v[112:127], v[188:191], v[196:199], v[112:127]
	v_mfma_f32_32x32x16_bf16 v[48:63], v[192:195], v[196:199], v[48:63]
	v_mfma_f32_32x32x16_bf16 v[96:111], v[188:191], v[200:203], v[96:111]
	v_mfma_f32_32x32x16_bf16 v[32:47], v[192:195], v[200:203], v[32:47]
	v_mfma_f32_32x32x16_bf16 v[80:95], v[188:191], v[204:207], v[80:95]
	v_mfma_f32_32x32x16_bf16 v[16:31], v[192:195], v[204:207], v[16:31]
	v_mfma_f32_32x32x16_bf16 v[64:79], v[188:191], v[226:229], v[64:79]
	v_mfma_f32_32x32x16_bf16 v[0:15], v[192:195], v[226:229], v[0:15]
	s_waitcnt vmcnt(0) lgkmcnt(0)
	s_barrier
	v_mfma_f32_32x32x16_bf16 v[112:127], v[128:131], v[136:139], v[112:127]
	v_mfma_f32_32x32x16_bf16 v[48:63], v[132:135], v[136:139], v[48:63]
	v_mfma_f32_32x32x16_bf16 v[96:111], v[128:131], v[140:143], v[96:111]
	v_mfma_f32_32x32x16_bf16 v[32:47], v[132:135], v[140:143], v[32:47]
	v_mfma_f32_32x32x16_bf16 v[80:95], v[128:131], v[144:147], v[80:95]
	v_mfma_f32_32x32x16_bf16 v[16:31], v[132:135], v[144:147], v[16:31]
	v_mfma_f32_32x32x16_bf16 v[64:79], v[128:131], v[148:151], v[64:79]
	v_mfma_f32_32x32x16_bf16 v[0:15], v[132:135], v[148:151], v[0:15]
	s_lshl_b32 s2, s5, 8
	s_sub_i32 s2, s2, s6
	v_mov_b32_e32 v168, v214
	s_add_i32 s55, s4, s30
	s_or_b32 s26, s2, s31
	s_ashr_i32 s27, s26, 31
	s_load_dwordx2 s[24:25], s[0:1], 0x140
	v_ashrrev_i32_e32 v180, 3, v168
	v_and_b32_e32 v183, -4, v180
	v_add_u32_e32 v225, s55, v183
	v_add_u32_e32 v190, 8, v225
	v_min_i32_e32 v190, 0x7fff, v190
	v_ashrrev_i32_e32 v190, 12, v190
	v_add_u32_e32 v190, 24, v190
	v_mul_hi_i32_i24_e32 v191, 0x3000, v190
	v_mul_i32_i24_e32 v190, 0x3000, v190
	v_min_i32_e32 v184, 0x7fff, v225
	v_ashrrev_i32_e32 v184, 12, v184
	v_and_b32_e32 v182, 31, v168
	v_add_u32_e32 v184, 24, v184
	v_or_b32_e32 v180, s26, v182
	v_mul_hi_i32_i24_e32 v185, 0x3000, v184
	v_mul_i32_i24_e32 v184, 0x3000, v184
	v_ashrrev_i32_e32 v181, 31, v180
	s_waitcnt lgkmcnt(0)
	v_lshl_add_u64 v[184:185], s[24:25], 0, v[184:185]
	v_lshl_add_u64 v[184:185], v[184:185], 0, s[18:19]
	v_lshlrev_b64 v[180:181], 2, v[180:181]
	v_lshl_add_u64 v[196:197], v[184:185], 0, v[180:181]
	v_lshl_add_u64 v[186:187], s[24:25], 0, v[190:191]
	v_add_u32_e32 v188, 9, v225
	v_add_u32_e32 v190, 10, v225
	v_min_i32_e32 v188, 0x7fff, v188
	v_min_i32_e32 v190, 0x7fff, v190
	v_ashrrev_i32_e32 v188, 12, v188
	v_ashrrev_i32_e32 v190, 12, v190
	v_add_u32_e32 v188, 24, v188
	v_add_u32_e32 v190, 24, v190
	v_mul_hi_i32_i24_e32 v189, 0x3000, v188
	v_mul_i32_i24_e32 v188, 0x3000, v188
	v_mul_hi_i32_i24_e32 v191, 0x3000, v190
	v_mul_i32_i24_e32 v190, 0x3000, v190
	v_lshl_add_u64 v[188:189], s[24:25], 0, v[188:189]
	v_lshl_add_u64 v[190:191], s[24:25], 0, v[190:191]
	v_lshl_add_u64 v[186:187], v[186:187], 0, s[18:19]
	v_lshl_add_u64 v[188:189], v[188:189], 0, s[18:19]
	v_lshl_add_u64 v[190:191], v[190:191], 0, s[18:19]
	v_lshl_add_u64 v[206:207], v[186:187], 0, v[180:181]
	v_add_u32_e32 v208, 18, v225
	v_min_i32_e32 v208, 0x7fff, v208
	v_ashrrev_i32_e32 v208, 12, v208
	v_add_u32_e32 v208, 24, v208
	v_mul_hi_i32_i24_e32 v209, 0x3000, v208
	v_mul_i32_i24_e32 v208, 0x3000, v208
	v_lshl_add_u64 v[208:209], s[24:25], 0, v[208:209]
	v_lshl_add_u64 v[202:203], v[188:189], 0, v[180:181]
	v_lshl_add_u64 v[204:205], v[190:191], 0, v[180:181]
	global_load_dword v232, v[196:197], off
	global_load_dword v233, v[196:197], off offset:128
	global_load_dword v242, v[206:207], off
	global_load_dword v243, v[206:207], off offset:128
	global_load_dword v244, v[202:203], off
	global_load_dword v245, v[202:203], off offset:128
	global_load_dword v246, v[204:205], off
	global_load_dword v247, v[204:205], off offset:128
	v_add_u32_e32 v196, 17, v225
	v_min_i32_e32 v196, 0x7fff, v196
	v_ashrrev_i32_e32 v196, 12, v196
	v_add_u32_e32 v196, 24, v196
	v_mul_hi_i32_i24_e32 v197, 0x3000, v196
	v_mul_i32_i24_e32 v196, 0x3000, v196
	v_lshl_add_u64 v[196:197], s[24:25], 0, v[196:197]
	v_lshl_add_u64 v[196:197], v[196:197], 0, s[18:19]
	v_lshl_add_u64 v[206:207], v[196:197], 0, v[180:181]
	s_waitcnt vmcnt(7)
	s_nop 5
	v_mul_f32_e32 v112, v112, v232
	v_add_u32_e32 v192, 11, v225
	v_add_u32_e32 v194, 16, v225
	v_min_i32_e32 v192, 0x7fff, v192
	v_min_i32_e32 v194, 0x7fff, v194
	v_ashrrev_i32_e32 v192, 12, v192
	v_ashrrev_i32_e32 v194, 12, v194
	v_add_u32_e32 v192, 24, v192
	v_add_u32_e32 v194, 24, v194
	v_mul_hi_i32_i24_e32 v193, 0x3000, v192
	v_mul_i32_i24_e32 v192, 0x3000, v192
	v_mul_hi_i32_i24_e32 v195, 0x3000, v194
	v_mul_i32_i24_e32 v194, 0x3000, v194
	v_lshl_add_u64 v[192:193], s[24:25], 0, v[192:193]
	v_lshl_add_u64 v[194:195], s[24:25], 0, v[194:195]
	v_lshl_add_u64 v[192:193], v[192:193], 0, s[18:19]
	v_lshl_add_u64 v[194:195], v[194:195], 0, s[18:19]
	v_lshl_add_u64 v[202:203], v[192:193], 0, v[180:181]
	v_lshl_add_u64 v[204:205], v[194:195], 0, v[180:181]
	s_waitcnt vmcnt(6)
	s_nop 5
	v_mul_f32_e32 v96, v96, v233
	v_mul_f32_e32 v97, v97, v233
	v_lshl_add_u64 v[198:199], v[208:209], 0, s[18:19]
	v_lshl_add_u64 v[200:201], v[198:199], 0, v[180:181]
	global_load_dword v234, v[202:203], off
	global_load_dword v235, v[202:203], off offset:128
	global_load_dword v236, v[204:205], off
	global_load_dword v237, v[204:205], off offset:128
	global_load_dword v238, v[206:207], off
	global_load_dword v239, v[206:207], off offset:128
	global_load_dword v240, v[200:201], off
	global_load_dword v241, v[200:201], off offset:128
	v_add_u32_e32 v200, 19, v225
	v_add_u32_e32 v204, 25, v225
	v_add_u32_e32 v206, 26, v225
	v_min_i32_e32 v200, 0x7fff, v200
	v_add_u32_e32 v202, 24, v225
	v_min_i32_e32 v204, 0x7fff, v204
	v_min_i32_e32 v206, 0x7fff, v206
	v_ashrrev_i32_e32 v200, 12, v200
	v_min_i32_e32 v202, 0x7fff, v202
	v_ashrrev_i32_e32 v204, 12, v204
	v_ashrrev_i32_e32 v206, 12, v206
	v_add_u32_e32 v200, 24, v200
	v_ashrrev_i32_e32 v202, 12, v202
	v_add_u32_e32 v204, 24, v204
	v_add_u32_e32 v206, 24, v206
	v_mul_hi_i32_i24_e32 v201, 0x3000, v200
	v_mul_i32_i24_e32 v200, 0x3000, v200
	v_add_u32_e32 v202, 24, v202
	v_mul_hi_i32_i24_e32 v205, 0x3000, v204
	v_mul_i32_i24_e32 v204, 0x3000, v204
	v_mul_hi_i32_i24_e32 v207, 0x3000, v206
	v_mul_i32_i24_e32 v206, 0x3000, v206
	v_lshl_add_u64 v[200:201], s[24:25], 0, v[200:201]
	v_mul_hi_i32_i24_e32 v203, 0x3000, v202
	v_mul_i32_i24_e32 v202, 0x3000, v202
	v_lshl_add_u64 v[204:205], s[24:25], 0, v[204:205]
	v_lshl_add_u64 v[206:207], s[24:25], 0, v[206:207]
	v_lshl_add_u64 v[200:201], v[200:201], 0, s[18:19]
	v_lshl_add_u64 v[202:203], s[24:25], 0, v[202:203]
	v_lshl_add_u64 v[204:205], v[204:205], 0, s[18:19]
	v_lshl_add_u64 v[206:207], v[206:207], 0, s[18:19]
	v_lshl_add_u64 v[208:209], v[200:201], 0, v[180:181]
	v_lshl_add_u64 v[202:203], v[202:203], 0, s[18:19]
	v_lshl_add_u64 v[228:229], v[204:205], 0, v[180:181]
	v_lshl_add_u64 v[230:231], v[206:207], 0, v[180:181]
	v_lshl_add_u64 v[226:227], v[202:203], 0, v[180:181]
	global_load_dword v248, v[208:209], off
	global_load_dword v249, v[208:209], off offset:128
	global_load_dword v250, v[226:227], off
	global_load_dword v251, v[226:227], off offset:128
	global_load_dword v252, v[228:229], off
	s_nop 0
	global_load_dword v228, v[228:229], off offset:128
	s_nop 0
	global_load_dword v229, v[230:231], off
	s_nop 0
	global_load_dword v230, v[230:231], off offset:128
	v_add_u32_e32 v208, 27, v225
	v_min_i32_e32 v208, 0x7fff, v208
	v_ashrrev_i32_e32 v208, 12, v208
	v_add_u32_e32 v208, 24, v208
	v_mul_hi_i32_i24_e32 v209, 0x3000, v208
	v_mul_i32_i24_e32 v208, 0x3000, v208
	v_lshl_add_u64 v[208:209], s[24:25], 0, v[208:209]
	v_lshl_add_u64 v[208:209], v[208:209], 0, s[18:19]
	v_lshl_add_u64 v[226:227], v[208:209], 0, v[180:181]
	global_load_dword v225, v[226:227], off
	s_nop 0
	global_load_dword v226, v[226:227], off offset:128
	v_mad_u64_u32 v[160:161], s[2:3], v183, s36, v[182:183]
	v_lshl_add_u32 v162, v160, 2, s34
	ds_write2_b32 v162, v112, v96 offset1:32
	v_mul_f32_e32 v96, v113, v232
	ds_write2_b32 v162, v96, v97 offset0:68 offset1:100
	v_mul_f32_e32 v96, v114, v232
	v_mul_f32_e32 v97, v98, v233
	ds_write2_b32 v162, v96, v97 offset0:136 offset1:168
	v_mul_f32_e32 v96, v115, v232
	v_mul_f32_e32 v97, v99, v233
	ds_write2_b32 v162, v96, v97 offset0:204 offset1:236
	s_waitcnt vmcnt(23)
	v_mul_f32_e32 v96, v116, v242
	s_waitcnt vmcnt(22)
	v_mul_f32_e32 v97, v100, v243
	v_add_u32_e32 v115, 0x800, v162
	ds_write2_b32 v115, v96, v97 offset0:32 offset1:64
	s_waitcnt vmcnt(21)
	v_mul_f32_e32 v96, v117, v244
	s_waitcnt vmcnt(20)
	v_mul_f32_e32 v97, v101, v245
	ds_write2_b32 v115, v96, v97 offset0:100 offset1:132
	s_waitcnt vmcnt(19)
	v_mul_f32_e32 v96, v118, v246
	s_waitcnt vmcnt(18)
	v_mul_f32_e32 v97, v102, v247
	ds_write2_b32 v115, v96, v97 offset0:168 offset1:200
	v_add_u32_e32 v116, 0xa00, v162
	v_add_u32_e32 v117, 0x1000, v162
	s_waitcnt vmcnt(17)
	v_mul_f32_e32 v96, v119, v234
	s_waitcnt vmcnt(16)
	v_mul_f32_e32 v97, v103, v235
	ds_write2_b32 v116, v96, v97 offset0:108 offset1:140
	s_waitcnt vmcnt(15)
	v_mul_f32_e32 v96, v120, v236
	s_waitcnt vmcnt(14)
	v_mul_f32_e32 v97, v104, v237
	ds_write2_b32 v117, v96, v97 offset0:64 offset1:96
	s_waitcnt vmcnt(13)
	v_mul_f32_e32 v96, v121, v238
	s_waitcnt vmcnt(12)
	v_mul_f32_e32 v97, v105, v239
	ds_write2_b32 v117, v96, v97 offset0:132 offset1:164
	s_waitcnt vmcnt(11)
	v_mul_f32_e32 v96, v122, v240
	s_waitcnt vmcnt(10)
	v_mul_f32_e32 v97, v106, v241
	ds_write2_b32 v117, v96, v97 offset0:200 offset1:232
	v_add_u32_e32 v118, 0x1400, v162
	v_add_u32_e32 v119, 0x1800, v162
	v_ashrrev_i32_e32 v163, 4, v168
	v_and_b32_e32 v160, 15, v168
	v_add_u32_e32 v120, 0x1a00, v162
	v_mul_lo_u32 v164, v163, s37
	v_lshl_add_u32 v165, v160, 4, s34
	v_lshlrev_b32_e32 v168, 2, v160
	v_add_u32_e32 v160, s55, v163
	v_add_u32_e32 v121, 0x1c00, v162
	v_cmp_gt_i32_e32 vcc, s38, v160
	v_ashrrev_i32_e32 v161, 31, v160
	v_add_u32_e32 v114, v165, v164
	s_waitcnt vmcnt(9)
	v_mul_f32_e32 v96, v123, v248
	s_waitcnt vmcnt(8)
	v_mul_f32_e32 v97, v107, v249
	ds_write2_b32 v118, v96, v97 offset0:12 offset1:44
	s_waitcnt vmcnt(7)
	v_mul_f32_e32 v96, v124, v250
	s_waitcnt vmcnt(6)
	v_mul_f32_e32 v97, v108, v251
	ds_write2_b32 v119, v96, v97 offset0:96 offset1:128
	s_waitcnt vmcnt(5)
	v_mul_f32_e32 v96, v125, v252
	s_waitcnt vmcnt(4)
	v_mul_f32_e32 v97, v109, v228
	ds_write2_b32 v119, v96, v97 offset0:164 offset1:196
	s_waitcnt vmcnt(3)
	v_mul_f32_e32 v96, v126, v229
	s_waitcnt vmcnt(2)
	v_mul_f32_e32 v97, v110, v230
	ds_write2_b32 v120, v96, v97 offset0:104 offset1:136
	s_waitcnt vmcnt(1)
	v_mul_f32_e32 v96, v127, v225
	s_waitcnt vmcnt(0)
	v_mul_f32_e32 v97, v111, v226
	ds_write2_b32 v121, v96, v97 offset0:44 offset1:76
	v_or_b32_e32 v96, s26, v168
	v_mov_b32_e32 v97, s27
	v_add_u32_e32 v128, 0, v160
	v_ashrrev_i32_e32 v129, 31, v128
	v_lshlrev_b64 v[128:129], 12, v[128:129]
	v_lshl_add_u64 v[128:129], s[16:17], 0, v[128:129]
	v_lshl_add_u64 v[128:129], v[96:97], 2, v[128:129]
	global_load_dwordx4 v[128:131], v[128:129], off nt
	v_add_u32_e32 v132, 4, v160
	v_ashrrev_i32_e32 v133, 31, v132
	v_lshlrev_b64 v[132:133], 12, v[132:133]
	v_lshl_add_u64 v[132:133], s[16:17], 0, v[132:133]
	v_lshl_add_u64 v[132:133], v[96:97], 2, v[132:133]
	global_load_dwordx4 v[132:135], v[132:133], off nt
	v_add_u32_e32 v136, 8, v160
	v_ashrrev_i32_e32 v137, 31, v136
	v_lshlrev_b64 v[136:137], 12, v[136:137]
	v_lshl_add_u64 v[136:137], s[16:17], 0, v[136:137]
	v_lshl_add_u64 v[136:137], v[96:97], 2, v[136:137]
	global_load_dwordx4 v[136:139], v[136:137], off nt
	v_add_u32_e32 v140, 12, v160
	v_ashrrev_i32_e32 v141, 31, v140
	v_lshlrev_b64 v[140:141], 12, v[140:141]
	v_lshl_add_u64 v[140:141], s[16:17], 0, v[140:141]
	v_lshl_add_u64 v[140:141], v[96:97], 2, v[140:141]
	global_load_dwordx4 v[140:143], v[140:141], off nt
	v_add_u32_e32 v144, 16, v160
	v_ashrrev_i32_e32 v145, 31, v144
	v_lshlrev_b64 v[144:145], 12, v[144:145]
	v_lshl_add_u64 v[144:145], s[16:17], 0, v[144:145]
	v_lshl_add_u64 v[144:145], v[96:97], 2, v[144:145]
	global_load_dwordx4 v[144:147], v[144:145], off nt
	v_add_u32_e32 v148, 20, v160
	v_ashrrev_i32_e32 v149, 31, v148
	v_lshlrev_b64 v[148:149], 12, v[148:149]
	v_lshl_add_u64 v[148:149], s[16:17], 0, v[148:149]
	v_lshl_add_u64 v[148:149], v[96:97], 2, v[148:149]
	global_load_dwordx4 v[148:151], v[148:149], off nt
	v_add_u32_e32 v152, 24, v160
	v_ashrrev_i32_e32 v153, 31, v152
	v_lshlrev_b64 v[152:153], 12, v[152:153]
	v_lshl_add_u64 v[152:153], s[16:17], 0, v[152:153]
	v_lshl_add_u64 v[152:153], v[96:97], 2, v[152:153]
	global_load_dwordx4 v[152:155], v[152:153], off nt
	v_add_u32_e32 v156, 28, v160
	v_ashrrev_i32_e32 v157, 31, v156
	v_lshlrev_b64 v[156:157], 12, v[156:157]
	v_lshl_add_u64 v[156:157], s[16:17], 0, v[156:157]
	v_lshl_add_u64 v[156:157], v[96:97], 2, v[156:157]
	global_load_dwordx4 v[156:159], v[156:157], off nt
	s_and_saveexec_b64 s[2:3], vcc
	s_cbranch_execz .LBB0_5646
	v_lshlrev_b64 v[98:99], 12, v[160:161]
	v_lshl_add_u64 v[98:99], s[16:17], 0, v[98:99]
	v_lshl_add_u64 v[106:107], v[96:97], 2, v[98:99]
	ds_read_b128 v[102:105], v114
	s_waitcnt vmcnt(7) lgkmcnt(0)
	v_pk_add_f32 v[100:101], v[104:105], v[130:131]
	v_pk_add_f32 v[98:99], v[102:103], v[128:129]
	global_store_dwordx4 v[106:107], v[98:101], off nt

.LBB0_5676:
	s_or_b64 exec, exec, s[2:3]
	s_or_b32 s2, s55, 32
	v_add_u32_e32 v102, s2, v183
	v_min_i32_e32 v66, 0x7fff, v102
	v_add_u32_e32 v68, 8, v102
	v_add_u32_e32 v70, 9, v102
	v_add_u32_e32 v72, 10, v102
	v_ashrrev_i32_e32 v66, 12, v66
	v_min_i32_e32 v68, 0x7fff, v68
	v_min_i32_e32 v70, 0x7fff, v70
	v_min_i32_e32 v72, 0x7fff, v72
	v_add_u32_e32 v66, 24, v66
	v_ashrrev_i32_e32 v68, 12, v68
	v_ashrrev_i32_e32 v70, 12, v70
	v_ashrrev_i32_e32 v72, 12, v72
	v_mul_hi_i32_i24_e32 v67, 0x3000, v66
	v_mul_i32_i24_e32 v66, 0x3000, v66
	v_add_u32_e32 v68, 24, v68
	v_add_u32_e32 v70, 24, v70
	v_add_u32_e32 v72, 24, v72
	v_lshl_add_u64 v[66:67], s[24:25], 0, v[66:67]
	v_mul_hi_i32_i24_e32 v69, 0x3000, v68
	v_mul_i32_i24_e32 v68, 0x3000, v68
	v_mul_hi_i32_i24_e32 v71, 0x3000, v70
	v_mul_i32_i24_e32 v70, 0x3000, v70
	v_mul_hi_i32_i24_e32 v73, 0x3000, v72
	v_mul_i32_i24_e32 v72, 0x3000, v72
	v_lshl_add_u64 v[66:67], v[66:67], 0, s[18:19]
	v_lshl_add_u64 v[68:69], s[24:25], 0, v[68:69]
	v_lshl_add_u64 v[70:71], s[24:25], 0, v[70:71]
	v_lshl_add_u64 v[72:73], s[24:25], 0, v[72:73]
	v_lshl_add_u64 v[74:75], v[66:67], 0, v[180:181]
	v_lshl_add_u64 v[68:69], v[68:69], 0, s[18:19]
	v_lshl_add_u64 v[70:71], v[70:71], 0, s[18:19]
	v_lshl_add_u64 v[72:73], v[72:73], 0, s[18:19]
	v_lshl_add_u64 v[76:77], v[68:69], 0, v[180:181]
	v_lshl_add_u64 v[78:79], v[70:71], 0, v[180:181]
	v_lshl_add_u64 v[80:81], v[72:73], 0, v[180:181]
	global_load_dword v103, v[74:75], off
	global_load_dword v104, v[74:75], off offset:128
	global_load_dword v105, v[76:77], off
	global_load_dword v106, v[76:77], off offset:128
	global_load_dword v107, v[78:79], off
	global_load_dword v108, v[78:79], off offset:128
	global_load_dword v109, v[80:81], off
	global_load_dword v110, v[80:81], off offset:128
	v_add_u32_e32 v74, 11, v102
	v_add_u32_e32 v82, 18, v102
	v_min_i32_e32 v74, 0x7fff, v74
	v_add_u32_e32 v76, 16, v102
	v_add_u32_e32 v78, 17, v102
	v_min_i32_e32 v82, 0x7fff, v82
	v_ashrrev_i32_e32 v74, 12, v74
	v_min_i32_e32 v76, 0x7fff, v76
	v_min_i32_e32 v78, 0x7fff, v78
	v_ashrrev_i32_e32 v82, 12, v82
	v_add_u32_e32 v74, 24, v74
	v_ashrrev_i32_e32 v76, 12, v76
	v_ashrrev_i32_e32 v78, 12, v78
	v_add_u32_e32 v82, 24, v82
	v_mul_hi_i32_i24_e32 v75, 0x3000, v74
	v_mul_i32_i24_e32 v74, 0x3000, v74
	v_add_u32_e32 v76, 24, v76
	v_add_u32_e32 v78, 24, v78
	v_mul_hi_i32_i24_e32 v83, 0x3000, v82
	v_mul_i32_i24_e32 v82, 0x3000, v82
	v_lshl_add_u64 v[74:75], s[24:25], 0, v[74:75]
	v_mul_hi_i32_i24_e32 v77, 0x3000, v76
	v_mul_i32_i24_e32 v76, 0x3000, v76
	v_mul_hi_i32_i24_e32 v79, 0x3000, v78
	v_mul_i32_i24_e32 v78, 0x3000, v78
	v_lshl_add_u64 v[82:83], s[24:25], 0, v[82:83]
	v_lshl_add_u64 v[74:75], v[74:75], 0, s[18:19]
	v_lshl_add_u64 v[76:77], s[24:25], 0, v[76:77]
	v_lshl_add_u64 v[78:79], s[24:25], 0, v[78:79]
	v_lshl_add_u64 v[82:83], v[82:83], 0, s[18:19]
	v_lshl_add_u64 v[80:81], v[74:75], 0, v[180:181]
	v_lshl_add_u64 v[76:77], v[76:77], 0, s[18:19]
	v_lshl_add_u64 v[78:79], v[78:79], 0, s[18:19]
	v_lshl_add_u64 v[88:89], v[82:83], 0, v[180:181]
	v_lshl_add_u64 v[84:85], v[76:77], 0, v[180:181]
	v_lshl_add_u64 v[86:87], v[78:79], 0, v[180:181]
	global_load_dword v111, v[80:81], off
	global_load_dword v112, v[80:81], off offset:128
	global_load_dword v113, v[84:85], off
	global_load_dword v122, v[84:85], off offset:128
	global_load_dword v123, v[86:87], off
	global_load_dword v124, v[86:87], off offset:128
	global_load_dword v125, v[88:89], off
	global_load_dword v126, v[88:89], off offset:128
	v_add_u32_e32 v80, 19, v102
	v_add_u32_e32 v88, 25, v102
	v_add_u32_e32 v90, 26, v102
	v_min_i32_e32 v80, 0x7fff, v80
	v_add_u32_e32 v86, 24, v102
	v_min_i32_e32 v88, 0x7fff, v88
	v_min_i32_e32 v90, 0x7fff, v90
	v_ashrrev_i32_e32 v80, 12, v80
	v_min_i32_e32 v86, 0x7fff, v86
	v_ashrrev_i32_e32 v88, 12, v88
	v_ashrrev_i32_e32 v90, 12, v90
	v_add_u32_e32 v80, 24, v80
	v_ashrrev_i32_e32 v86, 12, v86
	v_add_u32_e32 v88, 24, v88
	v_add_u32_e32 v90, 24, v90
	v_mul_hi_i32_i24_e32 v81, 0x3000, v80
	v_mul_i32_i24_e32 v80, 0x3000, v80
	v_add_u32_e32 v86, 24, v86
	v_mul_hi_i32_i24_e32 v89, 0x3000, v88
	v_mul_i32_i24_e32 v88, 0x3000, v88
	v_mul_hi_i32_i24_e32 v91, 0x3000, v90
	v_mul_i32_i24_e32 v90, 0x3000, v90
	v_lshl_add_u64 v[80:81], s[24:25], 0, v[80:81]
	v_mul_hi_i32_i24_e32 v87, 0x3000, v86
	v_mul_i32_i24_e32 v86, 0x3000, v86
	v_lshl_add_u64 v[88:89], s[24:25], 0, v[88:89]
	v_lshl_add_u64 v[90:91], s[24:25], 0, v[90:91]
	v_lshl_add_u64 v[84:85], v[80:81], 0, s[18:19]
	v_lshl_add_u64 v[86:87], s[24:25], 0, v[86:87]
	v_lshl_add_u64 v[88:89], v[88:89], 0, s[18:19]
	v_lshl_add_u64 v[90:91], v[90:91], 0, s[18:19]
	v_lshl_add_u64 v[80:81], v[84:85], 0, v[180:181]
	v_lshl_add_u64 v[86:87], v[86:87], 0, s[18:19]
	v_lshl_add_u64 v[94:95], v[88:89], 0, v[180:181]
	v_lshl_add_u64 v[100:101], v[90:91], 0, v[180:181]
	v_lshl_add_u64 v[92:93], v[86:87], 0, v[180:181]
	global_load_dword v127, v[80:81], off
	global_load_dword v160, v[80:81], off offset:128
	global_load_dword v161, v[92:93], off
	global_load_dword v164, v[92:93], off offset:128
	global_load_dword v165, v[94:95], off
	s_nop 0
	global_load_dword v94, v[94:95], off offset:128
	s_nop 0
	global_load_dword v95, v[100:101], off
	s_nop 0
	global_load_dword v100, v[100:101], off offset:128
	v_add_u32_e32 v80, 27, v102
	v_min_i32_e32 v80, 0x7fff, v80
	v_ashrrev_i32_e32 v80, 12, v80
	v_add_u32_e32 v80, 24, v80
	v_mul_hi_i32_i24_e32 v81, 0x3000, v80
	v_mul_i32_i24_e32 v80, 0x3000, v80
	v_lshl_add_u64 v[80:81], s[24:25], 0, v[80:81]
	v_lshl_add_u64 v[92:93], v[80:81], 0, s[18:19]
	v_lshl_add_u64 v[80:81], v[92:93], 0, v[180:181]
	global_load_dword v101, v[80:81], off
	s_nop 0
	global_load_dword v81, v[80:81], off offset:128
	s_waitcnt vmcnt(25)
	v_mul_f32_e32 v48, v48, v103
	s_waitcnt vmcnt(24)
	v_mul_f32_e32 v32, v32, v104
	ds_write2_b32 v162, v48, v32 offset1:32
	v_mul_f32_e32 v32, v49, v103
	v_mul_f32_e32 v33, v33, v104
	ds_write2_b32 v162, v32, v33 offset0:68 offset1:100
	v_mul_f32_e32 v32, v50, v103
	v_mul_f32_e32 v33, v34, v104
	ds_write2_b32 v162, v32, v33 offset0:136 offset1:168
	v_mul_f32_e32 v32, v51, v103
	v_mul_f32_e32 v33, v35, v104
	ds_write2_b32 v162, v32, v33 offset0:204 offset1:236
	s_waitcnt vmcnt(23)
	v_mul_f32_e32 v32, v52, v105
	s_waitcnt vmcnt(22)
	v_mul_f32_e32 v33, v36, v106
	ds_write2_b32 v115, v32, v33 offset0:32 offset1:64
	s_waitcnt vmcnt(21)
	v_mul_f32_e32 v32, v53, v107
	s_waitcnt vmcnt(20)
	v_mul_f32_e32 v33, v37, v108
	ds_write2_b32 v115, v32, v33 offset0:100 offset1:132
	s_waitcnt vmcnt(19)
	v_mul_f32_e32 v32, v54, v109
	s_waitcnt vmcnt(18)
	v_mul_f32_e32 v33, v38, v110
	ds_write2_b32 v115, v32, v33 offset0:168 offset1:200
	v_add_u32_e32 v80, s2, v163
	v_cmp_gt_i32_e32 vcc, s38, v80
	s_waitcnt vmcnt(17)
	v_mul_f32_e32 v32, v55, v111
	s_waitcnt vmcnt(16)
	v_mul_f32_e32 v33, v39, v112
	ds_write2_b32 v116, v32, v33 offset0:108 offset1:140
	s_waitcnt vmcnt(15)
	v_mul_f32_e32 v32, v56, v113
	s_waitcnt vmcnt(14)
	v_mul_f32_e32 v33, v40, v122
	ds_write2_b32 v117, v32, v33 offset0:64 offset1:96
	s_waitcnt vmcnt(13)
	v_mul_f32_e32 v32, v57, v123
	s_waitcnt vmcnt(12)
	v_mul_f32_e32 v33, v41, v124
	ds_write2_b32 v117, v32, v33 offset0:132 offset1:164
	s_waitcnt vmcnt(11)
	v_mul_f32_e32 v32, v58, v125
	s_waitcnt vmcnt(10)
	v_mul_f32_e32 v33, v42, v126
	ds_write2_b32 v117, v32, v33 offset0:200 offset1:232
	s_waitcnt vmcnt(9)
	v_mul_f32_e32 v32, v59, v127
	s_waitcnt vmcnt(8)
	v_mul_f32_e32 v33, v43, v160
	ds_write2_b32 v118, v32, v33 offset0:12 offset1:44
	s_waitcnt vmcnt(7)
	v_mul_f32_e32 v32, v60, v161
	s_waitcnt vmcnt(6)
	v_mul_f32_e32 v33, v44, v164
	ds_write2_b32 v119, v32, v33 offset0:96 offset1:128
	s_waitcnt vmcnt(5)
	v_mul_f32_e32 v32, v61, v165
	s_waitcnt vmcnt(4)
	v_mul_f32_e32 v33, v45, v94
	ds_write2_b32 v119, v32, v33 offset0:164 offset1:196
	s_waitcnt vmcnt(3)
	v_mul_f32_e32 v32, v62, v95
	s_waitcnt vmcnt(2)
	v_mul_f32_e32 v33, v46, v100
	ds_write2_b32 v120, v32, v33 offset0:104 offset1:136
	s_waitcnt vmcnt(1)
	v_mul_f32_e32 v32, v63, v101
	s_waitcnt vmcnt(0)
	v_mul_f32_e32 v33, v47, v81
	v_ashrrev_i32_e32 v81, 31, v80
	ds_write2_b32 v121, v32, v33 offset0:44 offset1:76
	v_add_u32_e32 v128, 0, v80
	v_ashrrev_i32_e32 v129, 31, v128
	v_lshlrev_b64 v[128:129], 12, v[128:129]
	v_lshl_add_u64 v[128:129], s[16:17], 0, v[128:129]
	v_lshl_add_u64 v[128:129], v[96:97], 2, v[128:129]
	global_load_dwordx4 v[128:131], v[128:129], off nt
	v_add_u32_e32 v132, 4, v80
	v_ashrrev_i32_e32 v133, 31, v132
	v_lshlrev_b64 v[132:133], 12, v[132:133]
	v_lshl_add_u64 v[132:133], s[16:17], 0, v[132:133]
	v_lshl_add_u64 v[132:133], v[96:97], 2, v[132:133]
	global_load_dwordx4 v[132:135], v[132:133], off nt
	v_add_u32_e32 v136, 8, v80
	v_ashrrev_i32_e32 v137, 31, v136
	v_lshlrev_b64 v[136:137], 12, v[136:137]
	v_lshl_add_u64 v[136:137], s[16:17], 0, v[136:137]
	v_lshl_add_u64 v[136:137], v[96:97], 2, v[136:137]
	global_load_dwordx4 v[136:139], v[136:137], off nt
	v_add_u32_e32 v140, 12, v80
	v_ashrrev_i32_e32 v141, 31, v140
	v_lshlrev_b64 v[140:141], 12, v[140:141]
	v_lshl_add_u64 v[140:141], s[16:17], 0, v[140:141]
	v_lshl_add_u64 v[140:141], v[96:97], 2, v[140:141]
	global_load_dwordx4 v[140:143], v[140:141], off nt
	v_add_u32_e32 v144, 16, v80
	v_ashrrev_i32_e32 v145, 31, v144
	v_lshlrev_b64 v[144:145], 12, v[144:145]
	v_lshl_add_u64 v[144:145], s[16:17], 0, v[144:145]
	v_lshl_add_u64 v[144:145], v[96:97], 2, v[144:145]
	global_load_dwordx4 v[144:147], v[144:145], off nt
	v_add_u32_e32 v148, 20, v80
	v_ashrrev_i32_e32 v149, 31, v148
	v_lshlrev_b64 v[148:149], 12, v[148:149]
	v_lshl_add_u64 v[148:149], s[16:17], 0, v[148:149]
	v_lshl_add_u64 v[148:149], v[96:97], 2, v[148:149]
	global_load_dwordx4 v[148:151], v[148:149], off nt
	v_add_u32_e32 v152, 24, v80
	v_ashrrev_i32_e32 v153, 31, v152
	v_lshlrev_b64 v[152:153], 12, v[152:153]
	v_lshl_add_u64 v[152:153], s[16:17], 0, v[152:153]
	v_lshl_add_u64 v[152:153], v[96:97], 2, v[152:153]
	global_load_dwordx4 v[152:155], v[152:153], off nt
	v_add_u32_e32 v156, 28, v80
	v_ashrrev_i32_e32 v157, 31, v156
	v_lshlrev_b64 v[156:157], 12, v[156:157]
	v_lshl_add_u64 v[156:157], s[16:17], 0, v[156:157]
	v_lshl_add_u64 v[156:157], v[96:97], 2, v[156:157]
	global_load_dwordx4 v[156:159], v[156:157], off nt
	s_and_saveexec_b64 s[2:3], vcc
	s_cbranch_execz .LBB0_5678
	v_lshlrev_b64 v[32:33], 12, v[80:81]
	v_lshl_add_u64 v[32:33], s[16:17], 0, v[32:33]
	v_lshl_add_u64 v[40:41], v[96:97], 2, v[32:33]
	ds_read_b128 v[36:39], v114
	s_waitcnt vmcnt(7) lgkmcnt(0)
	v_pk_add_f32 v[34:35], v[38:39], v[130:131]
	v_pk_add_f32 v[32:33], v[36:37], v[128:129]
	global_store_dwordx4 v[40:41], v[32:35], off nt
